# GEMM K-loops: 64-bit VALU address adds of the LDS-DMA stage loads replaced by scalar-base + 32-bit lane offset addressing
# speedup vs baseline: 1.0040x; 1.0040x over previous
; #define PG8_STAGE(bufoff, gbase, voff) do { _Pragma("unroll") for (int _i = 0; _i < 2; ++_i) \
;         __builtin_amdgcn_global_load_lds((const unsigned*)((const char*)(gbase) + (voff)[_i]), (PG8_LAS unsigned*)(lds + (bufoff) + ldsw + _i * 8192), 16, 0, 0); } while (0)
; #define PG8_LDA(dst, b, h) do { _Pragma("unroll") for (int m = 0; m < 4; ++m) _Pragma("unroll") for (int k = 0; k < 2; ++k) dst[m][k] = *(const PG8_LAS bf16x8*)(lds + PG8_SA(b, h) + aoff + m * 2048 + k * 1024); } while (0)
; #define PG8_LDB(dst, b, h) do { _Pragma("unroll") for (int n = 0; n < 2; ++n) _Pragma("unroll") for (int k = 0; k < 2; ++k) dst[n][k] = *(const PG8_LAS bf16x8*)(lds + PG8_SB(b, h) + boff + n * 2048 + k * 1024); } while (0)
; #define PG8_MMA(ai, bj, At, Bt) do { __builtin_amdgcn_s_setprio(1); _Pragma("unroll") for (int m = 0; m < 4; ++m) _Pragma("unroll") for (int n = 0; n < 2; ++n) _Pragma("unroll") for (int k = 0; k < 2; ++k) \
;         acc[ai][bj][m][n] = __builtin_amdgcn_mfma_f32_16x16x32_bf16(Bt[n][k], At[m][k], acc[ai][bj][m][n], 0, 0, 0); __builtin_amdgcn_s_setprio(0); } while (0)
; #define PG8_WAIT_V(n) asm volatile("s_waitcnt vmcnt(" #n ")" ::: "memory")
; #define PG8_WAIT_L(n) asm volatile("s_waitcnt lgkmcnt(" #n ")" ::: "memory")
; #define PG8_BAR __builtin_amdgcn_s_barrier()
; #define PG8_SCHED __builtin_amdgcn_sched_barrier(0)
; template <class Epi, class Sched, bool ALIGN_EPI = false, bool SP2 = false>
; __device__ __forceinline__ void gemm_phase(PG8_LAS unsigned char* lds, const Gemm g, const Sched& S, const Epi& E) {
;     ...
;             PG8_LDB(B0, 0, 0); PG8_LDB(B1, 0, 1); PG8_SCHED; PG8_LDA(At, 0, 0); PG8_STAGE(PG8_SA(1, 1), a1 + hstep, voffA);
;             PG8_WAIT_V(8); PG8_WAIT_L(0); PG8_BAR; PG8_MMA(0, 0, At, B0); PG8_MMA(0, 1, At, B1); PG8_BAR; PG8_SCHED;
;             PG8_LDA(At, 0, 1); PG8_STAGE(PG8_SB(0, 0), b2, voffB); PG8_STAGE(PG8_SB(0, 1), b2 + hstep, voffB); PG8_STAGE(PG8_SA(0, 0), a2, voffA);
;             PG8_WAIT_V(8); PG8_WAIT_L(0); PG8_BAR; PG8_MMA(1, 0, At, B0); PG8_MMA(1, 1, At, B1); PG8_BAR; PG8_SCHED;
.LBB0_189:
	ds_read_b128 v[168:171], v150
	ds_read_b128 v[172:175], v151
	ds_read_b128 v[176:179], v152
	ds_read_b128 v[180:183], v153
	ds_read_b128 v[184:187], v154
	ds_read_b128 v[188:191], v155
	ds_read_b128 v[192:195], v156
	ds_read_b128 v[196:199], v157
	s_add_u32 s64, s58, 0xfffc0080
	s_addc_u32 s65, s59, -1
	s_cmp_eq_u32 s87, 12
	s_cselect_b32 s67, s51, s65
	s_cselect_b32 s66, s83, s64
	s_cselect_b32 s65, s49, s86
	s_cselect_b32 s64, s84, s85
	s_mov_b32 m0, s79
	ds_read_b128 v[200:203], v148
	ds_read_b128 v[204:207], v148 offset:1024
	ds_read_b128 v[208:211], v148 offset:2048
	ds_read_b128 v[212:215], v148 offset:3072
	ds_read_b128 v[216:219], v148 offset:4096
	ds_read_b128 v[224:227], v148 offset:5120
	ds_read_b128 v[228:231], v148 offset:6144
	ds_read_b128 v[232:235], v148 offset:7168
	global_load_lds_dwordx4 v136, s[58:59]
	s_mov_b32 m0, s80
	s_nop 0
	global_load_lds_dwordx4 v138, s[58:59]
	s_waitcnt vmcnt(8)
	s_waitcnt lgkmcnt(0)
	s_barrier
	s_setprio 1
	s_waitcnt lgkmcnt(0)
	v_mfma_f32_16x16x32_bf16 v[124:127], v[168:171], v[200:203], v[124:127]
	v_mfma_f32_16x16x32_bf16 v[120:123], v[176:179], v[200:203], v[120:123]
	v_mfma_f32_16x16x32_bf16 v[112:115], v[168:171], v[208:211], v[112:115]
	v_mfma_f32_16x16x32_bf16 v[104:107], v[176:179], v[208:211], v[104:107]
	v_mfma_f32_16x16x32_bf16 v[96:99], v[168:171], v[216:219], v[96:99]
	v_mfma_f32_16x16x32_bf16 v[88:91], v[176:179], v[216:219], v[88:91]
	v_mfma_f32_16x16x32_bf16 v[80:83], v[168:171], v[228:231], v[80:83]
	v_mfma_f32_16x16x32_bf16 v[72:75], v[176:179], v[228:231], v[72:75]
	v_mfma_f32_16x16x32_bf16 v[124:127], v[172:175], v[204:207], v[124:127]
	v_mfma_f32_16x16x32_bf16 v[120:123], v[180:183], v[204:207], v[120:123]
	v_mfma_f32_16x16x32_bf16 v[112:115], v[172:175], v[212:215], v[112:115]
	v_mfma_f32_16x16x32_bf16 v[104:107], v[180:183], v[212:215], v[104:107]
	v_mfma_f32_16x16x32_bf16 v[96:99], v[172:175], v[224:227], v[96:99]
	v_mfma_f32_16x16x32_bf16 v[88:91], v[180:183], v[224:227], v[88:91]
	v_mfma_f32_16x16x32_bf16 v[80:83], v[172:175], v[232:235], v[80:83]
	v_mfma_f32_16x16x32_bf16 v[72:75], v[180:183], v[232:235], v[72:75]
	s_setprio 0
	s_setprio 1
	v_mfma_f32_16x16x32_bf16 v[116:119], v[184:187], v[200:203], v[116:119]
	v_mfma_f32_16x16x32_bf16 v[108:111], v[192:195], v[200:203], v[108:111]
	v_mfma_f32_16x16x32_bf16 v[100:103], v[184:187], v[208:211], v[100:103]
	v_mfma_f32_16x16x32_bf16 v[92:95], v[192:195], v[208:211], v[92:95]
	v_mfma_f32_16x16x32_bf16 v[84:87], v[184:187], v[216:219], v[84:87]
	v_mfma_f32_16x16x32_bf16 v[76:79], v[192:195], v[216:219], v[76:79]
	v_mfma_f32_16x16x32_bf16 v[68:71], v[184:187], v[228:231], v[68:71]
	v_mfma_f32_16x16x32_bf16 v[64:67], v[192:195], v[228:231], v[64:67]
	v_mfma_f32_16x16x32_bf16 v[116:119], v[188:191], v[204:207], v[116:119]
	v_mfma_f32_16x16x32_bf16 v[108:111], v[196:199], v[204:207], v[108:111]
	v_mfma_f32_16x16x32_bf16 v[100:103], v[188:191], v[212:215], v[100:103]
	v_mfma_f32_16x16x32_bf16 v[92:95], v[196:199], v[212:215], v[92:95]
	v_mfma_f32_16x16x32_bf16 v[84:87], v[188:191], v[224:227], v[84:87]
	v_mfma_f32_16x16x32_bf16 v[76:79], v[196:199], v[224:227], v[76:79]
	v_mfma_f32_16x16x32_bf16 v[68:71], v[188:191], v[232:235], v[68:71]
	v_mfma_f32_16x16x32_bf16 v[64:67], v[196:199], v[232:235], v[64:67]
	s_setprio 0
	s_barrier
	s_mov_b32 m0, s3
	v_lshl_add_u64 v[146:147], s[64:65], 0, v[130:131]
	s_add_u32 s88, s64, 0x40000
	ds_read_b128 v[200:203], v148 offset:16384
	ds_read_b128 v[204:207], v148 offset:17408
	ds_read_b128 v[208:211], v148 offset:18432
	ds_read_b128 v[212:215], v148 offset:19456
	ds_read_b128 v[216:219], v148 offset:20480
	ds_read_b128 v[224:227], v148 offset:21504
	ds_read_b128 v[228:231], v148 offset:22528
	ds_read_b128 v[232:235], v148 offset:23552
	global_load_lds_dwordx4 v[146:147], off
	v_lshl_add_u64 v[220:221], s[64:65], 0, v[134:135]
	s_mov_b32 m0, s14
	s_addc_u32 s89, s65, 0
	global_load_lds_dwordx4 v[220:221], off
	s_mov_b32 m0, s15
	v_lshl_add_u64 v[238:239], s[66:67], 0, v[132:133]
	global_load_lds_dwordx4 v130, s[88:89]
	s_mov_b32 m0, s33
	s_nop 0
	global_load_lds_dwordx4 v134, s[88:89]
	v_lshl_add_u64 v[236:237], s[66:67], 0, v[128:129]
	s_mov_b32 m0, s1
	s_nop 0
	global_load_lds_dwordx4 v[236:237], off
	s_mov_b32 m0, s39
	s_nop 0
	global_load_lds_dwordx4 v[238:239], off
	s_waitcnt vmcnt(8)
	s_waitcnt lgkmcnt(0)
	s_barrier
	s_setprio 1
	s_waitcnt lgkmcnt(0)
	v_mfma_f32_16x16x32_bf16 v[60:63], v[168:171], v[200:203], v[60:63]
	v_mfma_f32_16x16x32_bf16 v[56:59], v[176:179], v[200:203], v[56:59]
	v_mfma_f32_16x16x32_bf16 v[48:51], v[168:171], v[208:211], v[48:51]
	v_mfma_f32_16x16x32_bf16 v[40:43], v[176:179], v[208:211], v[40:43]
	v_mfma_f32_16x16x32_bf16 v[32:35], v[168:171], v[216:219], v[32:35]
	v_mfma_f32_16x16x32_bf16 v[24:27], v[176:179], v[216:219], v[24:27]
	v_mfma_f32_16x16x32_bf16 v[16:19], v[168:171], v[228:231], v[16:19]
	v_mfma_f32_16x16x32_bf16 v[8:11], v[176:179], v[228:231], v[8:11]
	v_mfma_f32_16x16x32_bf16 v[60:63], v[172:175], v[204:207], v[60:63]
	v_mfma_f32_16x16x32_bf16 v[56:59], v[180:183], v[204:207], v[56:59]
	v_mfma_f32_16x16x32_bf16 v[48:51], v[172:175], v[212:215], v[48:51]
	v_mfma_f32_16x16x32_bf16 v[40:43], v[180:183], v[212:215], v[40:43]
	v_mfma_f32_16x16x32_bf16 v[32:35], v[172:175], v[224:227], v[32:35]
	v_mfma_f32_16x16x32_bf16 v[24:27], v[180:183], v[224:227], v[24:27]
	v_mfma_f32_16x16x32_bf16 v[16:19], v[172:175], v[232:235], v[16:19]
	v_mfma_f32_16x16x32_bf16 v[8:11], v[180:183], v[232:235], v[8:11]
	s_setprio 0
	s_setprio 1
	v_mfma_f32_16x16x32_bf16 v[52:55], v[184:187], v[200:203], v[52:55]
	v_mfma_f32_16x16x32_bf16 v[44:47], v[192:195], v[200:203], v[44:47]
	v_mfma_f32_16x16x32_bf16 v[36:39], v[184:187], v[208:211], v[36:39]
	v_mfma_f32_16x16x32_bf16 v[28:31], v[192:195], v[208:211], v[28:31]
	v_mfma_f32_16x16x32_bf16 v[20:23], v[184:187], v[216:219], v[20:23]
	v_mfma_f32_16x16x32_bf16 v[12:15], v[192:195], v[216:219], v[12:15]
	v_mfma_f32_16x16x32_bf16 v[4:7], v[184:187], v[228:231], v[4:7]
	v_mfma_f32_16x16x32_bf16 v[0:3], v[192:195], v[228:231], v[0:3]
	v_mfma_f32_16x16x32_bf16 v[52:55], v[188:191], v[204:207], v[52:55]
	v_mfma_f32_16x16x32_bf16 v[44:47], v[196:199], v[204:207], v[44:47]
	v_mfma_f32_16x16x32_bf16 v[36:39], v[188:191], v[212:215], v[36:39]
	v_mfma_f32_16x16x32_bf16 v[28:31], v[196:199], v[212:215], v[28:31]
	v_mfma_f32_16x16x32_bf16 v[20:23], v[188:191], v[224:227], v[20:23]
	v_mfma_f32_16x16x32_bf16 v[12:15], v[196:199], v[224:227], v[12:15]
	v_mfma_f32_16x16x32_bf16 v[4:7], v[188:191], v[232:235], v[4:7]
	v_mfma_f32_16x16x32_bf16 v[0:3], v[196:199], v[232:235], v[0:3]
	s_setprio 0
	s_barrier
; #define PG8_STAGE(bufoff, gbase, voff) do { _Pragma("unroll") for (int _i = 0; _i < 2; ++_i) \
;         __builtin_amdgcn_global_load_lds((const unsigned*)((const char*)(gbase) + (voff)[_i]), (PG8_LAS unsigned*)(lds + (bufoff) + ldsw + _i * 8192), 16, 0, 0); } while (0)
; #define PG8_LDA(dst, b, h) do { _Pragma("unroll") for (int m = 0; m < 4; ++m) _Pragma("unroll") for (int k = 0; k < 2; ++k) dst[m][k] = *(const PG8_LAS bf16x8*)(lds + PG8_SA(b, h) + aoff + m * 2048 + k * 1024); } while (0)
; #define PG8_LDB(dst, b, h) do { _Pragma("unroll") for (int n = 0; n < 2; ++n) _Pragma("unroll") for (int k = 0; k < 2; ++k) dst[n][k] = *(const PG8_LAS bf16x8*)(lds + PG8_SB(b, h) + boff + n * 2048 + k * 1024); } while (0)
; #define PG8_MMA(ai, bj, At, Bt) do { __builtin_amdgcn_s_setprio(1); _Pragma("unroll") for (int m = 0; m < 4; ++m) _Pragma("unroll") for (int n = 0; n < 2; ++n) _Pragma("unroll") for (int k = 0; k < 2; ++k) \
;         acc[ai][bj][m][n] = __builtin_amdgcn_mfma_f32_16x16x32_bf16(Bt[n][k], At[m][k], acc[ai][bj][m][n], 0, 0, 0); __builtin_amdgcn_s_setprio(0); } while (0)
; #define PG8_WAIT_V(n) asm volatile("s_waitcnt vmcnt(" #n ")" ::: "memory")
; #define PG8_WAIT_L(n) asm volatile("s_waitcnt lgkmcnt(" #n ")" ::: "memory")
; #define PG8_BAR __builtin_amdgcn_s_barrier()
; template <class Epi, class Sched, bool ALIGN_EPI = false, bool SP2 = false>
; __device__ __forceinline__ void gemm_phase(PG8_LAS unsigned char* lds, const Gemm g, const Sched& S, const Epi& E) {
;     ...
;         for (int t = 0; t < nt; t += 2) {
;             const bool last = (t == nt - 2);
;             const char* a1 = cA + (size_t)(t + 1) * kstep;
;             const char* a2 = last ? nA : cA + (size_t)(t + 2) * kstep; const char* b2 = last ? nB : cB + (size_t)(t + 2) * kstep;
;             const char* a3 = a2 + kstep; const char* b3 = b2 + kstep;
;     ...
;             PG8_LDB(B0, 1, 0); PG8_LDB(B1, 1, 1); PG8_SCHED; PG8_LDA(At, 1, 0); PG8_STAGE(PG8_SA(0, 1), a2 + hstep, voffA);
;             PG8_WAIT_V(8); PG8_WAIT_L(0); PG8_BAR; PG8_MMA(0, 0, At, B0); PG8_MMA(0, 1, At, B1); PG8_BAR; PG8_SCHED;
;             PG8_LDA(At, 1, 1); PG8_STAGE(PG8_SB(1, 0), b3, voffB); PG8_STAGE(PG8_SB(1, 1), b3 + hstep, voffB); PG8_STAGE(PG8_SA(1, 0), a3, voffA);
;             PG8_WAIT_V(8); PG8_WAIT_L(0); PG8_BAR; PG8_MMA(1, 0, At, B0); PG8_MMA(1, 1, At, B1); PG8_BAR; PG8_SCHED;
	ds_read_b128 v[168:171], v158
	ds_read_b128 v[172:175], v159
	ds_read_b128 v[176:179], v160
	ds_read_b128 v[180:183], v161
	ds_read_b128 v[184:187], v162
	ds_read_b128 v[188:191], v163
	ds_read_b128 v[192:195], v164
	ds_read_b128 v[196:199], v165
	s_add_u32 s66, s66, 0x40000
	s_addc_u32 s67, s67, 0
	s_mov_b32 m0, s43
	ds_read_b128 v[200:203], v148 offset:32768
	ds_read_b128 v[204:207], v148 offset:33792
	ds_read_b128 v[208:211], v148 offset:34816
	ds_read_b128 v[212:215], v148 offset:35840
	ds_read_b128 v[216:219], v148 offset:36864
	ds_read_b128 v[224:227], v148 offset:37888
	ds_read_b128 v[228:231], v148 offset:38912
	ds_read_b128 v[232:235], v148 offset:39936
	global_load_lds_dwordx4 v128, s[66:67]
	v_lshl_add_u64 v[240:241], s[66:67], 0, v[132:133]
	s_mov_b32 m0, s57
	s_nop 0
	global_load_lds_dwordx4 v[240:241], off
	s_waitcnt vmcnt(8)
	s_waitcnt lgkmcnt(0)
	s_barrier
	s_setprio 1
	s_waitcnt lgkmcnt(0)
	v_mfma_f32_16x16x32_bf16 v[124:127], v[168:171], v[200:203], v[124:127]
	v_mfma_f32_16x16x32_bf16 v[120:123], v[176:179], v[200:203], v[120:123]
	v_mfma_f32_16x16x32_bf16 v[112:115], v[168:171], v[208:211], v[112:115]
	v_mfma_f32_16x16x32_bf16 v[104:107], v[176:179], v[208:211], v[104:107]
	v_mfma_f32_16x16x32_bf16 v[96:99], v[168:171], v[216:219], v[96:99]
	v_mfma_f32_16x16x32_bf16 v[88:91], v[176:179], v[216:219], v[88:91]
	v_mfma_f32_16x16x32_bf16 v[80:83], v[168:171], v[228:231], v[80:83]
	v_mfma_f32_16x16x32_bf16 v[72:75], v[176:179], v[228:231], v[72:75]
	v_mfma_f32_16x16x32_bf16 v[124:127], v[172:175], v[204:207], v[124:127]
	v_mfma_f32_16x16x32_bf16 v[120:123], v[180:183], v[204:207], v[120:123]
	v_mfma_f32_16x16x32_bf16 v[112:115], v[172:175], v[212:215], v[112:115]
	v_mfma_f32_16x16x32_bf16 v[104:107], v[180:183], v[212:215], v[104:107]
	v_mfma_f32_16x16x32_bf16 v[96:99], v[172:175], v[224:227], v[96:99]
	v_mfma_f32_16x16x32_bf16 v[88:91], v[180:183], v[224:227], v[88:91]
	v_mfma_f32_16x16x32_bf16 v[80:83], v[172:175], v[232:235], v[80:83]
	v_mfma_f32_16x16x32_bf16 v[72:75], v[180:183], v[232:235], v[72:75]
	s_setprio 0
	s_setprio 1
	v_mfma_f32_16x16x32_bf16 v[116:119], v[184:187], v[200:203], v[116:119]
	v_mfma_f32_16x16x32_bf16 v[108:111], v[192:195], v[200:203], v[108:111]
	v_mfma_f32_16x16x32_bf16 v[100:103], v[184:187], v[208:211], v[100:103]
	v_mfma_f32_16x16x32_bf16 v[92:95], v[192:195], v[208:211], v[92:95]
	v_mfma_f32_16x16x32_bf16 v[84:87], v[184:187], v[216:219], v[84:87]
	v_mfma_f32_16x16x32_bf16 v[76:79], v[192:195], v[216:219], v[76:79]
	v_mfma_f32_16x16x32_bf16 v[68:71], v[184:187], v[228:231], v[68:71]
	v_mfma_f32_16x16x32_bf16 v[64:67], v[192:195], v[228:231], v[64:67]
	v_mfma_f32_16x16x32_bf16 v[116:119], v[188:191], v[204:207], v[116:119]
	v_mfma_f32_16x16x32_bf16 v[108:111], v[196:199], v[204:207], v[108:111]
	v_mfma_f32_16x16x32_bf16 v[100:103], v[188:191], v[212:215], v[100:103]
	v_mfma_f32_16x16x32_bf16 v[92:95], v[196:199], v[212:215], v[92:95]
	v_mfma_f32_16x16x32_bf16 v[84:87], v[188:191], v[224:227], v[84:87]
	v_mfma_f32_16x16x32_bf16 v[76:79], v[196:199], v[224:227], v[76:79]
	v_mfma_f32_16x16x32_bf16 v[68:71], v[188:191], v[232:235], v[68:71]
	v_mfma_f32_16x16x32_bf16 v[64:67], v[196:199], v[232:235], v[64:67]
	s_setprio 0
	s_barrier
	s_mov_b32 m0, s71
	v_lshl_add_u64 v[146:147], v[146:147], 0, s[10:11]
	s_add_u32 s64, s64, 0x40080
	ds_read_b128 v[200:203], v148 offset:49152
	ds_read_b128 v[204:207], v148 offset:50176
	ds_read_b128 v[208:211], v148 offset:51200
	ds_read_b128 v[212:215], v148 offset:52224
	ds_read_b128 v[216:219], v148 offset:53248
	ds_read_b128 v[224:227], v148 offset:54272
	ds_read_b128 v[228:231], v148 offset:55296
	ds_read_b128 v[232:235], v148 offset:56320
	global_load_lds_dwordx4 v[146:147], off
	v_lshl_add_u64 v[146:147], v[220:221], 0, s[10:11]
	s_mov_b32 m0, s72
	s_addc_u32 s65, s65, 0
	global_load_lds_dwordx4 v[146:147], off
	s_mov_b32 m0, s75
	s_nop 0
	global_load_lds_dwordx4 v130, s[64:65]
	s_mov_b32 m0, s76
	s_nop 0
	global_load_lds_dwordx4 v134, s[64:65]
	v_lshl_add_u64 v[146:147], v[236:237], 0, s[10:11]
	s_mov_b32 m0, s73
	s_nop 0
	global_load_lds_dwordx4 v[146:147], off
	v_lshl_add_u64 v[146:147], v[238:239], 0, s[10:11]
	s_mov_b32 m0, s74
	s_nop 0
	global_load_lds_dwordx4 v[146:147], off
	s_waitcnt vmcnt(8)
	s_waitcnt lgkmcnt(0)
	s_barrier
	s_setprio 1
	s_waitcnt lgkmcnt(0)
	v_mfma_f32_16x16x32_bf16 v[60:63], v[168:171], v[200:203], v[60:63]
	v_mfma_f32_16x16x32_bf16 v[56:59], v[176:179], v[200:203], v[56:59]
	v_mfma_f32_16x16x32_bf16 v[48:51], v[168:171], v[208:211], v[48:51]
	v_mfma_f32_16x16x32_bf16 v[40:43], v[176:179], v[208:211], v[40:43]
	v_mfma_f32_16x16x32_bf16 v[32:35], v[168:171], v[216:219], v[32:35]
	v_mfma_f32_16x16x32_bf16 v[24:27], v[176:179], v[216:219], v[24:27]
	v_mfma_f32_16x16x32_bf16 v[16:19], v[168:171], v[228:231], v[16:19]
	v_mfma_f32_16x16x32_bf16 v[8:11], v[176:179], v[228:231], v[8:11]
	v_mfma_f32_16x16x32_bf16 v[60:63], v[172:175], v[204:207], v[60:63]
	v_mfma_f32_16x16x32_bf16 v[56:59], v[180:183], v[204:207], v[56:59]
	v_mfma_f32_16x16x32_bf16 v[48:51], v[172:175], v[212:215], v[48:51]
	v_mfma_f32_16x16x32_bf16 v[40:43], v[180:183], v[212:215], v[40:43]
	v_mfma_f32_16x16x32_bf16 v[32:35], v[172:175], v[224:227], v[32:35]
	v_mfma_f32_16x16x32_bf16 v[24:27], v[180:183], v[224:227], v[24:27]
	v_mfma_f32_16x16x32_bf16 v[16:19], v[172:175], v[232:235], v[16:19]
	v_mfma_f32_16x16x32_bf16 v[8:11], v[180:183], v[232:235], v[8:11]
	s_setprio 0
	s_setprio 1
	v_mfma_f32_16x16x32_bf16 v[52:55], v[184:187], v[200:203], v[52:55]
	v_mfma_f32_16x16x32_bf16 v[44:47], v[192:195], v[200:203], v[44:47]
	v_mfma_f32_16x16x32_bf16 v[36:39], v[184:187], v[208:211], v[36:39]
	v_mfma_f32_16x16x32_bf16 v[28:31], v[192:195], v[208:211], v[28:31]
	v_mfma_f32_16x16x32_bf16 v[20:23], v[184:187], v[216:219], v[20:23]
	v_mfma_f32_16x16x32_bf16 v[12:15], v[192:195], v[216:219], v[12:15]
	v_mfma_f32_16x16x32_bf16 v[4:7], v[184:187], v[228:231], v[4:7]
	v_mfma_f32_16x16x32_bf16 v[0:3], v[192:195], v[228:231], v[0:3]
	v_mfma_f32_16x16x32_bf16 v[52:55], v[188:191], v[204:207], v[52:55]
	v_mfma_f32_16x16x32_bf16 v[44:47], v[196:199], v[204:207], v[44:47]
	v_mfma_f32_16x16x32_bf16 v[36:39], v[188:191], v[212:215], v[36:39]
	v_mfma_f32_16x16x32_bf16 v[28:31], v[196:199], v[212:215], v[28:31]
	v_mfma_f32_16x16x32_bf16 v[20:23], v[188:191], v[224:227], v[20:23]
	v_mfma_f32_16x16x32_bf16 v[12:15], v[196:199], v[224:227], v[12:15]
	v_mfma_f32_16x16x32_bf16 v[4:7], v[188:191], v[232:235], v[4:7]
	v_mfma_f32_16x16x32_bf16 v[0:3], v[196:199], v[232:235], v[0:3]
	s_setprio 0
	s_barrier
	s_add_i32 s87, s87, 2
	s_add_u32 s58, s58, 0x100
	s_addc_u32 s59, s59, 0
	s_add_u32 s85, s85, 0x100
	s_addc_u32 s86, s86, 0
	s_cmp_gt_u32 s87, 13
	s_cbranch_scc0 .LBB0_189
	s_and_b64 vcc, exec, s[12:13]
	s_cbranch_vccz .LBB0_192
	s_barrier

; #define PG8_STAGE(bufoff, gbase, voff) do { _Pragma("unroll") for (int _i = 0; _i < 2; ++_i) \
;         __builtin_amdgcn_global_load_lds((const unsigned*)((const char*)(gbase) + (voff)[_i]), (PG8_LAS unsigned*)(lds + (bufoff) + ldsw + _i * 8192), 16, 0, 0); } while (0)
; #define PG8_LDA(dst, b, h) do { _Pragma("unroll") for (int m = 0; m < 4; ++m) _Pragma("unroll") for (int k = 0; k < 2; ++k) dst[m][k] = *(const PG8_LAS bf16x8*)(lds + PG8_SA(b, h) + aoff + m * 2048 + k * 1024); } while (0)
; #define PG8_LDB(dst, b, h) do { _Pragma("unroll") for (int n = 0; n < 2; ++n) _Pragma("unroll") for (int k = 0; k < 2; ++k) dst[n][k] = *(const PG8_LAS bf16x8*)(lds + PG8_SB(b, h) + boff + n * 2048 + k * 1024); } while (0)
; #define PG8_MMA(ai, bj, At, Bt) do { __builtin_amdgcn_s_setprio(1); _Pragma("unroll") for (int m = 0; m < 4; ++m) _Pragma("unroll") for (int n = 0; n < 2; ++n) _Pragma("unroll") for (int k = 0; k < 2; ++k) \
;         acc[ai][bj][m][n] = __builtin_amdgcn_mfma_f32_16x16x32_bf16(Bt[n][k], At[m][k], acc[ai][bj][m][n], 0, 0, 0); __builtin_amdgcn_s_setprio(0); } while (0)
; #define PG8_WAIT_V(n) asm volatile("s_waitcnt vmcnt(" #n ")" ::: "memory")
; #define PG8_WAIT_L(n) asm volatile("s_waitcnt lgkmcnt(" #n ")" ::: "memory")
; #define PG8_BAR __builtin_amdgcn_s_barrier()
; #define PG8_SCHED __builtin_amdgcn_sched_barrier(0)
; template <class Epi, class Sched, bool ALIGN_EPI = false, bool SP2 = false>
; __device__ __forceinline__ void gemm_phase(PG8_LAS unsigned char* lds, const Gemm g, const Sched& S, const Epi& E) {
;     ...
;             PG8_LDB(B0, 0, 0); PG8_LDB(B1, 0, 1); PG8_SCHED; PG8_LDA(At, 0, 0); PG8_STAGE(PG8_SA(1, 1), a1 + hstep, voffA);
;             PG8_WAIT_V(8); PG8_WAIT_L(0); PG8_BAR; PG8_MMA(0, 0, At, B0); PG8_MMA(0, 1, At, B1); PG8_BAR; PG8_SCHED;
;             PG8_LDA(At, 0, 1); PG8_STAGE(PG8_SB(0, 0), b2, voffB); PG8_STAGE(PG8_SB(0, 1), b2 + hstep, voffB); PG8_STAGE(PG8_SA(0, 0), a2, voffA);
;             PG8_WAIT_V(8); PG8_WAIT_L(0); PG8_BAR; PG8_MMA(1, 0, At, B0); PG8_MMA(1, 1, At, B1); PG8_BAR; PG8_SCHED;
.LBB0_634:
	ds_read_b128 v[142:145], v174
	ds_read_b128 v[146:149], v175
	ds_read_b128 v[150:153], v176
	ds_read_b128 v[154:157], v177
	ds_read_b128 v[158:161], v178
	ds_read_b128 v[162:165], v179
	ds_read_b128 v[166:169], v180
	ds_read_b128 v[190:193], v181
	s_add_u32 s66, s64, 0x100
	s_addc_u32 s67, s65, 0
	s_cmp_eq_u32 s6, 12
	s_cselect_b32 s73, s57, s67
	s_cselect_b32 s72, vcc_lo, s66
	s_cselect_b32 s71, s55, s92
	s_cselect_b32 s70, vcc_hi, s90
	s_mov_b32 m0, s86
	v_lshl_add_u64 v[170:171], s[64:65], 0, v[134:135]
	ds_read_b128 v[194:197], v172
	ds_read_b128 v[198:201], v172 offset:1024
	ds_read_b128 v[202:205], v172 offset:2048
	ds_read_b128 v[206:209], v172 offset:3072
	ds_read_b128 v[210:213], v172 offset:4096
	ds_read_b128 v[214:217], v172 offset:5120
	ds_read_b128 v[218:221], v172 offset:6144
	ds_read_b128 v[224:227], v172 offset:7168
	global_load_lds_dwordx4 v[170:171], off
	v_lshl_add_u64 v[170:171], s[64:65], 0, v[136:137]
	s_mov_b32 m0, s87
	s_nop 0
	global_load_lds_dwordx4 v[170:171], off
	s_waitcnt vmcnt(8)
	s_waitcnt lgkmcnt(0)
	s_barrier
	s_setprio 1
	s_waitcnt lgkmcnt(0)
	v_mfma_f32_16x16x32_bf16 v[124:127], v[142:145], v[194:197], v[124:127]
	v_mfma_f32_16x16x32_bf16 v[108:111], v[150:153], v[194:197], v[108:111]
	v_mfma_f32_16x16x32_bf16 v[120:123], v[142:145], v[202:205], v[120:123]
	v_mfma_f32_16x16x32_bf16 v[96:99], v[150:153], v[202:205], v[96:99]
	v_mfma_f32_16x16x32_bf16 v[116:119], v[142:145], v[210:213], v[116:119]
	v_mfma_f32_16x16x32_bf16 v[88:91], v[150:153], v[210:213], v[88:91]
	v_mfma_f32_16x16x32_bf16 v[112:115], v[142:145], v[218:221], v[112:115]
	v_mfma_f32_16x16x32_bf16 v[84:87], v[150:153], v[218:221], v[84:87]
	v_mfma_f32_16x16x32_bf16 v[124:127], v[146:149], v[198:201], v[124:127]
	v_mfma_f32_16x16x32_bf16 v[108:111], v[154:157], v[198:201], v[108:111]
	v_mfma_f32_16x16x32_bf16 v[120:123], v[146:149], v[206:209], v[120:123]
	v_mfma_f32_16x16x32_bf16 v[96:99], v[154:157], v[206:209], v[96:99]
	v_mfma_f32_16x16x32_bf16 v[116:119], v[146:149], v[214:217], v[116:119]
	v_mfma_f32_16x16x32_bf16 v[88:91], v[154:157], v[214:217], v[88:91]
	v_mfma_f32_16x16x32_bf16 v[112:115], v[146:149], v[224:227], v[112:115]
	v_mfma_f32_16x16x32_bf16 v[84:87], v[154:157], v[224:227], v[84:87]
	s_setprio 0
	s_setprio 1
	v_mfma_f32_16x16x32_bf16 v[68:71], v[158:161], v[194:197], v[68:71]
	v_mfma_f32_16x16x32_bf16 v[40:43], v[166:169], v[194:197], v[40:43]
	v_mfma_f32_16x16x32_bf16 v[60:63], v[158:161], v[202:205], v[60:63]
	v_mfma_f32_16x16x32_bf16 v[32:35], v[166:169], v[202:205], v[32:35]
	v_mfma_f32_16x16x32_bf16 v[52:55], v[158:161], v[210:213], v[52:55]
	v_mfma_f32_16x16x32_bf16 v[24:27], v[166:169], v[210:213], v[24:27]
	v_mfma_f32_16x16x32_bf16 v[48:51], v[158:161], v[218:221], v[48:51]
	v_mfma_f32_16x16x32_bf16 v[16:19], v[166:169], v[218:221], v[16:19]
	v_mfma_f32_16x16x32_bf16 v[68:71], v[162:165], v[198:201], v[68:71]
	v_mfma_f32_16x16x32_bf16 v[40:43], v[190:193], v[198:201], v[40:43]
	v_mfma_f32_16x16x32_bf16 v[60:63], v[162:165], v[206:209], v[60:63]
	v_mfma_f32_16x16x32_bf16 v[32:35], v[190:193], v[206:209], v[32:35]
	v_mfma_f32_16x16x32_bf16 v[52:55], v[162:165], v[214:217], v[52:55]
	v_mfma_f32_16x16x32_bf16 v[24:27], v[190:193], v[214:217], v[24:27]
	v_mfma_f32_16x16x32_bf16 v[48:51], v[162:165], v[224:227], v[48:51]
	v_mfma_f32_16x16x32_bf16 v[16:19], v[190:193], v[224:227], v[16:19]
	s_setprio 0
	s_barrier
	s_mov_b32 m0, s13
	v_lshl_add_u64 v[170:171], s[70:71], 0, v[128:129]
	s_add_u32 s64, s70, 0x40000
	ds_read_b128 v[194:197], v172 offset:16384
	ds_read_b128 v[198:201], v172 offset:17408
	ds_read_b128 v[202:205], v172 offset:18432
	ds_read_b128 v[206:209], v172 offset:19456
	ds_read_b128 v[210:213], v172 offset:20480
	ds_read_b128 v[214:217], v172 offset:21504
	ds_read_b128 v[218:221], v172 offset:22528
	ds_read_b128 v[224:227], v172 offset:23552
	global_load_lds_dwordx4 v[170:171], off
	v_lshl_add_u64 v[228:229], s[70:71], 0, v[130:131]
	s_mov_b32 m0, s14
	s_addc_u32 s65, s71, 0
	global_load_lds_dwordx4 v[228:229], off
	s_mov_b32 m0, s15
	v_lshl_add_u64 v[232:233], s[72:73], 0, v[130:131]
	global_load_lds_dwordx4 v128, s[64:65]
	s_mov_b32 m0, s33
	s_nop 0
	global_load_lds_dwordx4 v130, s[64:65]
	v_lshl_add_u64 v[230:231], s[72:73], 0, v[128:129]
	s_mov_b32 m0, s12
	s_nop 0
	global_load_lds_dwordx4 v[230:231], off
	s_mov_b32 m0, s39
	s_nop 0
	global_load_lds_dwordx4 v[232:233], off
	s_waitcnt vmcnt(8)
	s_waitcnt lgkmcnt(0)
	s_barrier
	s_setprio 1
	s_waitcnt lgkmcnt(0)
	v_mfma_f32_16x16x32_bf16 v[104:107], v[142:145], v[194:197], v[104:107]
	v_mfma_f32_16x16x32_bf16 v[76:79], v[150:153], v[194:197], v[76:79]
	v_mfma_f32_16x16x32_bf16 v[100:103], v[142:145], v[202:205], v[100:103]
	v_mfma_f32_16x16x32_bf16 v[72:75], v[150:153], v[202:205], v[72:75]
	v_mfma_f32_16x16x32_bf16 v[92:95], v[142:145], v[210:213], v[92:95]
	v_mfma_f32_16x16x32_bf16 v[64:67], v[150:153], v[210:213], v[64:67]
	v_mfma_f32_16x16x32_bf16 v[80:83], v[142:145], v[218:221], v[80:83]
	v_mfma_f32_16x16x32_bf16 v[56:59], v[150:153], v[218:221], v[56:59]
	v_mfma_f32_16x16x32_bf16 v[104:107], v[146:149], v[198:201], v[104:107]
	v_mfma_f32_16x16x32_bf16 v[76:79], v[154:157], v[198:201], v[76:79]
	v_mfma_f32_16x16x32_bf16 v[100:103], v[146:149], v[206:209], v[100:103]
	v_mfma_f32_16x16x32_bf16 v[72:75], v[154:157], v[206:209], v[72:75]
	v_mfma_f32_16x16x32_bf16 v[92:95], v[146:149], v[214:217], v[92:95]
	v_mfma_f32_16x16x32_bf16 v[64:67], v[154:157], v[214:217], v[64:67]
	v_mfma_f32_16x16x32_bf16 v[80:83], v[146:149], v[224:227], v[80:83]
	v_mfma_f32_16x16x32_bf16 v[56:59], v[154:157], v[224:227], v[56:59]
	s_setprio 0
	s_setprio 1
	v_mfma_f32_16x16x32_bf16 v[44:47], v[158:161], v[194:197], v[44:47]
	v_mfma_f32_16x16x32_bf16 v[12:15], v[166:169], v[194:197], v[12:15]
	v_mfma_f32_16x16x32_bf16 v[36:39], v[158:161], v[202:205], v[36:39]
	v_mfma_f32_16x16x32_bf16 v[8:11], v[166:169], v[202:205], v[8:11]
	v_mfma_f32_16x16x32_bf16 v[28:31], v[158:161], v[210:213], v[28:31]
	v_mfma_f32_16x16x32_bf16 v[4:7], v[166:169], v[210:213], v[4:7]
	v_mfma_f32_16x16x32_bf16 v[20:23], v[158:161], v[218:221], v[20:23]
	v_mfma_f32_16x16x32_bf16 v[0:3], v[166:169], v[218:221], v[0:3]
	v_mfma_f32_16x16x32_bf16 v[44:47], v[162:165], v[198:201], v[44:47]
	v_mfma_f32_16x16x32_bf16 v[12:15], v[190:193], v[198:201], v[12:15]
	v_mfma_f32_16x16x32_bf16 v[36:39], v[162:165], v[206:209], v[36:39]
	v_mfma_f32_16x16x32_bf16 v[8:11], v[190:193], v[206:209], v[8:11]
	v_mfma_f32_16x16x32_bf16 v[28:31], v[162:165], v[214:217], v[28:31]
	v_mfma_f32_16x16x32_bf16 v[4:7], v[190:193], v[214:217], v[4:7]
	v_mfma_f32_16x16x32_bf16 v[20:23], v[162:165], v[224:227], v[20:23]
	v_mfma_f32_16x16x32_bf16 v[0:3], v[190:193], v[224:227], v[0:3]
	s_setprio 0
	s_barrier
; #define PG8_STAGE(bufoff, gbase, voff) do { _Pragma("unroll") for (int _i = 0; _i < 2; ++_i) \
;         __builtin_amdgcn_global_load_lds((const unsigned*)((const char*)(gbase) + (voff)[_i]), (PG8_LAS unsigned*)(lds + (bufoff) + ldsw + _i * 8192), 16, 0, 0); } while (0)
; #define PG8_LDA(dst, b, h) do { _Pragma("unroll") for (int m = 0; m < 4; ++m) _Pragma("unroll") for (int k = 0; k < 2; ++k) dst[m][k] = *(const PG8_LAS bf16x8*)(lds + PG8_SA(b, h) + aoff + m * 2048 + k * 1024); } while (0)
; #define PG8_LDB(dst, b, h) do { _Pragma("unroll") for (int n = 0; n < 2; ++n) _Pragma("unroll") for (int k = 0; k < 2; ++k) dst[n][k] = *(const PG8_LAS bf16x8*)(lds + PG8_SB(b, h) + boff + n * 2048 + k * 1024); } while (0)
; #define PG8_MMA(ai, bj, At, Bt) do { __builtin_amdgcn_s_setprio(1); _Pragma("unroll") for (int m = 0; m < 4; ++m) _Pragma("unroll") for (int n = 0; n < 2; ++n) _Pragma("unroll") for (int k = 0; k < 2; ++k) \
;         acc[ai][bj][m][n] = __builtin_amdgcn_mfma_f32_16x16x32_bf16(Bt[n][k], At[m][k], acc[ai][bj][m][n], 0, 0, 0); __builtin_amdgcn_s_setprio(0); } while (0)
; #define PG8_WAIT_V(n) asm volatile("s_waitcnt vmcnt(" #n ")" ::: "memory")
; #define PG8_WAIT_L(n) asm volatile("s_waitcnt lgkmcnt(" #n ")" ::: "memory")
; #define PG8_BAR __builtin_amdgcn_s_barrier()
; template <class Epi, class Sched, bool ALIGN_EPI = false, bool SP2 = false>
; __device__ __forceinline__ void gemm_phase(PG8_LAS unsigned char* lds, const Gemm g, const Sched& S, const Epi& E) {
;     ...
;         for (int t = 0; t < nt; t += 2) {
;             const bool last = (t == nt - 2);
;             const char* a1 = cA + (size_t)(t + 1) * kstep;
;             const char* a2 = last ? nA : cA + (size_t)(t + 2) * kstep; const char* b2 = last ? nB : cB + (size_t)(t + 2) * kstep;
;             const char* a3 = a2 + kstep; const char* b3 = b2 + kstep;
;     ...
;             PG8_LDB(B0, 1, 0); PG8_LDB(B1, 1, 1); PG8_SCHED; PG8_LDA(At, 1, 0); PG8_STAGE(PG8_SA(0, 1), a2 + hstep, voffA);
;             PG8_WAIT_V(8); PG8_WAIT_L(0); PG8_BAR; PG8_MMA(0, 0, At, B0); PG8_MMA(0, 1, At, B1); PG8_BAR; PG8_SCHED;
;             PG8_LDA(At, 1, 1); PG8_STAGE(PG8_SB(1, 0), b3, voffB); PG8_STAGE(PG8_SB(1, 1), b3 + hstep, voffB); PG8_STAGE(PG8_SA(1, 0), a3, voffA);
;             PG8_WAIT_V(8); PG8_WAIT_L(0); PG8_BAR; PG8_MMA(1, 0, At, B0); PG8_MMA(1, 1, At, B1); PG8_BAR; PG8_SCHED;
	ds_read_b128 v[142:145], v182
	ds_read_b128 v[146:149], v183
	ds_read_b128 v[150:153], v184
	ds_read_b128 v[154:157], v185
	ds_read_b128 v[158:161], v186
	ds_read_b128 v[162:165], v187
	ds_read_b128 v[166:169], v188
	ds_read_b128 v[190:193], v189
	s_add_u32 s64, s72, 0x40000
	s_addc_u32 s65, s73, 0
	s_mov_b32 m0, s43
	ds_read_b128 v[194:197], v172 offset:32768
	ds_read_b128 v[198:201], v172 offset:33792
	ds_read_b128 v[202:205], v172 offset:34816
	ds_read_b128 v[206:209], v172 offset:35840
	ds_read_b128 v[210:213], v172 offset:36864
	ds_read_b128 v[214:217], v172 offset:37888
	ds_read_b128 v[218:221], v172 offset:38912
	ds_read_b128 v[224:227], v172 offset:39936
	global_load_lds_dwordx4 v128, s[64:65]
	v_lshl_add_u64 v[234:235], s[64:65], 0, v[130:131]
	s_mov_b32 m0, s74
	s_nop 0
	global_load_lds_dwordx4 v[234:235], off
	s_waitcnt vmcnt(8)
	s_waitcnt lgkmcnt(0)
	s_barrier
	s_setprio 1
	s_waitcnt lgkmcnt(0)
	v_mfma_f32_16x16x32_bf16 v[124:127], v[142:145], v[194:197], v[124:127]
	v_mfma_f32_16x16x32_bf16 v[108:111], v[150:153], v[194:197], v[108:111]
	v_mfma_f32_16x16x32_bf16 v[120:123], v[142:145], v[202:205], v[120:123]
	v_mfma_f32_16x16x32_bf16 v[96:99], v[150:153], v[202:205], v[96:99]
	v_mfma_f32_16x16x32_bf16 v[116:119], v[142:145], v[210:213], v[116:119]
	v_mfma_f32_16x16x32_bf16 v[88:91], v[150:153], v[210:213], v[88:91]
	v_mfma_f32_16x16x32_bf16 v[112:115], v[142:145], v[218:221], v[112:115]
	v_mfma_f32_16x16x32_bf16 v[84:87], v[150:153], v[218:221], v[84:87]
	v_mfma_f32_16x16x32_bf16 v[124:127], v[146:149], v[198:201], v[124:127]
	v_mfma_f32_16x16x32_bf16 v[108:111], v[154:157], v[198:201], v[108:111]
	v_mfma_f32_16x16x32_bf16 v[120:123], v[146:149], v[206:209], v[120:123]
	v_mfma_f32_16x16x32_bf16 v[96:99], v[154:157], v[206:209], v[96:99]
	v_mfma_f32_16x16x32_bf16 v[116:119], v[146:149], v[214:217], v[116:119]
	v_mfma_f32_16x16x32_bf16 v[88:91], v[154:157], v[214:217], v[88:91]
	v_mfma_f32_16x16x32_bf16 v[112:115], v[146:149], v[224:227], v[112:115]
	v_mfma_f32_16x16x32_bf16 v[84:87], v[154:157], v[224:227], v[84:87]
	s_setprio 0
	s_setprio 1
	v_mfma_f32_16x16x32_bf16 v[68:71], v[158:161], v[194:197], v[68:71]
	v_mfma_f32_16x16x32_bf16 v[40:43], v[166:169], v[194:197], v[40:43]
	v_mfma_f32_16x16x32_bf16 v[60:63], v[158:161], v[202:205], v[60:63]
	v_mfma_f32_16x16x32_bf16 v[32:35], v[166:169], v[202:205], v[32:35]
	v_mfma_f32_16x16x32_bf16 v[52:55], v[158:161], v[210:213], v[52:55]
	v_mfma_f32_16x16x32_bf16 v[24:27], v[166:169], v[210:213], v[24:27]
	v_mfma_f32_16x16x32_bf16 v[48:51], v[158:161], v[218:221], v[48:51]
	v_mfma_f32_16x16x32_bf16 v[16:19], v[166:169], v[218:221], v[16:19]
	v_mfma_f32_16x16x32_bf16 v[68:71], v[162:165], v[198:201], v[68:71]
	v_mfma_f32_16x16x32_bf16 v[40:43], v[190:193], v[198:201], v[40:43]
	v_mfma_f32_16x16x32_bf16 v[60:63], v[162:165], v[206:209], v[60:63]
	v_mfma_f32_16x16x32_bf16 v[32:35], v[190:193], v[206:209], v[32:35]
	v_mfma_f32_16x16x32_bf16 v[52:55], v[162:165], v[214:217], v[52:55]
	v_mfma_f32_16x16x32_bf16 v[24:27], v[190:193], v[214:217], v[24:27]
	v_mfma_f32_16x16x32_bf16 v[48:51], v[162:165], v[224:227], v[48:51]
	v_mfma_f32_16x16x32_bf16 v[16:19], v[190:193], v[224:227], v[16:19]
	s_setprio 0
	s_barrier
	s_mov_b32 m0, s78
	v_lshl_add_u64 v[170:171], v[170:171], 0, s[10:11]
	s_add_u32 s64, s70, 0x40080
	ds_read_b128 v[194:197], v172 offset:49152
	ds_read_b128 v[198:201], v172 offset:50176
	ds_read_b128 v[202:205], v172 offset:51200
	ds_read_b128 v[206:209], v172 offset:52224
	ds_read_b128 v[210:213], v172 offset:53248
	ds_read_b128 v[214:217], v172 offset:54272
	ds_read_b128 v[218:221], v172 offset:55296
	ds_read_b128 v[224:227], v172 offset:56320
	global_load_lds_dwordx4 v[170:171], off
	v_lshl_add_u64 v[170:171], v[228:229], 0, s[10:11]
	s_mov_b32 m0, s79
	s_addc_u32 s65, s71, 0
	global_load_lds_dwordx4 v[170:171], off
	s_mov_b32 m0, s82
	s_nop 0
	global_load_lds_dwordx4 v128, s[64:65]
	s_mov_b32 m0, s83
	s_nop 0
	global_load_lds_dwordx4 v130, s[64:65]
	v_lshl_add_u64 v[170:171], v[230:231], 0, s[10:11]
	s_mov_b32 m0, s80
	s_nop 0
	global_load_lds_dwordx4 v[170:171], off
	v_lshl_add_u64 v[170:171], v[232:233], 0, s[10:11]
	s_mov_b32 m0, s81
	s_nop 0
	global_load_lds_dwordx4 v[170:171], off
	s_waitcnt vmcnt(8)
	s_waitcnt lgkmcnt(0)
	s_barrier
	s_setprio 1
	s_waitcnt lgkmcnt(0)
	v_mfma_f32_16x16x32_bf16 v[104:107], v[142:145], v[194:197], v[104:107]
	v_mfma_f32_16x16x32_bf16 v[76:79], v[150:153], v[194:197], v[76:79]
	v_mfma_f32_16x16x32_bf16 v[100:103], v[142:145], v[202:205], v[100:103]
	v_mfma_f32_16x16x32_bf16 v[72:75], v[150:153], v[202:205], v[72:75]
	v_mfma_f32_16x16x32_bf16 v[92:95], v[142:145], v[210:213], v[92:95]
	v_mfma_f32_16x16x32_bf16 v[64:67], v[150:153], v[210:213], v[64:67]
	v_mfma_f32_16x16x32_bf16 v[80:83], v[142:145], v[218:221], v[80:83]
	v_mfma_f32_16x16x32_bf16 v[56:59], v[150:153], v[218:221], v[56:59]
	v_mfma_f32_16x16x32_bf16 v[104:107], v[146:149], v[198:201], v[104:107]
	v_mfma_f32_16x16x32_bf16 v[76:79], v[154:157], v[198:201], v[76:79]
	v_mfma_f32_16x16x32_bf16 v[100:103], v[146:149], v[206:209], v[100:103]
	v_mfma_f32_16x16x32_bf16 v[72:75], v[154:157], v[206:209], v[72:75]
	v_mfma_f32_16x16x32_bf16 v[92:95], v[146:149], v[214:217], v[92:95]
	v_mfma_f32_16x16x32_bf16 v[64:67], v[154:157], v[214:217], v[64:67]
	v_mfma_f32_16x16x32_bf16 v[80:83], v[146:149], v[224:227], v[80:83]
	v_mfma_f32_16x16x32_bf16 v[56:59], v[154:157], v[224:227], v[56:59]
	s_setprio 0
	s_setprio 1
	v_mfma_f32_16x16x32_bf16 v[44:47], v[158:161], v[194:197], v[44:47]
	v_mfma_f32_16x16x32_bf16 v[12:15], v[166:169], v[194:197], v[12:15]
	v_mfma_f32_16x16x32_bf16 v[36:39], v[158:161], v[202:205], v[36:39]
	v_mfma_f32_16x16x32_bf16 v[8:11], v[166:169], v[202:205], v[8:11]
	v_mfma_f32_16x16x32_bf16 v[28:31], v[158:161], v[210:213], v[28:31]
	v_mfma_f32_16x16x32_bf16 v[4:7], v[166:169], v[210:213], v[4:7]
	v_mfma_f32_16x16x32_bf16 v[20:23], v[158:161], v[218:221], v[20:23]
	v_mfma_f32_16x16x32_bf16 v[0:3], v[166:169], v[218:221], v[0:3]
	v_mfma_f32_16x16x32_bf16 v[44:47], v[162:165], v[198:201], v[44:47]
	v_mfma_f32_16x16x32_bf16 v[12:15], v[190:193], v[198:201], v[12:15]
	v_mfma_f32_16x16x32_bf16 v[36:39], v[162:165], v[206:209], v[36:39]
	v_mfma_f32_16x16x32_bf16 v[8:11], v[190:193], v[206:209], v[8:11]
	v_mfma_f32_16x16x32_bf16 v[28:31], v[162:165], v[214:217], v[28:31]
	v_mfma_f32_16x16x32_bf16 v[4:7], v[190:193], v[214:217], v[4:7]
	v_mfma_f32_16x16x32_bf16 v[20:23], v[162:165], v[224:227], v[20:23]
	v_mfma_f32_16x16x32_bf16 v[0:3], v[190:193], v[224:227], v[0:3]
	s_setprio 0
	s_barrier
	s_add_i32 s6, s6, 2
	s_add_u32 s90, s90, 0x100
	s_addc_u32 s92, s92, 0
	s_cmp_gt_u32 s6, 13
	s_mov_b64 s[64:65], s[66:67]
	s_cbranch_scc0 .LBB0_634
	s_and_b64 vcc, exec, s[52:53]
	s_cbranch_vccz .LBB0_637
	s_barrier

; #define PG8_STAGE(bufoff, gbase, voff) do { _Pragma("unroll") for (int _i = 0; _i < 2; ++_i) \
;         __builtin_amdgcn_global_load_lds((const unsigned*)((const char*)(gbase) + (voff)[_i]), (PG8_LAS unsigned*)(lds + (bufoff) + ldsw + _i * 8192), 16, 0, 0); } while (0)
; #define PG8_LDA(dst, b, h) do { _Pragma("unroll") for (int m = 0; m < 4; ++m) _Pragma("unroll") for (int k = 0; k < 2; ++k) dst[m][k] = *(const PG8_LAS bf16x8*)(lds + PG8_SA(b, h) + aoff + m * 2048 + k * 1024); } while (0)
; #define PG8_LDB(dst, b, h) do { _Pragma("unroll") for (int n = 0; n < 2; ++n) _Pragma("unroll") for (int k = 0; k < 2; ++k) dst[n][k] = *(const PG8_LAS bf16x8*)(lds + PG8_SB(b, h) + boff + n * 2048 + k * 1024); } while (0)
; #define PG8_MMA(ai, bj, At, Bt) do { __builtin_amdgcn_s_setprio(1); _Pragma("unroll") for (int m = 0; m < 4; ++m) _Pragma("unroll") for (int n = 0; n < 2; ++n) _Pragma("unroll") for (int k = 0; k < 2; ++k) \
;         acc[ai][bj][m][n] = __builtin_amdgcn_mfma_f32_16x16x32_bf16(Bt[n][k], At[m][k], acc[ai][bj][m][n], 0, 0, 0); __builtin_amdgcn_s_setprio(0); } while (0)
; #define PG8_WAIT_V(n) asm volatile("s_waitcnt vmcnt(" #n ")" ::: "memory")
; #define PG8_WAIT_L(n) asm volatile("s_waitcnt lgkmcnt(" #n ")" ::: "memory")
; #define PG8_BAR __builtin_amdgcn_s_barrier()
; #define PG8_SCHED __builtin_amdgcn_sched_barrier(0)
; template <class Epi, class Sched, bool ALIGN_EPI = false, bool SP2 = false>
; __device__ __forceinline__ void gemm_phase(PG8_LAS unsigned char* lds, const Gemm g, const Sched& S, const Epi& E) {
;     ...
;             PG8_LDB(B0, 0, 0); PG8_LDB(B1, 0, 1); PG8_SCHED; PG8_LDA(At, 0, 0); PG8_STAGE(PG8_SA(1, 1), a1 + hstep, voffA);
;             PG8_WAIT_V(8); PG8_WAIT_L(0); PG8_BAR; PG8_MMA(0, 0, At, B0); PG8_MMA(0, 1, At, B1); PG8_BAR; PG8_SCHED;
;             PG8_LDA(At, 0, 1); PG8_STAGE(PG8_SB(0, 0), b2, voffB); PG8_STAGE(PG8_SB(0, 1), b2 + hstep, voffB); PG8_STAGE(PG8_SA(0, 0), a2, voffA);
;             PG8_WAIT_V(8); PG8_WAIT_L(0); PG8_BAR; PG8_MMA(1, 0, At, B0); PG8_MMA(1, 1, At, B1); PG8_BAR; PG8_SCHED;
.LBB0_655:
	ds_read_b128 v[156:159], v140
	ds_read_b128 v[160:163], v141
	ds_read_b128 v[164:167], v142
	ds_read_b128 v[168:171], v143
	ds_read_b128 v[172:175], v144
	ds_read_b128 v[176:179], v145
	ds_read_b128 v[180:183], v146
	ds_read_b128 v[184:187], v147
	s_add_i32 s7, s6, 2
	s_add_u32 s74, s72, 0x100
	s_addc_u32 s75, s73, 0
	s_cmp_eq_u32 s87, s6
	s_cselect_b32 s79, s55, s75
	s_cselect_b32 s78, s57, s74
	s_cselect_b32 s77, s59, s92
	s_cselect_b32 s76, s61, s90
	s_mov_b32 m0, s88
	v_lshl_add_u64 v[220:221], s[72:73], 0, v[134:135]
	ds_read_b128 v[188:191], v138
	ds_read_b128 v[192:195], v138 offset:1024
	ds_read_b128 v[196:199], v138 offset:2048
	ds_read_b128 v[200:203], v138 offset:3072
	ds_read_b128 v[204:207], v138 offset:4096
	ds_read_b128 v[208:211], v138 offset:5120
	ds_read_b128 v[212:215], v138 offset:6144
	ds_read_b128 v[216:219], v138 offset:7168
	global_load_lds_dwordx4 v[220:221], off
	v_lshl_add_u64 v[220:221], s[72:73], 0, v[136:137]
	s_mov_b32 m0, s89
	s_nop 0
	global_load_lds_dwordx4 v[220:221], off
	s_waitcnt vmcnt(8)
	s_waitcnt lgkmcnt(0)
	s_barrier
	s_setprio 1
	s_waitcnt lgkmcnt(0)
	v_mfma_f32_16x16x32_bf16 v[124:127], v[156:159], v[188:191], v[124:127]
	v_mfma_f32_16x16x32_bf16 v[120:123], v[164:167], v[188:191], v[120:123]
	v_mfma_f32_16x16x32_bf16 v[108:111], v[156:159], v[196:199], v[108:111]
	v_mfma_f32_16x16x32_bf16 v[104:107], v[164:167], v[196:199], v[104:107]
	v_mfma_f32_16x16x32_bf16 v[92:95], v[156:159], v[204:207], v[92:95]
	v_mfma_f32_16x16x32_bf16 v[88:91], v[164:167], v[204:207], v[88:91]
	v_mfma_f32_16x16x32_bf16 v[76:79], v[156:159], v[212:215], v[76:79]
	v_mfma_f32_16x16x32_bf16 v[72:75], v[164:167], v[212:215], v[72:75]
	v_mfma_f32_16x16x32_bf16 v[124:127], v[160:163], v[192:195], v[124:127]
	v_mfma_f32_16x16x32_bf16 v[120:123], v[168:171], v[192:195], v[120:123]
	v_mfma_f32_16x16x32_bf16 v[108:111], v[160:163], v[200:203], v[108:111]
	v_mfma_f32_16x16x32_bf16 v[104:107], v[168:171], v[200:203], v[104:107]
	v_mfma_f32_16x16x32_bf16 v[92:95], v[160:163], v[208:211], v[92:95]
	v_mfma_f32_16x16x32_bf16 v[88:91], v[168:171], v[208:211], v[88:91]
	v_mfma_f32_16x16x32_bf16 v[76:79], v[160:163], v[216:219], v[76:79]
	v_mfma_f32_16x16x32_bf16 v[72:75], v[168:171], v[216:219], v[72:75]
	s_setprio 0
	s_setprio 1
	v_mfma_f32_16x16x32_bf16 v[116:119], v[172:175], v[188:191], v[116:119]
	v_mfma_f32_16x16x32_bf16 v[112:115], v[180:183], v[188:191], v[112:115]
	v_mfma_f32_16x16x32_bf16 v[100:103], v[172:175], v[196:199], v[100:103]
	v_mfma_f32_16x16x32_bf16 v[96:99], v[180:183], v[196:199], v[96:99]
	v_mfma_f32_16x16x32_bf16 v[84:87], v[172:175], v[204:207], v[84:87]
	v_mfma_f32_16x16x32_bf16 v[80:83], v[180:183], v[204:207], v[80:83]
	v_mfma_f32_16x16x32_bf16 v[68:71], v[172:175], v[212:215], v[68:71]
	v_mfma_f32_16x16x32_bf16 v[64:67], v[180:183], v[212:215], v[64:67]
	v_mfma_f32_16x16x32_bf16 v[116:119], v[176:179], v[192:195], v[116:119]
	v_mfma_f32_16x16x32_bf16 v[112:115], v[184:187], v[192:195], v[112:115]
	v_mfma_f32_16x16x32_bf16 v[100:103], v[176:179], v[200:203], v[100:103]
	v_mfma_f32_16x16x32_bf16 v[96:99], v[184:187], v[200:203], v[96:99]
	v_mfma_f32_16x16x32_bf16 v[84:87], v[176:179], v[208:211], v[84:87]
	v_mfma_f32_16x16x32_bf16 v[80:83], v[184:187], v[208:211], v[80:83]
	v_mfma_f32_16x16x32_bf16 v[68:71], v[176:179], v[216:219], v[68:71]
	v_mfma_f32_16x16x32_bf16 v[64:67], v[184:187], v[216:219], v[64:67]
	s_setprio 0
	s_barrier
	s_mov_b32 m0, s13
	v_lshl_add_u64 v[220:221], s[76:77], 0, v[130:131]
	s_add_u32 s72, s76, 0x40000
	ds_read_b128 v[188:191], v138 offset:16384
	ds_read_b128 v[192:195], v138 offset:17408
	ds_read_b128 v[196:199], v138 offset:18432
	ds_read_b128 v[200:203], v138 offset:19456
	ds_read_b128 v[204:207], v138 offset:20480
	ds_read_b128 v[208:211], v138 offset:21504
	ds_read_b128 v[212:215], v138 offset:22528
	ds_read_b128 v[216:219], v138 offset:23552
	global_load_lds_dwordx4 v[220:221], off
	v_lshl_add_u64 v[224:225], s[76:77], 0, v[128:129]
	s_mov_b32 m0, s14
	s_addc_u32 s73, s77, 0
	global_load_lds_dwordx4 v[224:225], off
	s_mov_b32 m0, s15
	v_lshl_add_u64 v[228:229], s[78:79], 0, v[128:129]
	global_load_lds_dwordx4 v130, s[72:73]
	s_mov_b32 m0, s33
	s_nop 0
	global_load_lds_dwordx4 v128, s[72:73]
	v_lshl_add_u64 v[226:227], s[78:79], 0, v[130:131]
	s_mov_b32 m0, s12
	s_nop 0
	global_load_lds_dwordx4 v[226:227], off
	s_mov_b32 m0, s39
	s_nop 0
	global_load_lds_dwordx4 v[228:229], off
	s_waitcnt vmcnt(8)
	s_waitcnt lgkmcnt(0)
	s_barrier
	s_setprio 1
	s_waitcnt lgkmcnt(0)
	v_mfma_f32_16x16x32_bf16 v[60:63], v[156:159], v[188:191], v[60:63]
	v_mfma_f32_16x16x32_bf16 v[56:59], v[164:167], v[188:191], v[56:59]
	v_mfma_f32_16x16x32_bf16 v[44:47], v[156:159], v[196:199], v[44:47]
	v_mfma_f32_16x16x32_bf16 v[40:43], v[164:167], v[196:199], v[40:43]
	v_mfma_f32_16x16x32_bf16 v[28:31], v[156:159], v[204:207], v[28:31]
	v_mfma_f32_16x16x32_bf16 v[24:27], v[164:167], v[204:207], v[24:27]
	v_mfma_f32_16x16x32_bf16 v[12:15], v[156:159], v[212:215], v[12:15]
	v_mfma_f32_16x16x32_bf16 v[8:11], v[164:167], v[212:215], v[8:11]
	v_mfma_f32_16x16x32_bf16 v[60:63], v[160:163], v[192:195], v[60:63]
	v_mfma_f32_16x16x32_bf16 v[56:59], v[168:171], v[192:195], v[56:59]
	v_mfma_f32_16x16x32_bf16 v[44:47], v[160:163], v[200:203], v[44:47]
	v_mfma_f32_16x16x32_bf16 v[40:43], v[168:171], v[200:203], v[40:43]
	v_mfma_f32_16x16x32_bf16 v[28:31], v[160:163], v[208:211], v[28:31]
	v_mfma_f32_16x16x32_bf16 v[24:27], v[168:171], v[208:211], v[24:27]
	v_mfma_f32_16x16x32_bf16 v[12:15], v[160:163], v[216:219], v[12:15]
	v_mfma_f32_16x16x32_bf16 v[8:11], v[168:171], v[216:219], v[8:11]
	s_setprio 0
	s_setprio 1
	v_mfma_f32_16x16x32_bf16 v[52:55], v[172:175], v[188:191], v[52:55]
	v_mfma_f32_16x16x32_bf16 v[48:51], v[180:183], v[188:191], v[48:51]
	v_mfma_f32_16x16x32_bf16 v[36:39], v[172:175], v[196:199], v[36:39]
	v_mfma_f32_16x16x32_bf16 v[32:35], v[180:183], v[196:199], v[32:35]
	v_mfma_f32_16x16x32_bf16 v[20:23], v[172:175], v[204:207], v[20:23]
	v_mfma_f32_16x16x32_bf16 v[16:19], v[180:183], v[204:207], v[16:19]
	v_mfma_f32_16x16x32_bf16 v[4:7], v[172:175], v[212:215], v[4:7]
	v_mfma_f32_16x16x32_bf16 v[0:3], v[180:183], v[212:215], v[0:3]
	v_mfma_f32_16x16x32_bf16 v[52:55], v[176:179], v[192:195], v[52:55]
	v_mfma_f32_16x16x32_bf16 v[48:51], v[184:187], v[192:195], v[48:51]
	v_mfma_f32_16x16x32_bf16 v[36:39], v[176:179], v[200:203], v[36:39]
	v_mfma_f32_16x16x32_bf16 v[32:35], v[184:187], v[200:203], v[32:35]
	v_mfma_f32_16x16x32_bf16 v[20:23], v[176:179], v[208:211], v[20:23]
	v_mfma_f32_16x16x32_bf16 v[16:19], v[184:187], v[208:211], v[16:19]
	v_mfma_f32_16x16x32_bf16 v[4:7], v[176:179], v[216:219], v[4:7]
	v_mfma_f32_16x16x32_bf16 v[0:3], v[184:187], v[216:219], v[0:3]
	s_setprio 0
	s_barrier
; #define PG8_STAGE(bufoff, gbase, voff) do { _Pragma("unroll") for (int _i = 0; _i < 2; ++_i) \
;         __builtin_amdgcn_global_load_lds((const unsigned*)((const char*)(gbase) + (voff)[_i]), (PG8_LAS unsigned*)(lds + (bufoff) + ldsw + _i * 8192), 16, 0, 0); } while (0)
; #define PG8_LDA(dst, b, h) do { _Pragma("unroll") for (int m = 0; m < 4; ++m) _Pragma("unroll") for (int k = 0; k < 2; ++k) dst[m][k] = *(const PG8_LAS bf16x8*)(lds + PG8_SA(b, h) + aoff + m * 2048 + k * 1024); } while (0)
; #define PG8_LDB(dst, b, h) do { _Pragma("unroll") for (int n = 0; n < 2; ++n) _Pragma("unroll") for (int k = 0; k < 2; ++k) dst[n][k] = *(const PG8_LAS bf16x8*)(lds + PG8_SB(b, h) + boff + n * 2048 + k * 1024); } while (0)
; #define PG8_MMA(ai, bj, At, Bt) do { __builtin_amdgcn_s_setprio(1); _Pragma("unroll") for (int m = 0; m < 4; ++m) _Pragma("unroll") for (int n = 0; n < 2; ++n) _Pragma("unroll") for (int k = 0; k < 2; ++k) \
;         acc[ai][bj][m][n] = __builtin_amdgcn_mfma_f32_16x16x32_bf16(Bt[n][k], At[m][k], acc[ai][bj][m][n], 0, 0, 0); __builtin_amdgcn_s_setprio(0); } while (0)
; #define PG8_WAIT_V(n) asm volatile("s_waitcnt vmcnt(" #n ")" ::: "memory")
; #define PG8_WAIT_L(n) asm volatile("s_waitcnt lgkmcnt(" #n ")" ::: "memory")
; #define PG8_BAR __builtin_amdgcn_s_barrier()
; template <class Epi, class Sched, bool ALIGN_EPI = false, bool SP2 = false>
; __device__ __forceinline__ void gemm_phase(PG8_LAS unsigned char* lds, const Gemm g, const Sched& S, const Epi& E) {
;     ...
;         for (int t = 0; t < nt; t += 2) {
;             const bool last = (t == nt - 2);
;             const char* a1 = cA + (size_t)(t + 1) * kstep;
;             const char* a2 = last ? nA : cA + (size_t)(t + 2) * kstep; const char* b2 = last ? nB : cB + (size_t)(t + 2) * kstep;
;             const char* a3 = a2 + kstep; const char* b3 = b2 + kstep;
;     ...
;             PG8_LDB(B0, 1, 0); PG8_LDB(B1, 1, 1); PG8_SCHED; PG8_LDA(At, 1, 0); PG8_STAGE(PG8_SA(0, 1), a2 + hstep, voffA);
;             PG8_WAIT_V(8); PG8_WAIT_L(0); PG8_BAR; PG8_MMA(0, 0, At, B0); PG8_MMA(0, 1, At, B1); PG8_BAR; PG8_SCHED;
;             PG8_LDA(At, 1, 1); PG8_STAGE(PG8_SB(1, 0), b3, voffB); PG8_STAGE(PG8_SB(1, 1), b3 + hstep, voffB); PG8_STAGE(PG8_SA(1, 0), a3, voffA);
;             PG8_WAIT_V(8); PG8_WAIT_L(0); PG8_BAR; PG8_MMA(1, 0, At, B0); PG8_MMA(1, 1, At, B1); PG8_BAR; PG8_SCHED;
	ds_read_b128 v[156:159], v148
	ds_read_b128 v[160:163], v149
	ds_read_b128 v[164:167], v150
	ds_read_b128 v[168:171], v151
	ds_read_b128 v[172:175], v152
	ds_read_b128 v[176:179], v153
	ds_read_b128 v[180:183], v154
	ds_read_b128 v[184:187], v155
	s_add_u32 s72, s78, 0x40000
	s_addc_u32 s73, s79, 0
	s_mov_b32 m0, s43
	ds_read_b128 v[188:191], v138 offset:32768
	ds_read_b128 v[192:195], v138 offset:33792
	ds_read_b128 v[196:199], v138 offset:34816
	ds_read_b128 v[200:203], v138 offset:35840
	ds_read_b128 v[204:207], v138 offset:36864
	ds_read_b128 v[208:211], v138 offset:37888
	ds_read_b128 v[212:215], v138 offset:38912
	ds_read_b128 v[216:219], v138 offset:39936
	global_load_lds_dwordx4 v130, s[72:73]
	v_lshl_add_u64 v[230:231], s[72:73], 0, v[128:129]
	s_mov_b32 m0, s65
	s_nop 0
	global_load_lds_dwordx4 v[230:231], off
	s_waitcnt vmcnt(8)
	s_waitcnt lgkmcnt(0)
	s_barrier
	s_setprio 1
	s_waitcnt lgkmcnt(0)
	v_mfma_f32_16x16x32_bf16 v[124:127], v[156:159], v[188:191], v[124:127]
	v_mfma_f32_16x16x32_bf16 v[120:123], v[164:167], v[188:191], v[120:123]
	v_mfma_f32_16x16x32_bf16 v[108:111], v[156:159], v[196:199], v[108:111]
	v_mfma_f32_16x16x32_bf16 v[104:107], v[164:167], v[196:199], v[104:107]
	v_mfma_f32_16x16x32_bf16 v[92:95], v[156:159], v[204:207], v[92:95]
	v_mfma_f32_16x16x32_bf16 v[88:91], v[164:167], v[204:207], v[88:91]
	v_mfma_f32_16x16x32_bf16 v[76:79], v[156:159], v[212:215], v[76:79]
	v_mfma_f32_16x16x32_bf16 v[72:75], v[164:167], v[212:215], v[72:75]
	v_mfma_f32_16x16x32_bf16 v[124:127], v[160:163], v[192:195], v[124:127]
	v_mfma_f32_16x16x32_bf16 v[120:123], v[168:171], v[192:195], v[120:123]
	v_mfma_f32_16x16x32_bf16 v[108:111], v[160:163], v[200:203], v[108:111]
	v_mfma_f32_16x16x32_bf16 v[104:107], v[168:171], v[200:203], v[104:107]
	v_mfma_f32_16x16x32_bf16 v[92:95], v[160:163], v[208:211], v[92:95]
	v_mfma_f32_16x16x32_bf16 v[88:91], v[168:171], v[208:211], v[88:91]
	v_mfma_f32_16x16x32_bf16 v[76:79], v[160:163], v[216:219], v[76:79]
	v_mfma_f32_16x16x32_bf16 v[72:75], v[168:171], v[216:219], v[72:75]
	s_setprio 0
	s_setprio 1
	v_mfma_f32_16x16x32_bf16 v[116:119], v[172:175], v[188:191], v[116:119]
	v_mfma_f32_16x16x32_bf16 v[112:115], v[180:183], v[188:191], v[112:115]
	v_mfma_f32_16x16x32_bf16 v[100:103], v[172:175], v[196:199], v[100:103]
	v_mfma_f32_16x16x32_bf16 v[96:99], v[180:183], v[196:199], v[96:99]
	v_mfma_f32_16x16x32_bf16 v[84:87], v[172:175], v[204:207], v[84:87]
	v_mfma_f32_16x16x32_bf16 v[80:83], v[180:183], v[204:207], v[80:83]
	v_mfma_f32_16x16x32_bf16 v[68:71], v[172:175], v[212:215], v[68:71]
	v_mfma_f32_16x16x32_bf16 v[64:67], v[180:183], v[212:215], v[64:67]
	v_mfma_f32_16x16x32_bf16 v[116:119], v[176:179], v[192:195], v[116:119]
	v_mfma_f32_16x16x32_bf16 v[112:115], v[184:187], v[192:195], v[112:115]
	v_mfma_f32_16x16x32_bf16 v[100:103], v[176:179], v[200:203], v[100:103]
	v_mfma_f32_16x16x32_bf16 v[96:99], v[184:187], v[200:203], v[96:99]
	v_mfma_f32_16x16x32_bf16 v[84:87], v[176:179], v[208:211], v[84:87]
	v_mfma_f32_16x16x32_bf16 v[80:83], v[184:187], v[208:211], v[80:83]
	v_mfma_f32_16x16x32_bf16 v[68:71], v[176:179], v[216:219], v[68:71]
	v_mfma_f32_16x16x32_bf16 v[64:67], v[184:187], v[216:219], v[64:67]
	s_setprio 0
	s_barrier
	s_mov_b32 m0, s81
	v_lshl_add_u64 v[220:221], v[220:221], 0, s[36:37]
	s_add_u32 s72, s76, 0x40080
	ds_read_b128 v[188:191], v138 offset:49152
	ds_read_b128 v[192:195], v138 offset:50176
	ds_read_b128 v[196:199], v138 offset:51200
	ds_read_b128 v[200:203], v138 offset:52224
	ds_read_b128 v[204:207], v138 offset:53248
	ds_read_b128 v[208:211], v138 offset:54272
	ds_read_b128 v[212:215], v138 offset:55296
	ds_read_b128 v[216:219], v138 offset:56320
	global_load_lds_dwordx4 v[220:221], off
	v_lshl_add_u64 v[220:221], v[224:225], 0, s[36:37]
	s_mov_b32 m0, s82
	s_addc_u32 s73, s77, 0
	global_load_lds_dwordx4 v[220:221], off
	s_mov_b32 m0, s85
	s_nop 0
	global_load_lds_dwordx4 v130, s[72:73]
	s_mov_b32 m0, s86
	s_nop 0
	global_load_lds_dwordx4 v128, s[72:73]
	v_lshl_add_u64 v[220:221], v[226:227], 0, s[36:37]
	s_mov_b32 m0, s83
	s_nop 0
	global_load_lds_dwordx4 v[220:221], off
	v_lshl_add_u64 v[220:221], v[228:229], 0, s[36:37]
	s_mov_b32 m0, s84
	s_nop 0
	global_load_lds_dwordx4 v[220:221], off
	s_waitcnt vmcnt(8)
	s_waitcnt lgkmcnt(0)
	s_barrier
	s_setprio 1
	s_waitcnt lgkmcnt(0)
	v_mfma_f32_16x16x32_bf16 v[60:63], v[156:159], v[188:191], v[60:63]
	v_mfma_f32_16x16x32_bf16 v[56:59], v[164:167], v[188:191], v[56:59]
	v_mfma_f32_16x16x32_bf16 v[44:47], v[156:159], v[196:199], v[44:47]
	v_mfma_f32_16x16x32_bf16 v[40:43], v[164:167], v[196:199], v[40:43]
	v_mfma_f32_16x16x32_bf16 v[28:31], v[156:159], v[204:207], v[28:31]
	v_mfma_f32_16x16x32_bf16 v[24:27], v[164:167], v[204:207], v[24:27]
	v_mfma_f32_16x16x32_bf16 v[12:15], v[156:159], v[212:215], v[12:15]
	v_mfma_f32_16x16x32_bf16 v[8:11], v[164:167], v[212:215], v[8:11]
	v_mfma_f32_16x16x32_bf16 v[60:63], v[160:163], v[192:195], v[60:63]
	v_mfma_f32_16x16x32_bf16 v[56:59], v[168:171], v[192:195], v[56:59]
	v_mfma_f32_16x16x32_bf16 v[44:47], v[160:163], v[200:203], v[44:47]
	v_mfma_f32_16x16x32_bf16 v[40:43], v[168:171], v[200:203], v[40:43]
	v_mfma_f32_16x16x32_bf16 v[28:31], v[160:163], v[208:211], v[28:31]
	v_mfma_f32_16x16x32_bf16 v[24:27], v[168:171], v[208:211], v[24:27]
	v_mfma_f32_16x16x32_bf16 v[12:15], v[160:163], v[216:219], v[12:15]
	v_mfma_f32_16x16x32_bf16 v[8:11], v[168:171], v[216:219], v[8:11]
	s_setprio 0
	s_setprio 1
	v_mfma_f32_16x16x32_bf16 v[52:55], v[172:175], v[188:191], v[52:55]
	v_mfma_f32_16x16x32_bf16 v[48:51], v[180:183], v[188:191], v[48:51]
	v_mfma_f32_16x16x32_bf16 v[36:39], v[172:175], v[196:199], v[36:39]
	v_mfma_f32_16x16x32_bf16 v[32:35], v[180:183], v[196:199], v[32:35]
	v_mfma_f32_16x16x32_bf16 v[20:23], v[172:175], v[204:207], v[20:23]
	v_mfma_f32_16x16x32_bf16 v[16:19], v[180:183], v[204:207], v[16:19]
	v_mfma_f32_16x16x32_bf16 v[4:7], v[172:175], v[212:215], v[4:7]
	v_mfma_f32_16x16x32_bf16 v[0:3], v[180:183], v[212:215], v[0:3]
	v_mfma_f32_16x16x32_bf16 v[52:55], v[176:179], v[192:195], v[52:55]
	v_mfma_f32_16x16x32_bf16 v[48:51], v[184:187], v[192:195], v[48:51]
	v_mfma_f32_16x16x32_bf16 v[36:39], v[176:179], v[200:203], v[36:39]
	v_mfma_f32_16x16x32_bf16 v[32:35], v[184:187], v[200:203], v[32:35]
	v_mfma_f32_16x16x32_bf16 v[20:23], v[176:179], v[208:211], v[20:23]
	v_mfma_f32_16x16x32_bf16 v[16:19], v[184:187], v[208:211], v[16:19]
	v_mfma_f32_16x16x32_bf16 v[4:7], v[176:179], v[216:219], v[4:7]
	v_mfma_f32_16x16x32_bf16 v[0:3], v[184:187], v[216:219], v[0:3]
	s_setprio 0
	s_barrier
	s_add_u32 s90, s90, 0x100
	s_addc_u32 s92, s92, 0
	s_cmp_ge_i32 s7, s3
	s_mov_b64 s[72:73], s[74:75]
	s_mov_b32 s6, s7
	s_cbranch_scc0 .LBB0_655
	s_and_b64 vcc, exec, s[52:53]
	s_cbranch_vccz .LBB0_658

; #define PG8_STAGE(bufoff, gbase, voff) do { _Pragma("unroll") for (int _i = 0; _i < 2; ++_i) \
;         __builtin_amdgcn_global_load_lds((const unsigned*)((const char*)(gbase) + (voff)[_i]), (PG8_LAS unsigned*)(lds + (bufoff) + ldsw + _i * 8192), 16, 0, 0); } while (0)
; #define PG8_LDA(dst, b, h) do { _Pragma("unroll") for (int m = 0; m < 4; ++m) _Pragma("unroll") for (int k = 0; k < 2; ++k) dst[m][k] = *(const PG8_LAS bf16x8*)(lds + PG8_SA(b, h) + aoff + m * 2048 + k * 1024); } while (0)
; #define PG8_LDB(dst, b, h) do { _Pragma("unroll") for (int n = 0; n < 2; ++n) _Pragma("unroll") for (int k = 0; k < 2; ++k) dst[n][k] = *(const PG8_LAS bf16x8*)(lds + PG8_SB(b, h) + boff + n * 2048 + k * 1024); } while (0)
; #define PG8_MMA(ai, bj, At, Bt) do { __builtin_amdgcn_s_setprio(1); _Pragma("unroll") for (int m = 0; m < 4; ++m) _Pragma("unroll") for (int n = 0; n < 2; ++n) _Pragma("unroll") for (int k = 0; k < 2; ++k) \
;         acc[ai][bj][m][n] = __builtin_amdgcn_mfma_f32_16x16x32_bf16(Bt[n][k], At[m][k], acc[ai][bj][m][n], 0, 0, 0); __builtin_amdgcn_s_setprio(0); } while (0)
; #define PG8_WAIT_V(n) asm volatile("s_waitcnt vmcnt(" #n ")" ::: "memory")
; #define PG8_WAIT_L(n) asm volatile("s_waitcnt lgkmcnt(" #n ")" ::: "memory")
; #define PG8_BAR __builtin_amdgcn_s_barrier()
; #define PG8_SCHED __builtin_amdgcn_sched_barrier(0)
; template <class Epi, class Sched, bool ALIGN_EPI = false, bool SP2 = false>
; __device__ __forceinline__ void gemm_phase(PG8_LAS unsigned char* lds, const Gemm g, const Sched& S, const Epi& E) {
;     ...
;             PG8_LDB(B0, 0, 0); PG8_LDB(B1, 0, 1); PG8_SCHED; PG8_LDA(At, 0, 0); PG8_STAGE(PG8_SA(1, 1), a1 + hstep, voffA);
;             PG8_WAIT_V(8); PG8_WAIT_L(0); PG8_BAR; PG8_MMA(0, 0, At, B0); PG8_MMA(0, 1, At, B1); PG8_BAR; PG8_SCHED;
;             PG8_LDA(At, 0, 1); PG8_STAGE(PG8_SB(0, 0), b2, voffB); PG8_STAGE(PG8_SB(0, 1), b2 + hstep, voffB); PG8_STAGE(PG8_SA(0, 0), a2, voffA);
;             PG8_WAIT_V(8); PG8_WAIT_L(0); PG8_BAR; PG8_MMA(1, 0, At, B0); PG8_MMA(1, 1, At, B1); PG8_BAR; PG8_SCHED;
.LBB0_793:
	ds_read_b128 v[166:169], v149
	ds_read_b128 v[170:173], v150
	ds_read_b128 v[174:177], v151
	ds_read_b128 v[178:181], v152
	ds_read_b128 v[182:185], v153
	ds_read_b128 v[186:189], v154
	ds_read_b128 v[190:193], v155
	ds_read_b128 v[194:197], v156
	s_add_u32 s6, s62, 0xfffc0080
	s_addc_u32 s7, s63, -1
	s_cmp_eq_u32 s86, 12
	s_cselect_b32 s67, s55, s7
	s_cselect_b32 s66, s82, s6
	s_cselect_b32 s65, s53, s85
	s_cselect_b32 s64, s83, s84
	s_mov_b32 m0, s79
	ds_read_b128 v[198:201], v147
	ds_read_b128 v[202:205], v147 offset:1024
	ds_read_b128 v[206:209], v147 offset:2048
	ds_read_b128 v[210:213], v147 offset:3072
	ds_read_b128 v[214:217], v147 offset:4096
	ds_read_b128 v[218:221], v147 offset:5120
	ds_read_b128 v[224:227], v147 offset:6144
	ds_read_b128 v[228:231], v147 offset:7168
	global_load_lds_dwordx4 v136, s[62:63]
	s_mov_b32 m0, s80
	s_nop 0
	global_load_lds_dwordx4 v138, s[62:63]
	s_waitcnt vmcnt(8)
	s_waitcnt lgkmcnt(0)
	s_barrier
	s_setprio 1
	s_waitcnt lgkmcnt(0)
	v_mfma_f32_16x16x32_bf16 v[124:127], v[166:169], v[198:201], v[124:127]
	v_mfma_f32_16x16x32_bf16 v[120:123], v[174:177], v[198:201], v[120:123]
	v_mfma_f32_16x16x32_bf16 v[108:111], v[166:169], v[206:209], v[108:111]
	v_mfma_f32_16x16x32_bf16 v[104:107], v[174:177], v[206:209], v[104:107]
	v_mfma_f32_16x16x32_bf16 v[92:95], v[166:169], v[214:217], v[92:95]
	v_mfma_f32_16x16x32_bf16 v[88:91], v[174:177], v[214:217], v[88:91]
	v_mfma_f32_16x16x32_bf16 v[76:79], v[166:169], v[224:227], v[76:79]
	v_mfma_f32_16x16x32_bf16 v[72:75], v[174:177], v[224:227], v[72:75]
	v_mfma_f32_16x16x32_bf16 v[124:127], v[170:173], v[202:205], v[124:127]
	v_mfma_f32_16x16x32_bf16 v[120:123], v[178:181], v[202:205], v[120:123]
	v_mfma_f32_16x16x32_bf16 v[108:111], v[170:173], v[210:213], v[108:111]
	v_mfma_f32_16x16x32_bf16 v[104:107], v[178:181], v[210:213], v[104:107]
	v_mfma_f32_16x16x32_bf16 v[92:95], v[170:173], v[218:221], v[92:95]
	v_mfma_f32_16x16x32_bf16 v[88:91], v[178:181], v[218:221], v[88:91]
	v_mfma_f32_16x16x32_bf16 v[76:79], v[170:173], v[228:231], v[76:79]
	v_mfma_f32_16x16x32_bf16 v[72:75], v[178:181], v[228:231], v[72:75]
	s_setprio 0
	s_setprio 1
	v_mfma_f32_16x16x32_bf16 v[116:119], v[182:185], v[198:201], v[116:119]
	v_mfma_f32_16x16x32_bf16 v[112:115], v[190:193], v[198:201], v[112:115]
	v_mfma_f32_16x16x32_bf16 v[100:103], v[182:185], v[206:209], v[100:103]
	v_mfma_f32_16x16x32_bf16 v[96:99], v[190:193], v[206:209], v[96:99]
	v_mfma_f32_16x16x32_bf16 v[84:87], v[182:185], v[214:217], v[84:87]
	v_mfma_f32_16x16x32_bf16 v[80:83], v[190:193], v[214:217], v[80:83]
	v_mfma_f32_16x16x32_bf16 v[68:71], v[182:185], v[224:227], v[68:71]
	v_mfma_f32_16x16x32_bf16 v[64:67], v[190:193], v[224:227], v[64:67]
	v_mfma_f32_16x16x32_bf16 v[116:119], v[186:189], v[202:205], v[116:119]
	v_mfma_f32_16x16x32_bf16 v[112:115], v[194:197], v[202:205], v[112:115]
	v_mfma_f32_16x16x32_bf16 v[100:103], v[186:189], v[210:213], v[100:103]
	v_mfma_f32_16x16x32_bf16 v[96:99], v[194:197], v[210:213], v[96:99]
	v_mfma_f32_16x16x32_bf16 v[84:87], v[186:189], v[218:221], v[84:87]
	v_mfma_f32_16x16x32_bf16 v[80:83], v[194:197], v[218:221], v[80:83]
	v_mfma_f32_16x16x32_bf16 v[68:71], v[186:189], v[228:231], v[68:71]
	v_mfma_f32_16x16x32_bf16 v[64:67], v[194:197], v[228:231], v[64:67]
	s_setprio 0
	s_barrier
	s_mov_b32 m0, s15
	v_lshl_add_u64 v[144:145], s[64:65], 0, v[132:133]
	s_add_u32 s6, s64, 0x40000
	ds_read_b128 v[198:201], v147 offset:16384
	ds_read_b128 v[202:205], v147 offset:17408
	ds_read_b128 v[206:209], v147 offset:18432
	ds_read_b128 v[210:213], v147 offset:19456
	ds_read_b128 v[214:217], v147 offset:20480
	ds_read_b128 v[218:221], v147 offset:21504
	ds_read_b128 v[224:227], v147 offset:22528
	ds_read_b128 v[228:231], v147 offset:23552
	global_load_lds_dwordx4 v[144:145], off
	v_lshl_add_u64 v[232:233], s[64:65], 0, v[128:129]
	s_mov_b32 m0, s39
	s_addc_u32 s7, s65, 0
	global_load_lds_dwordx4 v[232:233], off
	s_mov_b32 m0, s43
	v_lshl_add_u64 v[236:237], s[66:67], 0, v[130:131]
	global_load_lds_dwordx4 v132, s[6:7]
	s_mov_b32 m0, s61
	s_nop 0
	global_load_lds_dwordx4 v128, s[6:7]
	v_lshl_add_u64 v[234:235], s[66:67], 0, v[134:135]
	s_mov_b32 m0, s12
	s_nop 0
	global_load_lds_dwordx4 v[234:235], off
	s_mov_b32 m0, s68
	s_nop 0
	global_load_lds_dwordx4 v[236:237], off
	s_waitcnt vmcnt(8)
	s_waitcnt lgkmcnt(0)
	s_barrier
	s_setprio 1
	s_waitcnt lgkmcnt(0)
	v_mfma_f32_16x16x32_bf16 v[60:63], v[166:169], v[198:201], v[60:63]
	v_mfma_f32_16x16x32_bf16 v[56:59], v[174:177], v[198:201], v[56:59]
	v_mfma_f32_16x16x32_bf16 v[44:47], v[166:169], v[206:209], v[44:47]
	v_mfma_f32_16x16x32_bf16 v[40:43], v[174:177], v[206:209], v[40:43]
	v_mfma_f32_16x16x32_bf16 v[28:31], v[166:169], v[214:217], v[28:31]
	v_mfma_f32_16x16x32_bf16 v[24:27], v[174:177], v[214:217], v[24:27]
	v_mfma_f32_16x16x32_bf16 v[12:15], v[166:169], v[224:227], v[12:15]
	v_mfma_f32_16x16x32_bf16 v[8:11], v[174:177], v[224:227], v[8:11]
	v_mfma_f32_16x16x32_bf16 v[60:63], v[170:173], v[202:205], v[60:63]
	v_mfma_f32_16x16x32_bf16 v[56:59], v[178:181], v[202:205], v[56:59]
	v_mfma_f32_16x16x32_bf16 v[44:47], v[170:173], v[210:213], v[44:47]
	v_mfma_f32_16x16x32_bf16 v[40:43], v[178:181], v[210:213], v[40:43]
	v_mfma_f32_16x16x32_bf16 v[28:31], v[170:173], v[218:221], v[28:31]
	v_mfma_f32_16x16x32_bf16 v[24:27], v[178:181], v[218:221], v[24:27]
	v_mfma_f32_16x16x32_bf16 v[12:15], v[170:173], v[228:231], v[12:15]
	v_mfma_f32_16x16x32_bf16 v[8:11], v[178:181], v[228:231], v[8:11]
	s_setprio 0
	s_setprio 1
	v_mfma_f32_16x16x32_bf16 v[52:55], v[182:185], v[198:201], v[52:55]
	v_mfma_f32_16x16x32_bf16 v[48:51], v[190:193], v[198:201], v[48:51]
	v_mfma_f32_16x16x32_bf16 v[36:39], v[182:185], v[206:209], v[36:39]
	v_mfma_f32_16x16x32_bf16 v[32:35], v[190:193], v[206:209], v[32:35]
	v_mfma_f32_16x16x32_bf16 v[20:23], v[182:185], v[214:217], v[20:23]
	v_mfma_f32_16x16x32_bf16 v[16:19], v[190:193], v[214:217], v[16:19]
	v_mfma_f32_16x16x32_bf16 v[4:7], v[182:185], v[224:227], v[4:7]
	v_mfma_f32_16x16x32_bf16 v[0:3], v[190:193], v[224:227], v[0:3]
	v_mfma_f32_16x16x32_bf16 v[52:55], v[186:189], v[202:205], v[52:55]
	v_mfma_f32_16x16x32_bf16 v[48:51], v[194:197], v[202:205], v[48:51]
	v_mfma_f32_16x16x32_bf16 v[36:39], v[186:189], v[210:213], v[36:39]
	v_mfma_f32_16x16x32_bf16 v[32:35], v[194:197], v[210:213], v[32:35]
	v_mfma_f32_16x16x32_bf16 v[20:23], v[186:189], v[218:221], v[20:23]
	v_mfma_f32_16x16x32_bf16 v[16:19], v[194:197], v[218:221], v[16:19]
	v_mfma_f32_16x16x32_bf16 v[4:7], v[186:189], v[228:231], v[4:7]
	v_mfma_f32_16x16x32_bf16 v[0:3], v[194:197], v[228:231], v[0:3]
	s_setprio 0
	s_barrier
; #define PG8_STAGE(bufoff, gbase, voff) do { _Pragma("unroll") for (int _i = 0; _i < 2; ++_i) \
;         __builtin_amdgcn_global_load_lds((const unsigned*)((const char*)(gbase) + (voff)[_i]), (PG8_LAS unsigned*)(lds + (bufoff) + ldsw + _i * 8192), 16, 0, 0); } while (0)
; #define PG8_LDA(dst, b, h) do { _Pragma("unroll") for (int m = 0; m < 4; ++m) _Pragma("unroll") for (int k = 0; k < 2; ++k) dst[m][k] = *(const PG8_LAS bf16x8*)(lds + PG8_SA(b, h) + aoff + m * 2048 + k * 1024); } while (0)
; #define PG8_LDB(dst, b, h) do { _Pragma("unroll") for (int n = 0; n < 2; ++n) _Pragma("unroll") for (int k = 0; k < 2; ++k) dst[n][k] = *(const PG8_LAS bf16x8*)(lds + PG8_SB(b, h) + boff + n * 2048 + k * 1024); } while (0)
; #define PG8_MMA(ai, bj, At, Bt) do { __builtin_amdgcn_s_setprio(1); _Pragma("unroll") for (int m = 0; m < 4; ++m) _Pragma("unroll") for (int n = 0; n < 2; ++n) _Pragma("unroll") for (int k = 0; k < 2; ++k) \
;         acc[ai][bj][m][n] = __builtin_amdgcn_mfma_f32_16x16x32_bf16(Bt[n][k], At[m][k], acc[ai][bj][m][n], 0, 0, 0); __builtin_amdgcn_s_setprio(0); } while (0)
; #define PG8_WAIT_V(n) asm volatile("s_waitcnt vmcnt(" #n ")" ::: "memory")
; #define PG8_WAIT_L(n) asm volatile("s_waitcnt lgkmcnt(" #n ")" ::: "memory")
; #define PG8_BAR __builtin_amdgcn_s_barrier()
; #define PG8_SCHED __builtin_amdgcn_sched_barrier(0)
; template <class Epi, class Sched, bool ALIGN_EPI = false, bool SP2 = false>
; __device__ __forceinline__ void gemm_phase(PG8_LAS unsigned char* lds, const Gemm g, const Sched& S, const Epi& E) {
;     ...
;             PG8_LDB(B0, 1, 0); PG8_LDB(B1, 1, 1); PG8_SCHED; PG8_LDA(At, 1, 0); PG8_STAGE(PG8_SA(0, 1), a2 + hstep, voffA);
;             PG8_WAIT_V(8); PG8_WAIT_L(0); PG8_BAR; PG8_MMA(0, 0, At, B0); PG8_MMA(0, 1, At, B1); PG8_BAR; PG8_SCHED;
;             PG8_LDA(At, 1, 1); PG8_STAGE(PG8_SB(1, 0), b3, voffB); PG8_STAGE(PG8_SB(1, 1), b3 + hstep, voffB); PG8_STAGE(PG8_SA(1, 0), a3, voffA);
;             PG8_WAIT_V(8); PG8_WAIT_L(0); PG8_BAR; PG8_MMA(1, 0, At, B0); PG8_MMA(1, 1, At, B1); PG8_BAR; PG8_SCHED;
	ds_read_b128 v[166:169], v157
	ds_read_b128 v[170:173], v158
	ds_read_b128 v[174:177], v159
	ds_read_b128 v[178:181], v160
	ds_read_b128 v[182:185], v161
	ds_read_b128 v[186:189], v162
	ds_read_b128 v[190:193], v163
	ds_read_b128 v[194:197], v164
	s_add_u32 s6, s66, 0x40000
	s_addc_u32 s7, s67, 0
	s_mov_b32 m0, s69
	ds_read_b128 v[198:201], v147 offset:32768
	ds_read_b128 v[202:205], v147 offset:33792
	ds_read_b128 v[206:209], v147 offset:34816
	ds_read_b128 v[210:213], v147 offset:35840
	ds_read_b128 v[214:217], v147 offset:36864
	ds_read_b128 v[218:221], v147 offset:37888
	ds_read_b128 v[224:227], v147 offset:38912
	ds_read_b128 v[228:231], v147 offset:39936
	global_load_lds_dwordx4 v134, s[6:7]
	v_lshl_add_u64 v[238:239], s[6:7], 0, v[130:131]
	s_mov_b32 m0, s70
	s_nop 0
	global_load_lds_dwordx4 v[238:239], off
	s_waitcnt vmcnt(8)
	s_waitcnt lgkmcnt(0)
	s_barrier
	s_setprio 1
	s_waitcnt lgkmcnt(0)
	v_mfma_f32_16x16x32_bf16 v[124:127], v[166:169], v[198:201], v[124:127]
	v_mfma_f32_16x16x32_bf16 v[120:123], v[174:177], v[198:201], v[120:123]
	v_mfma_f32_16x16x32_bf16 v[108:111], v[166:169], v[206:209], v[108:111]
	v_mfma_f32_16x16x32_bf16 v[104:107], v[174:177], v[206:209], v[104:107]
	v_mfma_f32_16x16x32_bf16 v[92:95], v[166:169], v[214:217], v[92:95]
	v_mfma_f32_16x16x32_bf16 v[88:91], v[174:177], v[214:217], v[88:91]
	v_mfma_f32_16x16x32_bf16 v[76:79], v[166:169], v[224:227], v[76:79]
	v_mfma_f32_16x16x32_bf16 v[72:75], v[174:177], v[224:227], v[72:75]
	v_mfma_f32_16x16x32_bf16 v[124:127], v[170:173], v[202:205], v[124:127]
	v_mfma_f32_16x16x32_bf16 v[120:123], v[178:181], v[202:205], v[120:123]
	v_mfma_f32_16x16x32_bf16 v[108:111], v[170:173], v[210:213], v[108:111]
	v_mfma_f32_16x16x32_bf16 v[104:107], v[178:181], v[210:213], v[104:107]
	v_mfma_f32_16x16x32_bf16 v[92:95], v[170:173], v[218:221], v[92:95]
	v_mfma_f32_16x16x32_bf16 v[88:91], v[178:181], v[218:221], v[88:91]
	v_mfma_f32_16x16x32_bf16 v[76:79], v[170:173], v[228:231], v[76:79]
	v_mfma_f32_16x16x32_bf16 v[72:75], v[178:181], v[228:231], v[72:75]
	s_setprio 0
	s_setprio 1
	v_mfma_f32_16x16x32_bf16 v[116:119], v[182:185], v[198:201], v[116:119]
	v_mfma_f32_16x16x32_bf16 v[112:115], v[190:193], v[198:201], v[112:115]
	v_mfma_f32_16x16x32_bf16 v[100:103], v[182:185], v[206:209], v[100:103]
	v_mfma_f32_16x16x32_bf16 v[96:99], v[190:193], v[206:209], v[96:99]
	v_mfma_f32_16x16x32_bf16 v[84:87], v[182:185], v[214:217], v[84:87]
	v_mfma_f32_16x16x32_bf16 v[80:83], v[190:193], v[214:217], v[80:83]
	v_mfma_f32_16x16x32_bf16 v[68:71], v[182:185], v[224:227], v[68:71]
	v_mfma_f32_16x16x32_bf16 v[64:67], v[190:193], v[224:227], v[64:67]
	v_mfma_f32_16x16x32_bf16 v[116:119], v[186:189], v[202:205], v[116:119]
	v_mfma_f32_16x16x32_bf16 v[112:115], v[194:197], v[202:205], v[112:115]
	v_mfma_f32_16x16x32_bf16 v[100:103], v[186:189], v[210:213], v[100:103]
	v_mfma_f32_16x16x32_bf16 v[96:99], v[194:197], v[210:213], v[96:99]
	v_mfma_f32_16x16x32_bf16 v[84:87], v[186:189], v[218:221], v[84:87]
	v_mfma_f32_16x16x32_bf16 v[80:83], v[194:197], v[218:221], v[80:83]
	v_mfma_f32_16x16x32_bf16 v[68:71], v[186:189], v[228:231], v[68:71]
	v_mfma_f32_16x16x32_bf16 v[64:67], v[194:197], v[228:231], v[64:67]
	s_setprio 0
	s_barrier
	s_mov_b32 m0, s72
	v_lshl_add_u64 v[144:145], v[144:145], 0, s[36:37]
	s_add_u32 s6, s64, 0x40080
	ds_read_b128 v[198:201], v147 offset:49152
	ds_read_b128 v[202:205], v147 offset:50176
	ds_read_b128 v[206:209], v147 offset:51200
	ds_read_b128 v[210:213], v147 offset:52224
	ds_read_b128 v[214:217], v147 offset:53248
	ds_read_b128 v[218:221], v147 offset:54272
	ds_read_b128 v[224:227], v147 offset:55296
	ds_read_b128 v[228:231], v147 offset:56320
	global_load_lds_dwordx4 v[144:145], off
	v_lshl_add_u64 v[144:145], v[232:233], 0, s[36:37]
	s_mov_b32 m0, s73
	s_addc_u32 s7, s65, 0
	global_load_lds_dwordx4 v[144:145], off
	s_mov_b32 m0, s76
	s_nop 0
	global_load_lds_dwordx4 v132, s[6:7]
	s_mov_b32 m0, s77
	s_nop 0
	global_load_lds_dwordx4 v128, s[6:7]
	v_lshl_add_u64 v[144:145], v[234:235], 0, s[36:37]
	s_mov_b32 m0, s74
	s_nop 0
	global_load_lds_dwordx4 v[144:145], off
	v_lshl_add_u64 v[144:145], v[236:237], 0, s[36:37]
	s_mov_b32 m0, s75
	s_nop 0
	global_load_lds_dwordx4 v[144:145], off
	s_waitcnt vmcnt(8)
	s_waitcnt lgkmcnt(0)
	s_barrier
	s_setprio 1
	s_waitcnt lgkmcnt(0)
	v_mfma_f32_16x16x32_bf16 v[60:63], v[166:169], v[198:201], v[60:63]
	v_mfma_f32_16x16x32_bf16 v[56:59], v[174:177], v[198:201], v[56:59]
	v_mfma_f32_16x16x32_bf16 v[44:47], v[166:169], v[206:209], v[44:47]
	v_mfma_f32_16x16x32_bf16 v[40:43], v[174:177], v[206:209], v[40:43]
	v_mfma_f32_16x16x32_bf16 v[28:31], v[166:169], v[214:217], v[28:31]
	v_mfma_f32_16x16x32_bf16 v[24:27], v[174:177], v[214:217], v[24:27]
	v_mfma_f32_16x16x32_bf16 v[12:15], v[166:169], v[224:227], v[12:15]
	v_mfma_f32_16x16x32_bf16 v[8:11], v[174:177], v[224:227], v[8:11]
	v_mfma_f32_16x16x32_bf16 v[60:63], v[170:173], v[202:205], v[60:63]
	v_mfma_f32_16x16x32_bf16 v[56:59], v[178:181], v[202:205], v[56:59]
	v_mfma_f32_16x16x32_bf16 v[44:47], v[170:173], v[210:213], v[44:47]
	v_mfma_f32_16x16x32_bf16 v[40:43], v[178:181], v[210:213], v[40:43]
	v_mfma_f32_16x16x32_bf16 v[28:31], v[170:173], v[218:221], v[28:31]
	v_mfma_f32_16x16x32_bf16 v[24:27], v[178:181], v[218:221], v[24:27]
	v_mfma_f32_16x16x32_bf16 v[12:15], v[170:173], v[228:231], v[12:15]
	v_mfma_f32_16x16x32_bf16 v[8:11], v[178:181], v[228:231], v[8:11]
	s_setprio 0
	s_setprio 1
	v_mfma_f32_16x16x32_bf16 v[52:55], v[182:185], v[198:201], v[52:55]
	v_mfma_f32_16x16x32_bf16 v[48:51], v[190:193], v[198:201], v[48:51]
	v_mfma_f32_16x16x32_bf16 v[36:39], v[182:185], v[206:209], v[36:39]
	v_mfma_f32_16x16x32_bf16 v[32:35], v[190:193], v[206:209], v[32:35]
	v_mfma_f32_16x16x32_bf16 v[20:23], v[182:185], v[214:217], v[20:23]
	v_mfma_f32_16x16x32_bf16 v[16:19], v[190:193], v[214:217], v[16:19]
	v_mfma_f32_16x16x32_bf16 v[4:7], v[182:185], v[224:227], v[4:7]
	v_mfma_f32_16x16x32_bf16 v[0:3], v[190:193], v[224:227], v[0:3]
	v_mfma_f32_16x16x32_bf16 v[52:55], v[186:189], v[202:205], v[52:55]
	v_mfma_f32_16x16x32_bf16 v[48:51], v[194:197], v[202:205], v[48:51]
	v_mfma_f32_16x16x32_bf16 v[36:39], v[186:189], v[210:213], v[36:39]
	v_mfma_f32_16x16x32_bf16 v[32:35], v[194:197], v[210:213], v[32:35]
	v_mfma_f32_16x16x32_bf16 v[20:23], v[186:189], v[218:221], v[20:23]
	v_mfma_f32_16x16x32_bf16 v[16:19], v[194:197], v[218:221], v[16:19]
	v_mfma_f32_16x16x32_bf16 v[4:7], v[186:189], v[228:231], v[4:7]
	v_mfma_f32_16x16x32_bf16 v[0:3], v[194:197], v[228:231], v[0:3]
	s_setprio 0
	s_barrier
	s_add_i32 s86, s86, 2
	s_add_u32 s62, s62, 0x100
	s_addc_u32 s63, s63, 0
	s_add_u32 s84, s84, 0x100
	s_addc_u32 s85, s85, 0
	s_cmp_gt_u32 s86, 13
	s_cbranch_scc0 .LBB0_793
	s_and_b64 vcc, exec, s[40:41]
	s_cbranch_vccz .LBB0_796
	s_barrier

; #define PG8_STAGE(bufoff, gbase, voff) do { _Pragma("unroll") for (int _i = 0; _i < 2; ++_i) \
;         __builtin_amdgcn_global_load_lds((const unsigned*)((const char*)(gbase) + (voff)[_i]), (PG8_LAS unsigned*)(lds + (bufoff) + ldsw + _i * 8192), 16, 0, 0); } while (0)
; #define PG8_LDA(dst, b, h) do { _Pragma("unroll") for (int m = 0; m < 4; ++m) _Pragma("unroll") for (int k = 0; k < 2; ++k) dst[m][k] = *(const PG8_LAS bf16x8*)(lds + PG8_SA(b, h) + aoff + m * 2048 + k * 1024); } while (0)
; #define PG8_LDB(dst, b, h) do { _Pragma("unroll") for (int n = 0; n < 2; ++n) _Pragma("unroll") for (int k = 0; k < 2; ++k) dst[n][k] = *(const PG8_LAS bf16x8*)(lds + PG8_SB(b, h) + boff + n * 2048 + k * 1024); } while (0)
; #define PG8_MMA(ai, bj, At, Bt) do { __builtin_amdgcn_s_setprio(1); _Pragma("unroll") for (int m = 0; m < 4; ++m) _Pragma("unroll") for (int n = 0; n < 2; ++n) _Pragma("unroll") for (int k = 0; k < 2; ++k) \
;         acc[ai][bj][m][n] = __builtin_amdgcn_mfma_f32_16x16x32_bf16(Bt[n][k], At[m][k], acc[ai][bj][m][n], 0, 0, 0); __builtin_amdgcn_s_setprio(0); } while (0)
; #define PG8_WAIT_V(n) asm volatile("s_waitcnt vmcnt(" #n ")" ::: "memory")
; #define PG8_WAIT_L(n) asm volatile("s_waitcnt lgkmcnt(" #n ")" ::: "memory")
; template <class Epi, class Sched, bool ALIGN_EPI = false, bool SP2 = false>
; __device__ __forceinline__ void gemm_phase(PG8_LAS unsigned char* lds, const Gemm g, const Sched& S, const Epi& E) {
;     ...
;             const bool last = (t == nt - 2);
;             const char* a1 = cA + (size_t)(t + 1) * kstep;
;             const char* a2 = last ? nA : cA + (size_t)(t + 2) * kstep; const char* b2 = last ? nB : cB + (size_t)(t + 2) * kstep;
;             const char* a3 = a2 + kstep; const char* b3 = b2 + kstep;
;             if (last && has_next) S.a_ready(nxt);
;             if constexpr (SP2) {
;             PG8_LDB(B0, 0, 0); PG8_LDB(B1, 0, 1); PG8_SCHED; PG8_LDA(At, 0, 0); PG8_STAGE(PG8_SA(1, 1), a1 + hstep, voffA);
;             PG8_WAIT_V(8); PG8_WAIT_L(0); PG8_BAR; PG8_MMA(0, 0, At, B0); PG8_MMA(0, 1, At, B1); PG8_BAR; PG8_SCHED;
;             PG8_LDA(At, 0, 1); PG8_STAGE(PG8_SB(0, 0), b2, voffB); PG8_STAGE(PG8_SB(0, 1), b2 + hstep, voffB); PG8_STAGE(PG8_SA(0, 0), a2, voffA);
;             PG8_WAIT_V(8); PG8_WAIT_L(0); PG8_BAR; PG8_MMA(1, 0, At, B0); PG8_MMA(1, 1, At, B1); PG8_BAR; PG8_SCHED;
.LBB0_873:
	ds_read_b128 v[142:145], v174
	ds_read_b128 v[146:149], v175
	ds_read_b128 v[150:153], v176
	ds_read_b128 v[154:157], v177
	ds_read_b128 v[158:161], v178
	ds_read_b128 v[162:165], v179
	ds_read_b128 v[166:169], v180
	ds_read_b128 v[190:193], v181
	s_add_u32 s60, s58, 0x100
	s_addc_u32 s61, s59, 0
	s_cmp_eq_u32 s89, 40
	s_cselect_b32 s65, s9, s61
	s_cselect_b32 s64, s8, s60
	s_cselect_b32 s63, s55, s88
	s_cselect_b32 s62, s54, s57
	s_mov_b32 m0, s78
	v_lshl_add_u64 v[170:171], s[58:59], 0, v[134:135]
	ds_read_b128 v[194:197], v172
	ds_read_b128 v[198:201], v172 offset:1024
	ds_read_b128 v[202:205], v172 offset:2048
	ds_read_b128 v[206:209], v172 offset:3072
	ds_read_b128 v[210:213], v172 offset:4096
	ds_read_b128 v[214:217], v172 offset:5120
	ds_read_b128 v[218:221], v172 offset:6144
	ds_read_b128 v[224:227], v172 offset:7168
	global_load_lds_dwordx4 v[170:171], off
	v_lshl_add_u64 v[170:171], s[58:59], 0, v[136:137]
	s_mov_b32 m0, s79
	s_nop 0
	global_load_lds_dwordx4 v[170:171], off
	s_waitcnt vmcnt(8)
	s_waitcnt lgkmcnt(0)
	s_barrier
	s_setprio 1
	s_waitcnt lgkmcnt(0)
	v_mfma_f32_16x16x32_bf16 v[124:127], v[142:145], v[194:197], v[124:127]
	v_mfma_f32_16x16x32_bf16 v[108:111], v[150:153], v[194:197], v[108:111]
	v_mfma_f32_16x16x32_bf16 v[120:123], v[142:145], v[202:205], v[120:123]
	v_mfma_f32_16x16x32_bf16 v[96:99], v[150:153], v[202:205], v[96:99]
	v_mfma_f32_16x16x32_bf16 v[116:119], v[142:145], v[210:213], v[116:119]
	v_mfma_f32_16x16x32_bf16 v[88:91], v[150:153], v[210:213], v[88:91]
	v_mfma_f32_16x16x32_bf16 v[112:115], v[142:145], v[218:221], v[112:115]
	v_mfma_f32_16x16x32_bf16 v[84:87], v[150:153], v[218:221], v[84:87]
	v_mfma_f32_16x16x32_bf16 v[124:127], v[146:149], v[198:201], v[124:127]
	v_mfma_f32_16x16x32_bf16 v[108:111], v[154:157], v[198:201], v[108:111]
	v_mfma_f32_16x16x32_bf16 v[120:123], v[146:149], v[206:209], v[120:123]
	v_mfma_f32_16x16x32_bf16 v[96:99], v[154:157], v[206:209], v[96:99]
	v_mfma_f32_16x16x32_bf16 v[116:119], v[146:149], v[214:217], v[116:119]
	v_mfma_f32_16x16x32_bf16 v[88:91], v[154:157], v[214:217], v[88:91]
	v_mfma_f32_16x16x32_bf16 v[112:115], v[146:149], v[224:227], v[112:115]
	v_mfma_f32_16x16x32_bf16 v[84:87], v[154:157], v[224:227], v[84:87]
	s_setprio 0
	s_setprio 1
	v_mfma_f32_16x16x32_bf16 v[68:71], v[158:161], v[194:197], v[68:71]
	v_mfma_f32_16x16x32_bf16 v[40:43], v[166:169], v[194:197], v[40:43]
	v_mfma_f32_16x16x32_bf16 v[60:63], v[158:161], v[202:205], v[60:63]
	v_mfma_f32_16x16x32_bf16 v[32:35], v[166:169], v[202:205], v[32:35]
	v_mfma_f32_16x16x32_bf16 v[52:55], v[158:161], v[210:213], v[52:55]
	v_mfma_f32_16x16x32_bf16 v[24:27], v[166:169], v[210:213], v[24:27]
	v_mfma_f32_16x16x32_bf16 v[48:51], v[158:161], v[218:221], v[48:51]
	v_mfma_f32_16x16x32_bf16 v[16:19], v[166:169], v[218:221], v[16:19]
	v_mfma_f32_16x16x32_bf16 v[68:71], v[162:165], v[198:201], v[68:71]
	v_mfma_f32_16x16x32_bf16 v[40:43], v[190:193], v[198:201], v[40:43]
	v_mfma_f32_16x16x32_bf16 v[60:63], v[162:165], v[206:209], v[60:63]
	v_mfma_f32_16x16x32_bf16 v[32:35], v[190:193], v[206:209], v[32:35]
	v_mfma_f32_16x16x32_bf16 v[52:55], v[162:165], v[214:217], v[52:55]
	v_mfma_f32_16x16x32_bf16 v[24:27], v[190:193], v[214:217], v[24:27]
	v_mfma_f32_16x16x32_bf16 v[48:51], v[162:165], v[224:227], v[48:51]
	v_mfma_f32_16x16x32_bf16 v[16:19], v[190:193], v[224:227], v[16:19]
	s_setprio 0
	s_barrier
	s_mov_b32 m0, s12
	v_lshl_add_u64 v[170:171], s[62:63], 0, v[128:129]
	s_add_u32 s58, s62, 0xb0000
	ds_read_b128 v[194:197], v172 offset:16384
	ds_read_b128 v[198:201], v172 offset:17408
	ds_read_b128 v[202:205], v172 offset:18432
	ds_read_b128 v[206:209], v172 offset:19456
	ds_read_b128 v[210:213], v172 offset:20480
	ds_read_b128 v[214:217], v172 offset:21504
	ds_read_b128 v[218:221], v172 offset:22528
	ds_read_b128 v[224:227], v172 offset:23552
	global_load_lds_dwordx4 v[170:171], off
	v_lshl_add_u64 v[228:229], s[62:63], 0, v[130:131]
	s_mov_b32 m0, s13
	s_addc_u32 s59, s63, 0
	global_load_lds_dwordx4 v[228:229], off
	s_mov_b32 m0, s14
	v_lshl_add_u64 v[232:233], s[64:65], 0, v[130:131]
	global_load_lds_dwordx4 v128, s[58:59]
	s_mov_b32 m0, s15
	s_nop 0
	global_load_lds_dwordx4 v130, s[58:59]
	v_lshl_add_u64 v[230:231], s[64:65], 0, v[128:129]
	s_mov_b32 m0, s5
	s_nop 0
	global_load_lds_dwordx4 v[230:231], off
	s_mov_b32 m0, s39
	s_nop 0
	global_load_lds_dwordx4 v[232:233], off
	s_waitcnt vmcnt(8)
	s_waitcnt lgkmcnt(0)
	s_barrier
	s_setprio 1
	s_waitcnt lgkmcnt(0)
	v_mfma_f32_16x16x32_bf16 v[104:107], v[142:145], v[194:197], v[104:107]
	v_mfma_f32_16x16x32_bf16 v[76:79], v[150:153], v[194:197], v[76:79]
	v_mfma_f32_16x16x32_bf16 v[100:103], v[142:145], v[202:205], v[100:103]
	v_mfma_f32_16x16x32_bf16 v[72:75], v[150:153], v[202:205], v[72:75]
	v_mfma_f32_16x16x32_bf16 v[92:95], v[142:145], v[210:213], v[92:95]
	v_mfma_f32_16x16x32_bf16 v[64:67], v[150:153], v[210:213], v[64:67]
	v_mfma_f32_16x16x32_bf16 v[80:83], v[142:145], v[218:221], v[80:83]
	v_mfma_f32_16x16x32_bf16 v[56:59], v[150:153], v[218:221], v[56:59]
	v_mfma_f32_16x16x32_bf16 v[104:107], v[146:149], v[198:201], v[104:107]
	v_mfma_f32_16x16x32_bf16 v[76:79], v[154:157], v[198:201], v[76:79]
	v_mfma_f32_16x16x32_bf16 v[100:103], v[146:149], v[206:209], v[100:103]
	v_mfma_f32_16x16x32_bf16 v[72:75], v[154:157], v[206:209], v[72:75]
	v_mfma_f32_16x16x32_bf16 v[92:95], v[146:149], v[214:217], v[92:95]
	v_mfma_f32_16x16x32_bf16 v[64:67], v[154:157], v[214:217], v[64:67]
	v_mfma_f32_16x16x32_bf16 v[80:83], v[146:149], v[224:227], v[80:83]
	v_mfma_f32_16x16x32_bf16 v[56:59], v[154:157], v[224:227], v[56:59]
	s_setprio 0
	s_setprio 1
	v_mfma_f32_16x16x32_bf16 v[44:47], v[158:161], v[194:197], v[44:47]
	v_mfma_f32_16x16x32_bf16 v[12:15], v[166:169], v[194:197], v[12:15]
	v_mfma_f32_16x16x32_bf16 v[36:39], v[158:161], v[202:205], v[36:39]
	v_mfma_f32_16x16x32_bf16 v[8:11], v[166:169], v[202:205], v[8:11]
	v_mfma_f32_16x16x32_bf16 v[28:31], v[158:161], v[210:213], v[28:31]
	v_mfma_f32_16x16x32_bf16 v[4:7], v[166:169], v[210:213], v[4:7]
	v_mfma_f32_16x16x32_bf16 v[20:23], v[158:161], v[218:221], v[20:23]
	v_mfma_f32_16x16x32_bf16 v[0:3], v[166:169], v[218:221], v[0:3]
	v_mfma_f32_16x16x32_bf16 v[44:47], v[162:165], v[198:201], v[44:47]
	v_mfma_f32_16x16x32_bf16 v[12:15], v[190:193], v[198:201], v[12:15]
	v_mfma_f32_16x16x32_bf16 v[36:39], v[162:165], v[206:209], v[36:39]
	v_mfma_f32_16x16x32_bf16 v[8:11], v[190:193], v[206:209], v[8:11]
	v_mfma_f32_16x16x32_bf16 v[28:31], v[162:165], v[214:217], v[28:31]
	v_mfma_f32_16x16x32_bf16 v[4:7], v[190:193], v[214:217], v[4:7]
	v_mfma_f32_16x16x32_bf16 v[20:23], v[162:165], v[224:227], v[20:23]
	v_mfma_f32_16x16x32_bf16 v[0:3], v[190:193], v[224:227], v[0:3]
	s_setprio 0
	s_barrier
; #define PG8_STAGE(bufoff, gbase, voff) do { _Pragma("unroll") for (int _i = 0; _i < 2; ++_i) \
;         __builtin_amdgcn_global_load_lds((const unsigned*)((const char*)(gbase) + (voff)[_i]), (PG8_LAS unsigned*)(lds + (bufoff) + ldsw + _i * 8192), 16, 0, 0); } while (0)
; #define PG8_LDA(dst, b, h) do { _Pragma("unroll") for (int m = 0; m < 4; ++m) _Pragma("unroll") for (int k = 0; k < 2; ++k) dst[m][k] = *(const PG8_LAS bf16x8*)(lds + PG8_SA(b, h) + aoff + m * 2048 + k * 1024); } while (0)
; #define PG8_LDB(dst, b, h) do { _Pragma("unroll") for (int n = 0; n < 2; ++n) _Pragma("unroll") for (int k = 0; k < 2; ++k) dst[n][k] = *(const PG8_LAS bf16x8*)(lds + PG8_SB(b, h) + boff + n * 2048 + k * 1024); } while (0)
; #define PG8_MMA(ai, bj, At, Bt) do { __builtin_amdgcn_s_setprio(1); _Pragma("unroll") for (int m = 0; m < 4; ++m) _Pragma("unroll") for (int n = 0; n < 2; ++n) _Pragma("unroll") for (int k = 0; k < 2; ++k) \
;         acc[ai][bj][m][n] = __builtin_amdgcn_mfma_f32_16x16x32_bf16(Bt[n][k], At[m][k], acc[ai][bj][m][n], 0, 0, 0); __builtin_amdgcn_s_setprio(0); } while (0)
; #define PG8_WAIT_V(n) asm volatile("s_waitcnt vmcnt(" #n ")" ::: "memory")
; #define PG8_WAIT_L(n) asm volatile("s_waitcnt lgkmcnt(" #n ")" ::: "memory")
; #define PG8_BAR __builtin_amdgcn_s_barrier()
; #define PG8_SCHED __builtin_amdgcn_sched_barrier(0)
; template <class Epi, class Sched, bool ALIGN_EPI = false, bool SP2 = false>
; __device__ __forceinline__ void gemm_phase(PG8_LAS unsigned char* lds, const Gemm g, const Sched& S, const Epi& E) {
;     ...
;             PG8_LDB(B0, 1, 0); PG8_LDB(B1, 1, 1); PG8_SCHED; PG8_LDA(At, 1, 0); PG8_STAGE(PG8_SA(0, 1), a2 + hstep, voffA);
;             PG8_WAIT_V(8); PG8_WAIT_L(0); PG8_BAR; PG8_MMA(0, 0, At, B0); PG8_MMA(0, 1, At, B1); PG8_BAR; PG8_SCHED;
;             PG8_LDA(At, 1, 1); PG8_STAGE(PG8_SB(1, 0), b3, voffB); PG8_STAGE(PG8_SB(1, 1), b3 + hstep, voffB); PG8_STAGE(PG8_SA(1, 0), a3, voffA);
;             PG8_WAIT_V(8); PG8_WAIT_L(0); PG8_BAR; PG8_MMA(1, 0, At, B0); PG8_MMA(1, 1, At, B1); PG8_BAR; PG8_SCHED;
	ds_read_b128 v[142:145], v182
	ds_read_b128 v[146:149], v183
	ds_read_b128 v[150:153], v184
	ds_read_b128 v[154:157], v185
	ds_read_b128 v[158:161], v186
	ds_read_b128 v[162:165], v187
	ds_read_b128 v[166:169], v188
	ds_read_b128 v[190:193], v189
	s_add_u32 s58, s64, 0xb0000
	s_addc_u32 s59, s65, 0
	s_mov_b32 m0, s43
	ds_read_b128 v[194:197], v172 offset:32768
	ds_read_b128 v[198:201], v172 offset:33792
	ds_read_b128 v[202:205], v172 offset:34816
	ds_read_b128 v[206:209], v172 offset:35840
	ds_read_b128 v[210:213], v172 offset:36864
	ds_read_b128 v[214:217], v172 offset:37888
	ds_read_b128 v[218:221], v172 offset:38912
	ds_read_b128 v[224:227], v172 offset:39936
	global_load_lds_dwordx4 v128, s[58:59]
	v_lshl_add_u64 v[234:235], s[58:59], 0, v[130:131]
	s_mov_b32 m0, s66
	s_nop 0
	global_load_lds_dwordx4 v[234:235], off
	s_waitcnt vmcnt(8)
	s_waitcnt lgkmcnt(0)
	s_barrier
	s_setprio 1
	s_waitcnt lgkmcnt(0)
	v_mfma_f32_16x16x32_bf16 v[124:127], v[142:145], v[194:197], v[124:127]
	v_mfma_f32_16x16x32_bf16 v[108:111], v[150:153], v[194:197], v[108:111]
	v_mfma_f32_16x16x32_bf16 v[120:123], v[142:145], v[202:205], v[120:123]
	v_mfma_f32_16x16x32_bf16 v[96:99], v[150:153], v[202:205], v[96:99]
	v_mfma_f32_16x16x32_bf16 v[116:119], v[142:145], v[210:213], v[116:119]
	v_mfma_f32_16x16x32_bf16 v[88:91], v[150:153], v[210:213], v[88:91]
	v_mfma_f32_16x16x32_bf16 v[112:115], v[142:145], v[218:221], v[112:115]
	v_mfma_f32_16x16x32_bf16 v[84:87], v[150:153], v[218:221], v[84:87]
	v_mfma_f32_16x16x32_bf16 v[124:127], v[146:149], v[198:201], v[124:127]
	v_mfma_f32_16x16x32_bf16 v[108:111], v[154:157], v[198:201], v[108:111]
	v_mfma_f32_16x16x32_bf16 v[120:123], v[146:149], v[206:209], v[120:123]
	v_mfma_f32_16x16x32_bf16 v[96:99], v[154:157], v[206:209], v[96:99]
	v_mfma_f32_16x16x32_bf16 v[116:119], v[146:149], v[214:217], v[116:119]
	v_mfma_f32_16x16x32_bf16 v[88:91], v[154:157], v[214:217], v[88:91]
	v_mfma_f32_16x16x32_bf16 v[112:115], v[146:149], v[224:227], v[112:115]
	v_mfma_f32_16x16x32_bf16 v[84:87], v[154:157], v[224:227], v[84:87]
	s_setprio 0
	s_setprio 1
	v_mfma_f32_16x16x32_bf16 v[68:71], v[158:161], v[194:197], v[68:71]
	v_mfma_f32_16x16x32_bf16 v[40:43], v[166:169], v[194:197], v[40:43]
	v_mfma_f32_16x16x32_bf16 v[60:63], v[158:161], v[202:205], v[60:63]
	v_mfma_f32_16x16x32_bf16 v[32:35], v[166:169], v[202:205], v[32:35]
	v_mfma_f32_16x16x32_bf16 v[52:55], v[158:161], v[210:213], v[52:55]
	v_mfma_f32_16x16x32_bf16 v[24:27], v[166:169], v[210:213], v[24:27]
	v_mfma_f32_16x16x32_bf16 v[48:51], v[158:161], v[218:221], v[48:51]
	v_mfma_f32_16x16x32_bf16 v[16:19], v[166:169], v[218:221], v[16:19]
	v_mfma_f32_16x16x32_bf16 v[68:71], v[162:165], v[198:201], v[68:71]
	v_mfma_f32_16x16x32_bf16 v[40:43], v[190:193], v[198:201], v[40:43]
	v_mfma_f32_16x16x32_bf16 v[60:63], v[162:165], v[206:209], v[60:63]
	v_mfma_f32_16x16x32_bf16 v[32:35], v[190:193], v[206:209], v[32:35]
	v_mfma_f32_16x16x32_bf16 v[52:55], v[162:165], v[214:217], v[52:55]
	v_mfma_f32_16x16x32_bf16 v[24:27], v[190:193], v[214:217], v[24:27]
	v_mfma_f32_16x16x32_bf16 v[48:51], v[162:165], v[224:227], v[48:51]
	v_mfma_f32_16x16x32_bf16 v[16:19], v[190:193], v[224:227], v[16:19]
	s_setprio 0
	s_barrier
	s_mov_b32 m0, s70
	v_lshl_add_u64 v[170:171], v[170:171], 0, s[40:41]
	s_add_u32 s58, s62, 0xb0080
	ds_read_b128 v[194:197], v172 offset:49152
	ds_read_b128 v[198:201], v172 offset:50176
	ds_read_b128 v[202:205], v172 offset:51200
	ds_read_b128 v[206:209], v172 offset:52224
	ds_read_b128 v[210:213], v172 offset:53248
	ds_read_b128 v[214:217], v172 offset:54272
	ds_read_b128 v[218:221], v172 offset:55296
	ds_read_b128 v[224:227], v172 offset:56320
	global_load_lds_dwordx4 v[170:171], off
	v_lshl_add_u64 v[170:171], v[228:229], 0, s[40:41]
	s_mov_b32 m0, s71
	s_addc_u32 s59, s63, 0
	global_load_lds_dwordx4 v[170:171], off
	s_mov_b32 m0, s74
	s_nop 0
	global_load_lds_dwordx4 v128, s[58:59]
	s_mov_b32 m0, s75
	s_nop 0
	global_load_lds_dwordx4 v130, s[58:59]
	v_lshl_add_u64 v[170:171], v[230:231], 0, s[40:41]
	s_mov_b32 m0, s72
	s_nop 0
	global_load_lds_dwordx4 v[170:171], off
	v_lshl_add_u64 v[170:171], v[232:233], 0, s[40:41]
	s_mov_b32 m0, s73
	s_nop 0
	global_load_lds_dwordx4 v[170:171], off
	s_waitcnt vmcnt(8)
	s_waitcnt lgkmcnt(0)
	s_barrier
	s_setprio 1
	s_waitcnt lgkmcnt(0)
	v_mfma_f32_16x16x32_bf16 v[104:107], v[142:145], v[194:197], v[104:107]
	v_mfma_f32_16x16x32_bf16 v[76:79], v[150:153], v[194:197], v[76:79]
	v_mfma_f32_16x16x32_bf16 v[100:103], v[142:145], v[202:205], v[100:103]
	v_mfma_f32_16x16x32_bf16 v[72:75], v[150:153], v[202:205], v[72:75]
	v_mfma_f32_16x16x32_bf16 v[92:95], v[142:145], v[210:213], v[92:95]
	v_mfma_f32_16x16x32_bf16 v[64:67], v[150:153], v[210:213], v[64:67]
	v_mfma_f32_16x16x32_bf16 v[80:83], v[142:145], v[218:221], v[80:83]
	v_mfma_f32_16x16x32_bf16 v[56:59], v[150:153], v[218:221], v[56:59]
	v_mfma_f32_16x16x32_bf16 v[104:107], v[146:149], v[198:201], v[104:107]
	v_mfma_f32_16x16x32_bf16 v[76:79], v[154:157], v[198:201], v[76:79]
	v_mfma_f32_16x16x32_bf16 v[100:103], v[146:149], v[206:209], v[100:103]
	v_mfma_f32_16x16x32_bf16 v[72:75], v[154:157], v[206:209], v[72:75]
	v_mfma_f32_16x16x32_bf16 v[92:95], v[146:149], v[214:217], v[92:95]
	v_mfma_f32_16x16x32_bf16 v[64:67], v[154:157], v[214:217], v[64:67]
	v_mfma_f32_16x16x32_bf16 v[80:83], v[146:149], v[224:227], v[80:83]
	v_mfma_f32_16x16x32_bf16 v[56:59], v[154:157], v[224:227], v[56:59]
	s_setprio 0
	s_setprio 1
	v_mfma_f32_16x16x32_bf16 v[44:47], v[158:161], v[194:197], v[44:47]
	v_mfma_f32_16x16x32_bf16 v[12:15], v[166:169], v[194:197], v[12:15]
	v_mfma_f32_16x16x32_bf16 v[36:39], v[158:161], v[202:205], v[36:39]
	v_mfma_f32_16x16x32_bf16 v[8:11], v[166:169], v[202:205], v[8:11]
	v_mfma_f32_16x16x32_bf16 v[28:31], v[158:161], v[210:213], v[28:31]
	v_mfma_f32_16x16x32_bf16 v[4:7], v[166:169], v[210:213], v[4:7]
	v_mfma_f32_16x16x32_bf16 v[20:23], v[158:161], v[218:221], v[20:23]
	v_mfma_f32_16x16x32_bf16 v[0:3], v[166:169], v[218:221], v[0:3]
	v_mfma_f32_16x16x32_bf16 v[44:47], v[162:165], v[198:201], v[44:47]
	v_mfma_f32_16x16x32_bf16 v[12:15], v[190:193], v[198:201], v[12:15]
	v_mfma_f32_16x16x32_bf16 v[36:39], v[162:165], v[206:209], v[36:39]
	v_mfma_f32_16x16x32_bf16 v[8:11], v[190:193], v[206:209], v[8:11]
	v_mfma_f32_16x16x32_bf16 v[28:31], v[162:165], v[214:217], v[28:31]
	v_mfma_f32_16x16x32_bf16 v[4:7], v[190:193], v[214:217], v[4:7]
	v_mfma_f32_16x16x32_bf16 v[20:23], v[162:165], v[224:227], v[20:23]
	v_mfma_f32_16x16x32_bf16 v[0:3], v[190:193], v[224:227], v[0:3]
	s_setprio 0
	s_barrier
	s_add_i32 s89, s89, 2
	s_add_u32 s57, s57, 0x100
	s_addc_u32 s88, s88, 0
	s_cmp_gt_u32 s89, 41
	s_mov_b64 s[58:59], s[60:61]
	s_cbranch_scc0 .LBB0_873
	s_and_b64 vcc, exec, s[52:53]
	s_cbranch_vccz .LBB0_876
	s_barrier

; #define PG8_STAGE(bufoff, gbase, voff) do { _Pragma("unroll") for (int _i = 0; _i < 2; ++_i) \
;         __builtin_amdgcn_global_load_lds((const unsigned*)((const char*)(gbase) + (voff)[_i]), (PG8_LAS unsigned*)(lds + (bufoff) + ldsw + _i * 8192), 16, 0, 0); } while (0)
; #define PG8_LDA(dst, b, h) do { _Pragma("unroll") for (int m = 0; m < 4; ++m) _Pragma("unroll") for (int k = 0; k < 2; ++k) dst[m][k] = *(const PG8_LAS bf16x8*)(lds + PG8_SA(b, h) + aoff + m * 2048 + k * 1024); } while (0)
; #define PG8_LDB(dst, b, h) do { _Pragma("unroll") for (int n = 0; n < 2; ++n) _Pragma("unroll") for (int k = 0; k < 2; ++k) dst[n][k] = *(const PG8_LAS bf16x8*)(lds + PG8_SB(b, h) + boff + n * 2048 + k * 1024); } while (0)
; #define PG8_MMA(ai, bj, At, Bt) do { __builtin_amdgcn_s_setprio(1); _Pragma("unroll") for (int m = 0; m < 4; ++m) _Pragma("unroll") for (int n = 0; n < 2; ++n) _Pragma("unroll") for (int k = 0; k < 2; ++k) \
;         acc[ai][bj][m][n] = __builtin_amdgcn_mfma_f32_16x16x32_bf16(Bt[n][k], At[m][k], acc[ai][bj][m][n], 0, 0, 0); __builtin_amdgcn_s_setprio(0); } while (0)
; #define PG8_WAIT_V(n) asm volatile("s_waitcnt vmcnt(" #n ")" ::: "memory")
; #define PG8_WAIT_L(n) asm volatile("s_waitcnt lgkmcnt(" #n ")" ::: "memory")
; template <class Epi, class Sched, bool ALIGN_EPI = false, bool SP2 = false>
; __device__ __forceinline__ void gemm_phase(PG8_LAS unsigned char* lds, const Gemm g, const Sched& S, const Epi& E) {
;     ...
;             const bool last = (t == nt - 2);
;             const char* a1 = cA + (size_t)(t + 1) * kstep;
;             const char* a2 = last ? nA : cA + (size_t)(t + 2) * kstep; const char* b2 = last ? nB : cB + (size_t)(t + 2) * kstep;
;             const char* a3 = a2 + kstep; const char* b3 = b2 + kstep;
;             if (last && has_next) S.a_ready(nxt);
;             if constexpr (SP2) {
;             PG8_LDB(B0, 0, 0); PG8_LDB(B1, 0, 1); PG8_SCHED; PG8_LDA(At, 0, 0); PG8_STAGE(PG8_SA(1, 1), a1 + hstep, voffA);
;             PG8_WAIT_V(8); PG8_WAIT_L(0); PG8_BAR; PG8_MMA(0, 0, At, B0); PG8_MMA(0, 1, At, B1); PG8_BAR; PG8_SCHED;
;             PG8_LDA(At, 0, 1); PG8_STAGE(PG8_SB(0, 0), b2, voffB); PG8_STAGE(PG8_SB(0, 1), b2 + hstep, voffB); PG8_STAGE(PG8_SA(0, 0), a2, voffA);
;             PG8_WAIT_V(8); PG8_WAIT_L(0); PG8_BAR; PG8_MMA(1, 0, At, B0); PG8_MMA(1, 1, At, B1); PG8_BAR; PG8_SCHED;
.LBB0_896:
	ds_read_b128 v[156:159], v140
	ds_read_b128 v[160:163], v141
	ds_read_b128 v[164:167], v142
	ds_read_b128 v[168:171], v143
	ds_read_b128 v[172:175], v144
	ds_read_b128 v[176:179], v145
	ds_read_b128 v[180:183], v146
	ds_read_b128 v[184:187], v147
	s_add_i32 s86, s57, 2
	s_add_u32 s64, s62, 0x100
	s_addc_u32 s65, s63, 0
	s_cmp_eq_u32 s78, s57
	s_cselect_b32 s69, s59, s65
	s_cselect_b32 s68, s58, s64
	s_cselect_b32 s67, s61, s55
	s_cselect_b32 s66, s60, s33
	s_mov_b32 m0, s79
	v_lshl_add_u64 v[220:221], s[62:63], 0, v[134:135]
	ds_read_b128 v[188:191], v138
	ds_read_b128 v[192:195], v138 offset:1024
	ds_read_b128 v[196:199], v138 offset:2048
	ds_read_b128 v[200:203], v138 offset:3072
	ds_read_b128 v[204:207], v138 offset:4096
	ds_read_b128 v[208:211], v138 offset:5120
	ds_read_b128 v[212:215], v138 offset:6144
	ds_read_b128 v[216:219], v138 offset:7168
	global_load_lds_dwordx4 v[220:221], off
	v_lshl_add_u64 v[220:221], s[62:63], 0, v[136:137]
	s_mov_b32 m0, s80
	s_nop 0
	global_load_lds_dwordx4 v[220:221], off
	s_waitcnt vmcnt(8)
	s_waitcnt lgkmcnt(0)
	s_barrier
	s_setprio 1
	s_waitcnt lgkmcnt(0)
	v_mfma_f32_16x16x32_bf16 v[124:127], v[156:159], v[188:191], v[124:127]
	v_mfma_f32_16x16x32_bf16 v[120:123], v[164:167], v[188:191], v[120:123]
	v_mfma_f32_16x16x32_bf16 v[108:111], v[156:159], v[196:199], v[108:111]
	v_mfma_f32_16x16x32_bf16 v[104:107], v[164:167], v[196:199], v[104:107]
	v_mfma_f32_16x16x32_bf16 v[92:95], v[156:159], v[204:207], v[92:95]
	v_mfma_f32_16x16x32_bf16 v[88:91], v[164:167], v[204:207], v[88:91]
	v_mfma_f32_16x16x32_bf16 v[76:79], v[156:159], v[212:215], v[76:79]
	v_mfma_f32_16x16x32_bf16 v[72:75], v[164:167], v[212:215], v[72:75]
	v_mfma_f32_16x16x32_bf16 v[124:127], v[160:163], v[192:195], v[124:127]
	v_mfma_f32_16x16x32_bf16 v[120:123], v[168:171], v[192:195], v[120:123]
	v_mfma_f32_16x16x32_bf16 v[108:111], v[160:163], v[200:203], v[108:111]
	v_mfma_f32_16x16x32_bf16 v[104:107], v[168:171], v[200:203], v[104:107]
	v_mfma_f32_16x16x32_bf16 v[92:95], v[160:163], v[208:211], v[92:95]
	v_mfma_f32_16x16x32_bf16 v[88:91], v[168:171], v[208:211], v[88:91]
	v_mfma_f32_16x16x32_bf16 v[76:79], v[160:163], v[216:219], v[76:79]
	v_mfma_f32_16x16x32_bf16 v[72:75], v[168:171], v[216:219], v[72:75]
	s_setprio 0
	s_setprio 1
	v_mfma_f32_16x16x32_bf16 v[116:119], v[172:175], v[188:191], v[116:119]
	v_mfma_f32_16x16x32_bf16 v[112:115], v[180:183], v[188:191], v[112:115]
	v_mfma_f32_16x16x32_bf16 v[100:103], v[172:175], v[196:199], v[100:103]
	v_mfma_f32_16x16x32_bf16 v[96:99], v[180:183], v[196:199], v[96:99]
	v_mfma_f32_16x16x32_bf16 v[84:87], v[172:175], v[204:207], v[84:87]
	v_mfma_f32_16x16x32_bf16 v[80:83], v[180:183], v[204:207], v[80:83]
	v_mfma_f32_16x16x32_bf16 v[68:71], v[172:175], v[212:215], v[68:71]
	v_mfma_f32_16x16x32_bf16 v[64:67], v[180:183], v[212:215], v[64:67]
	v_mfma_f32_16x16x32_bf16 v[116:119], v[176:179], v[192:195], v[116:119]
	v_mfma_f32_16x16x32_bf16 v[112:115], v[184:187], v[192:195], v[112:115]
	v_mfma_f32_16x16x32_bf16 v[100:103], v[176:179], v[200:203], v[100:103]
	v_mfma_f32_16x16x32_bf16 v[96:99], v[184:187], v[200:203], v[96:99]
	v_mfma_f32_16x16x32_bf16 v[84:87], v[176:179], v[208:211], v[84:87]
	v_mfma_f32_16x16x32_bf16 v[80:83], v[184:187], v[208:211], v[80:83]
	v_mfma_f32_16x16x32_bf16 v[68:71], v[176:179], v[216:219], v[68:71]
	v_mfma_f32_16x16x32_bf16 v[64:67], v[184:187], v[216:219], v[64:67]
	s_setprio 0
	s_barrier
	s_mov_b32 m0, s12
	v_lshl_add_u64 v[220:221], s[66:67], 0, v[130:131]
	s_add_u32 s62, s66, 0xb0000
	ds_read_b128 v[188:191], v138 offset:16384
	ds_read_b128 v[192:195], v138 offset:17408
	ds_read_b128 v[196:199], v138 offset:18432
	ds_read_b128 v[200:203], v138 offset:19456
	ds_read_b128 v[204:207], v138 offset:20480
	ds_read_b128 v[208:211], v138 offset:21504
	ds_read_b128 v[212:215], v138 offset:22528
	ds_read_b128 v[216:219], v138 offset:23552
	global_load_lds_dwordx4 v[220:221], off
	v_lshl_add_u64 v[224:225], s[66:67], 0, v[128:129]
	s_mov_b32 m0, s13
	s_addc_u32 s63, s67, 0
	global_load_lds_dwordx4 v[224:225], off
	s_mov_b32 m0, s14
	v_lshl_add_u64 v[228:229], s[68:69], 0, v[128:129]
	global_load_lds_dwordx4 v130, s[62:63]
	s_mov_b32 m0, s15
	s_nop 0
	global_load_lds_dwordx4 v128, s[62:63]
	v_lshl_add_u64 v[226:227], s[68:69], 0, v[130:131]
	s_mov_b32 m0, s5
	s_nop 0
	global_load_lds_dwordx4 v[226:227], off
	s_mov_b32 m0, s39
	s_nop 0
	global_load_lds_dwordx4 v[228:229], off
	s_waitcnt vmcnt(8)
	s_waitcnt lgkmcnt(0)
	s_barrier
	s_setprio 1
	s_waitcnt lgkmcnt(0)
	v_mfma_f32_16x16x32_bf16 v[60:63], v[156:159], v[188:191], v[60:63]
	v_mfma_f32_16x16x32_bf16 v[56:59], v[164:167], v[188:191], v[56:59]
	v_mfma_f32_16x16x32_bf16 v[44:47], v[156:159], v[196:199], v[44:47]
	v_mfma_f32_16x16x32_bf16 v[40:43], v[164:167], v[196:199], v[40:43]
	v_mfma_f32_16x16x32_bf16 v[28:31], v[156:159], v[204:207], v[28:31]
	v_mfma_f32_16x16x32_bf16 v[24:27], v[164:167], v[204:207], v[24:27]
	v_mfma_f32_16x16x32_bf16 v[12:15], v[156:159], v[212:215], v[12:15]
	v_mfma_f32_16x16x32_bf16 v[8:11], v[164:167], v[212:215], v[8:11]
	v_mfma_f32_16x16x32_bf16 v[60:63], v[160:163], v[192:195], v[60:63]
	v_mfma_f32_16x16x32_bf16 v[56:59], v[168:171], v[192:195], v[56:59]
	v_mfma_f32_16x16x32_bf16 v[44:47], v[160:163], v[200:203], v[44:47]
	v_mfma_f32_16x16x32_bf16 v[40:43], v[168:171], v[200:203], v[40:43]
	v_mfma_f32_16x16x32_bf16 v[28:31], v[160:163], v[208:211], v[28:31]
	v_mfma_f32_16x16x32_bf16 v[24:27], v[168:171], v[208:211], v[24:27]
	v_mfma_f32_16x16x32_bf16 v[12:15], v[160:163], v[216:219], v[12:15]
	v_mfma_f32_16x16x32_bf16 v[8:11], v[168:171], v[216:219], v[8:11]
	s_setprio 0
	s_setprio 1
	v_mfma_f32_16x16x32_bf16 v[52:55], v[172:175], v[188:191], v[52:55]
	v_mfma_f32_16x16x32_bf16 v[48:51], v[180:183], v[188:191], v[48:51]
	v_mfma_f32_16x16x32_bf16 v[36:39], v[172:175], v[196:199], v[36:39]
	v_mfma_f32_16x16x32_bf16 v[32:35], v[180:183], v[196:199], v[32:35]
	v_mfma_f32_16x16x32_bf16 v[20:23], v[172:175], v[204:207], v[20:23]
	v_mfma_f32_16x16x32_bf16 v[16:19], v[180:183], v[204:207], v[16:19]
	v_mfma_f32_16x16x32_bf16 v[4:7], v[172:175], v[212:215], v[4:7]
	v_mfma_f32_16x16x32_bf16 v[0:3], v[180:183], v[212:215], v[0:3]
	v_mfma_f32_16x16x32_bf16 v[52:55], v[176:179], v[192:195], v[52:55]
	v_mfma_f32_16x16x32_bf16 v[48:51], v[184:187], v[192:195], v[48:51]
	v_mfma_f32_16x16x32_bf16 v[36:39], v[176:179], v[200:203], v[36:39]
	v_mfma_f32_16x16x32_bf16 v[32:35], v[184:187], v[200:203], v[32:35]
	v_mfma_f32_16x16x32_bf16 v[20:23], v[176:179], v[208:211], v[20:23]
	v_mfma_f32_16x16x32_bf16 v[16:19], v[184:187], v[208:211], v[16:19]
	v_mfma_f32_16x16x32_bf16 v[4:7], v[176:179], v[216:219], v[4:7]
	v_mfma_f32_16x16x32_bf16 v[0:3], v[184:187], v[216:219], v[0:3]
	s_setprio 0
	s_barrier
; #define PG8_STAGE(bufoff, gbase, voff) do { _Pragma("unroll") for (int _i = 0; _i < 2; ++_i) \
;         __builtin_amdgcn_global_load_lds((const unsigned*)((const char*)(gbase) + (voff)[_i]), (PG8_LAS unsigned*)(lds + (bufoff) + ldsw + _i * 8192), 16, 0, 0); } while (0)
; #define PG8_LDA(dst, b, h) do { _Pragma("unroll") for (int m = 0; m < 4; ++m) _Pragma("unroll") for (int k = 0; k < 2; ++k) dst[m][k] = *(const PG8_LAS bf16x8*)(lds + PG8_SA(b, h) + aoff + m * 2048 + k * 1024); } while (0)
; #define PG8_LDB(dst, b, h) do { _Pragma("unroll") for (int n = 0; n < 2; ++n) _Pragma("unroll") for (int k = 0; k < 2; ++k) dst[n][k] = *(const PG8_LAS bf16x8*)(lds + PG8_SB(b, h) + boff + n * 2048 + k * 1024); } while (0)
; #define PG8_MMA(ai, bj, At, Bt) do { __builtin_amdgcn_s_setprio(1); _Pragma("unroll") for (int m = 0; m < 4; ++m) _Pragma("unroll") for (int n = 0; n < 2; ++n) _Pragma("unroll") for (int k = 0; k < 2; ++k) \
;         acc[ai][bj][m][n] = __builtin_amdgcn_mfma_f32_16x16x32_bf16(Bt[n][k], At[m][k], acc[ai][bj][m][n], 0, 0, 0); __builtin_amdgcn_s_setprio(0); } while (0)
; #define PG8_WAIT_V(n) asm volatile("s_waitcnt vmcnt(" #n ")" ::: "memory")
; #define PG8_WAIT_L(n) asm volatile("s_waitcnt lgkmcnt(" #n ")" ::: "memory")
; #define PG8_BAR __builtin_amdgcn_s_barrier()
; #define PG8_SCHED __builtin_amdgcn_sched_barrier(0)
; template <class Epi, class Sched, bool ALIGN_EPI = false, bool SP2 = false>
; __device__ __forceinline__ void gemm_phase(PG8_LAS unsigned char* lds, const Gemm g, const Sched& S, const Epi& E) {
;     ...
;             PG8_LDB(B0, 1, 0); PG8_LDB(B1, 1, 1); PG8_SCHED; PG8_LDA(At, 1, 0); PG8_STAGE(PG8_SA(0, 1), a2 + hstep, voffA);
;             PG8_WAIT_V(8); PG8_WAIT_L(0); PG8_BAR; PG8_MMA(0, 0, At, B0); PG8_MMA(0, 1, At, B1); PG8_BAR; PG8_SCHED;
;             PG8_LDA(At, 1, 1); PG8_STAGE(PG8_SB(1, 0), b3, voffB); PG8_STAGE(PG8_SB(1, 1), b3 + hstep, voffB); PG8_STAGE(PG8_SA(1, 0), a3, voffA);
;             PG8_WAIT_V(8); PG8_WAIT_L(0); PG8_BAR; PG8_MMA(1, 0, At, B0); PG8_MMA(1, 1, At, B1); PG8_BAR; PG8_SCHED;
	ds_read_b128 v[156:159], v148
	ds_read_b128 v[160:163], v149
	ds_read_b128 v[164:167], v150
	ds_read_b128 v[168:171], v151
	ds_read_b128 v[172:175], v152
	ds_read_b128 v[176:179], v153
	ds_read_b128 v[180:183], v154
	ds_read_b128 v[184:187], v155
	s_add_u32 s62, s68, 0xb0000
	s_addc_u32 s63, s69, 0
	s_mov_b32 m0, s43
	ds_read_b128 v[188:191], v138 offset:32768
	ds_read_b128 v[192:195], v138 offset:33792
	ds_read_b128 v[196:199], v138 offset:34816
	ds_read_b128 v[200:203], v138 offset:35840
	ds_read_b128 v[204:207], v138 offset:36864
	ds_read_b128 v[208:211], v138 offset:37888
	ds_read_b128 v[212:215], v138 offset:38912
	ds_read_b128 v[216:219], v138 offset:39936
	global_load_lds_dwordx4 v130, s[62:63]
	v_lshl_add_u64 v[230:231], s[62:63], 0, v[128:129]
	s_mov_b32 m0, s70
	s_nop 0
	global_load_lds_dwordx4 v[230:231], off
	s_waitcnt vmcnt(8)
	s_waitcnt lgkmcnt(0)
	s_barrier
	s_setprio 1
	s_waitcnt lgkmcnt(0)
	v_mfma_f32_16x16x32_bf16 v[124:127], v[156:159], v[188:191], v[124:127]
	v_mfma_f32_16x16x32_bf16 v[120:123], v[164:167], v[188:191], v[120:123]
	v_mfma_f32_16x16x32_bf16 v[108:111], v[156:159], v[196:199], v[108:111]
	v_mfma_f32_16x16x32_bf16 v[104:107], v[164:167], v[196:199], v[104:107]
	v_mfma_f32_16x16x32_bf16 v[92:95], v[156:159], v[204:207], v[92:95]
	v_mfma_f32_16x16x32_bf16 v[88:91], v[164:167], v[204:207], v[88:91]
	v_mfma_f32_16x16x32_bf16 v[76:79], v[156:159], v[212:215], v[76:79]
	v_mfma_f32_16x16x32_bf16 v[72:75], v[164:167], v[212:215], v[72:75]
	v_mfma_f32_16x16x32_bf16 v[124:127], v[160:163], v[192:195], v[124:127]
	v_mfma_f32_16x16x32_bf16 v[120:123], v[168:171], v[192:195], v[120:123]
	v_mfma_f32_16x16x32_bf16 v[108:111], v[160:163], v[200:203], v[108:111]
	v_mfma_f32_16x16x32_bf16 v[104:107], v[168:171], v[200:203], v[104:107]
	v_mfma_f32_16x16x32_bf16 v[92:95], v[160:163], v[208:211], v[92:95]
	v_mfma_f32_16x16x32_bf16 v[88:91], v[168:171], v[208:211], v[88:91]
	v_mfma_f32_16x16x32_bf16 v[76:79], v[160:163], v[216:219], v[76:79]
	v_mfma_f32_16x16x32_bf16 v[72:75], v[168:171], v[216:219], v[72:75]
	s_setprio 0
	s_setprio 1
	v_mfma_f32_16x16x32_bf16 v[116:119], v[172:175], v[188:191], v[116:119]
	v_mfma_f32_16x16x32_bf16 v[112:115], v[180:183], v[188:191], v[112:115]
	v_mfma_f32_16x16x32_bf16 v[100:103], v[172:175], v[196:199], v[100:103]
	v_mfma_f32_16x16x32_bf16 v[96:99], v[180:183], v[196:199], v[96:99]
	v_mfma_f32_16x16x32_bf16 v[84:87], v[172:175], v[204:207], v[84:87]
	v_mfma_f32_16x16x32_bf16 v[80:83], v[180:183], v[204:207], v[80:83]
	v_mfma_f32_16x16x32_bf16 v[68:71], v[172:175], v[212:215], v[68:71]
	v_mfma_f32_16x16x32_bf16 v[64:67], v[180:183], v[212:215], v[64:67]
	v_mfma_f32_16x16x32_bf16 v[116:119], v[176:179], v[192:195], v[116:119]
	v_mfma_f32_16x16x32_bf16 v[112:115], v[184:187], v[192:195], v[112:115]
	v_mfma_f32_16x16x32_bf16 v[100:103], v[176:179], v[200:203], v[100:103]
	v_mfma_f32_16x16x32_bf16 v[96:99], v[184:187], v[200:203], v[96:99]
	v_mfma_f32_16x16x32_bf16 v[84:87], v[176:179], v[208:211], v[84:87]
	v_mfma_f32_16x16x32_bf16 v[80:83], v[184:187], v[208:211], v[80:83]
	v_mfma_f32_16x16x32_bf16 v[68:71], v[176:179], v[216:219], v[68:71]
	v_mfma_f32_16x16x32_bf16 v[64:67], v[184:187], v[216:219], v[64:67]
	s_setprio 0
	s_barrier
	s_mov_b32 m0, s72
	v_lshl_add_u64 v[220:221], v[220:221], 0, s[40:41]
	s_add_u32 s62, s66, 0xb0080
	ds_read_b128 v[188:191], v138 offset:49152
	ds_read_b128 v[192:195], v138 offset:50176
	ds_read_b128 v[196:199], v138 offset:51200
	ds_read_b128 v[200:203], v138 offset:52224
	ds_read_b128 v[204:207], v138 offset:53248
	ds_read_b128 v[208:211], v138 offset:54272
	ds_read_b128 v[212:215], v138 offset:55296
	ds_read_b128 v[216:219], v138 offset:56320
	global_load_lds_dwordx4 v[220:221], off
	v_lshl_add_u64 v[220:221], v[224:225], 0, s[40:41]
	s_mov_b32 m0, s73
	s_addc_u32 s63, s67, 0
	global_load_lds_dwordx4 v[220:221], off
	s_mov_b32 m0, s76
	s_nop 0
	global_load_lds_dwordx4 v130, s[62:63]
	s_mov_b32 m0, s77
	s_nop 0
	global_load_lds_dwordx4 v128, s[62:63]
	v_lshl_add_u64 v[220:221], v[226:227], 0, s[40:41]
	s_mov_b32 m0, s74
	s_nop 0
	global_load_lds_dwordx4 v[220:221], off
	v_lshl_add_u64 v[220:221], v[228:229], 0, s[40:41]
	s_mov_b32 m0, s75
	s_nop 0
	global_load_lds_dwordx4 v[220:221], off
	s_waitcnt vmcnt(8)
	s_waitcnt lgkmcnt(0)
	s_barrier
	s_setprio 1
	s_waitcnt lgkmcnt(0)
	v_mfma_f32_16x16x32_bf16 v[60:63], v[156:159], v[188:191], v[60:63]
	v_mfma_f32_16x16x32_bf16 v[56:59], v[164:167], v[188:191], v[56:59]
	v_mfma_f32_16x16x32_bf16 v[44:47], v[156:159], v[196:199], v[44:47]
	v_mfma_f32_16x16x32_bf16 v[40:43], v[164:167], v[196:199], v[40:43]
	v_mfma_f32_16x16x32_bf16 v[28:31], v[156:159], v[204:207], v[28:31]
	v_mfma_f32_16x16x32_bf16 v[24:27], v[164:167], v[204:207], v[24:27]
	v_mfma_f32_16x16x32_bf16 v[12:15], v[156:159], v[212:215], v[12:15]
	v_mfma_f32_16x16x32_bf16 v[8:11], v[164:167], v[212:215], v[8:11]
	v_mfma_f32_16x16x32_bf16 v[60:63], v[160:163], v[192:195], v[60:63]
	v_mfma_f32_16x16x32_bf16 v[56:59], v[168:171], v[192:195], v[56:59]
	v_mfma_f32_16x16x32_bf16 v[44:47], v[160:163], v[200:203], v[44:47]
	v_mfma_f32_16x16x32_bf16 v[40:43], v[168:171], v[200:203], v[40:43]
	v_mfma_f32_16x16x32_bf16 v[28:31], v[160:163], v[208:211], v[28:31]
	v_mfma_f32_16x16x32_bf16 v[24:27], v[168:171], v[208:211], v[24:27]
	v_mfma_f32_16x16x32_bf16 v[12:15], v[160:163], v[216:219], v[12:15]
	v_mfma_f32_16x16x32_bf16 v[8:11], v[168:171], v[216:219], v[8:11]
	s_setprio 0
	s_setprio 1
	v_mfma_f32_16x16x32_bf16 v[52:55], v[172:175], v[188:191], v[52:55]
	v_mfma_f32_16x16x32_bf16 v[48:51], v[180:183], v[188:191], v[48:51]
	v_mfma_f32_16x16x32_bf16 v[36:39], v[172:175], v[196:199], v[36:39]
	v_mfma_f32_16x16x32_bf16 v[32:35], v[180:183], v[196:199], v[32:35]
	v_mfma_f32_16x16x32_bf16 v[20:23], v[172:175], v[204:207], v[20:23]
	v_mfma_f32_16x16x32_bf16 v[16:19], v[180:183], v[204:207], v[16:19]
	v_mfma_f32_16x16x32_bf16 v[4:7], v[172:175], v[212:215], v[4:7]
	v_mfma_f32_16x16x32_bf16 v[0:3], v[180:183], v[212:215], v[0:3]
	v_mfma_f32_16x16x32_bf16 v[52:55], v[176:179], v[192:195], v[52:55]
	v_mfma_f32_16x16x32_bf16 v[48:51], v[184:187], v[192:195], v[48:51]
	v_mfma_f32_16x16x32_bf16 v[36:39], v[176:179], v[200:203], v[36:39]
	v_mfma_f32_16x16x32_bf16 v[32:35], v[184:187], v[200:203], v[32:35]
	v_mfma_f32_16x16x32_bf16 v[20:23], v[176:179], v[208:211], v[20:23]
	v_mfma_f32_16x16x32_bf16 v[16:19], v[184:187], v[208:211], v[16:19]
	v_mfma_f32_16x16x32_bf16 v[4:7], v[176:179], v[216:219], v[4:7]
	v_mfma_f32_16x16x32_bf16 v[0:3], v[184:187], v[216:219], v[0:3]
	s_setprio 0
	s_barrier
	s_add_u32 s33, s33, 0x100
	s_addc_u32 s55, s55, 0
	s_cmp_ge_i32 s86, s4
	s_mov_b64 s[62:63], s[64:65]
	s_mov_b32 s57, s86
	s_cbranch_scc0 .LBB0_896
	s_and_b64 vcc, exec, s[52:53]
	s_cbranch_vccz .LBB0_899

; #define PG8_STAGE(bufoff, gbase, voff) do { _Pragma("unroll") for (int _i = 0; _i < 2; ++_i) \
;         __builtin_amdgcn_global_load_lds((const unsigned*)((const char*)(gbase) + (voff)[_i]), (PG8_LAS unsigned*)(lds + (bufoff) + ldsw + _i * 8192), 16, 0, 0); } while (0)
; #define PG8_LDA(dst, b, h) do { _Pragma("unroll") for (int m = 0; m < 4; ++m) _Pragma("unroll") for (int k = 0; k < 2; ++k) dst[m][k] = *(const PG8_LAS bf16x8*)(lds + PG8_SA(b, h) + aoff + m * 2048 + k * 1024); } while (0)
; #define PG8_LDB(dst, b, h) do { _Pragma("unroll") for (int n = 0; n < 2; ++n) _Pragma("unroll") for (int k = 0; k < 2; ++k) dst[n][k] = *(const PG8_LAS bf16x8*)(lds + PG8_SB(b, h) + boff + n * 2048 + k * 1024); } while (0)
; #define PG8_MMA(ai, bj, At, Bt) do { __builtin_amdgcn_s_setprio(1); _Pragma("unroll") for (int m = 0; m < 4; ++m) _Pragma("unroll") for (int n = 0; n < 2; ++n) _Pragma("unroll") for (int k = 0; k < 2; ++k) \
;         acc[ai][bj][m][n] = __builtin_amdgcn_mfma_f32_16x16x32_bf16(Bt[n][k], At[m][k], acc[ai][bj][m][n], 0, 0, 0); __builtin_amdgcn_s_setprio(0); } while (0)
; #define PG8_WAIT_V(n) asm volatile("s_waitcnt vmcnt(" #n ")" ::: "memory")
; #define PG8_WAIT_L(n) asm volatile("s_waitcnt lgkmcnt(" #n ")" ::: "memory")
; template <class Epi, class Sched, bool ALIGN_EPI = false, bool SP2 = false>
; __device__ __forceinline__ void gemm_phase(PG8_LAS unsigned char* lds, const Gemm g, const Sched& S, const Epi& E) {
;     ...
;             const bool last = (t == nt - 2);
;             const char* a1 = cA + (size_t)(t + 1) * kstep;
;             const char* a2 = last ? nA : cA + (size_t)(t + 2) * kstep; const char* b2 = last ? nB : cB + (size_t)(t + 2) * kstep;
;             const char* a3 = a2 + kstep; const char* b3 = b2 + kstep;
;             if (last && has_next) S.a_ready(nxt);
;             if constexpr (SP2) {
;             PG8_LDB(B0, 0, 0); PG8_LDB(B1, 0, 1); PG8_SCHED; PG8_LDA(At, 0, 0); PG8_STAGE(PG8_SA(1, 1), a1 + hstep, voffA);
;             PG8_WAIT_V(8); PG8_WAIT_L(0); PG8_BAR; PG8_MMA(0, 0, At, B0); PG8_MMA(0, 1, At, B1); PG8_BAR; PG8_SCHED;
;             PG8_LDA(At, 0, 1); PG8_STAGE(PG8_SB(0, 0), b2, voffB); PG8_STAGE(PG8_SB(0, 1), b2 + hstep, voffB); PG8_STAGE(PG8_SA(0, 0), a2, voffA);
;             PG8_WAIT_V(8); PG8_WAIT_L(0); PG8_BAR; PG8_MMA(1, 0, At, B0); PG8_MMA(1, 1, At, B1); PG8_BAR; PG8_SCHED;
.LBB0_1030:
	ds_read_b128 v[128:131], v171
	ds_read_b128 v[132:135], v172
	ds_read_b128 v[188:191], v173
	ds_read_b128 v[192:195], v174
	ds_read_b128 v[196:199], v175
	ds_read_b128 v[200:203], v176
	ds_read_b128 v[204:207], v177
	ds_read_b128 v[208:211], v178
	s_add_u32 s66, s10, 0xfffc0080
	s_addc_u32 s67, s11, -1
	s_cmp_eq_u32 s83, 12
	s_cselect_b32 s69, s33, s67
	s_cselect_b32 s68, s57, s66
	s_cselect_b32 s67, s55, s82
	s_cselect_b32 s66, s80, s81
	s_mov_b32 m0, s77
	ds_read_b128 v[212:215], v159
	ds_read_b128 v[216:219], v159 offset:1024
	ds_read_b128 v[224:227], v159 offset:2048
	ds_read_b128 v[228:231], v159 offset:3072
	ds_read_b128 v[232:235], v159 offset:4096
	ds_read_b128 v[236:239], v159 offset:5120
	ds_read_b128 v[240:243], v159 offset:6144
	ds_read_b128 v[244:247], v159 offset:7168
	global_load_lds_dwordx4 v146, s[10:11]
	s_mov_b32 m0, s78
	s_nop 0
	global_load_lds_dwordx4 v148, s[10:11]
	s_waitcnt vmcnt(8)
	s_waitcnt lgkmcnt(0)
	s_barrier
	s_setprio 1
	s_waitcnt lgkmcnt(0)
	v_mfma_f32_16x16x32_bf16 v[124:127], v[128:131], v[212:215], v[124:127]
	v_mfma_f32_16x16x32_bf16 v[120:123], v[188:191], v[212:215], v[120:123]
	v_mfma_f32_16x16x32_bf16 v[108:111], v[128:131], v[224:227], v[108:111]
	v_mfma_f32_16x16x32_bf16 v[104:107], v[188:191], v[224:227], v[104:107]
	v_mfma_f32_16x16x32_bf16 v[92:95], v[128:131], v[232:235], v[92:95]
	v_mfma_f32_16x16x32_bf16 v[88:91], v[188:191], v[232:235], v[88:91]
	v_mfma_f32_16x16x32_bf16 v[76:79], v[128:131], v[240:243], v[76:79]
	v_mfma_f32_16x16x32_bf16 v[72:75], v[188:191], v[240:243], v[72:75]
	v_mfma_f32_16x16x32_bf16 v[124:127], v[132:135], v[216:219], v[124:127]
	v_mfma_f32_16x16x32_bf16 v[120:123], v[192:195], v[216:219], v[120:123]
	v_mfma_f32_16x16x32_bf16 v[108:111], v[132:135], v[228:231], v[108:111]
	v_mfma_f32_16x16x32_bf16 v[104:107], v[192:195], v[228:231], v[104:107]
	v_mfma_f32_16x16x32_bf16 v[92:95], v[132:135], v[236:239], v[92:95]
	v_mfma_f32_16x16x32_bf16 v[88:91], v[192:195], v[236:239], v[88:91]
	v_mfma_f32_16x16x32_bf16 v[76:79], v[132:135], v[244:247], v[76:79]
	v_mfma_f32_16x16x32_bf16 v[72:75], v[192:195], v[244:247], v[72:75]
	s_setprio 0
	s_setprio 1
	v_mfma_f32_16x16x32_bf16 v[116:119], v[196:199], v[212:215], v[116:119]
	v_mfma_f32_16x16x32_bf16 v[112:115], v[204:207], v[212:215], v[112:115]
	v_mfma_f32_16x16x32_bf16 v[100:103], v[196:199], v[224:227], v[100:103]
	v_mfma_f32_16x16x32_bf16 v[96:99], v[204:207], v[224:227], v[96:99]
	v_mfma_f32_16x16x32_bf16 v[84:87], v[196:199], v[232:235], v[84:87]
	v_mfma_f32_16x16x32_bf16 v[80:83], v[204:207], v[232:235], v[80:83]
	v_mfma_f32_16x16x32_bf16 v[68:71], v[196:199], v[240:243], v[68:71]
	v_mfma_f32_16x16x32_bf16 v[64:67], v[204:207], v[240:243], v[64:67]
	v_mfma_f32_16x16x32_bf16 v[116:119], v[200:203], v[216:219], v[116:119]
	v_mfma_f32_16x16x32_bf16 v[112:115], v[208:211], v[216:219], v[112:115]
	v_mfma_f32_16x16x32_bf16 v[100:103], v[200:203], v[228:231], v[100:103]
	v_mfma_f32_16x16x32_bf16 v[96:99], v[208:211], v[228:231], v[96:99]
	v_mfma_f32_16x16x32_bf16 v[84:87], v[200:203], v[236:239], v[84:87]
	v_mfma_f32_16x16x32_bf16 v[80:83], v[208:211], v[236:239], v[80:83]
	v_mfma_f32_16x16x32_bf16 v[68:71], v[200:203], v[244:247], v[68:71]
	v_mfma_f32_16x16x32_bf16 v[64:67], v[208:211], v[244:247], v[64:67]
	s_setprio 0
	s_barrier
	s_mov_b32 m0, s5
	v_lshl_add_u64 v[136:137], s[66:67], 0, v[140:141]
	s_add_u32 s84, s66, 0x40000
	ds_read_b128 v[212:215], v159 offset:16384
	ds_read_b128 v[216:219], v159 offset:17408
	ds_read_b128 v[224:227], v159 offset:18432
	ds_read_b128 v[228:231], v159 offset:19456
	ds_read_b128 v[232:235], v159 offset:20480
	ds_read_b128 v[236:239], v159 offset:21504
	ds_read_b128 v[240:243], v159 offset:22528
	ds_read_b128 v[244:247], v159 offset:23552
	global_load_lds_dwordx4 v[136:137], off
	v_lshl_add_u64 v[154:155], s[66:67], 0, v[144:145]
	s_mov_b32 m0, s12
	s_addc_u32 s85, s67, 0
	global_load_lds_dwordx4 v[154:155], off
	s_mov_b32 m0, s13
	v_lshl_add_u64 v[248:249], s[68:69], 0, v[142:143]
	global_load_lds_dwordx4 v140, s[84:85]
	s_mov_b32 m0, s14
	s_nop 0
	global_load_lds_dwordx4 v144, s[84:85]
	v_lshl_add_u64 v[220:221], s[68:69], 0, v[138:139]
	s_mov_b32 m0, s4
	s_nop 0
	global_load_lds_dwordx4 v[220:221], off
	s_mov_b32 m0, s15
	s_nop 0
	global_load_lds_dwordx4 v[248:249], off
	s_waitcnt vmcnt(8)
	s_waitcnt lgkmcnt(0)
	s_barrier
	s_setprio 1
	s_waitcnt lgkmcnt(0)
	v_mfma_f32_16x16x32_bf16 v[60:63], v[128:131], v[212:215], v[60:63]
	v_mfma_f32_16x16x32_bf16 v[56:59], v[188:191], v[212:215], v[56:59]
	v_mfma_f32_16x16x32_bf16 v[44:47], v[128:131], v[224:227], v[44:47]
	v_mfma_f32_16x16x32_bf16 v[40:43], v[188:191], v[224:227], v[40:43]
	v_mfma_f32_16x16x32_bf16 v[28:31], v[128:131], v[232:235], v[28:31]
	v_mfma_f32_16x16x32_bf16 v[24:27], v[188:191], v[232:235], v[24:27]
	v_mfma_f32_16x16x32_bf16 v[12:15], v[128:131], v[240:243], v[12:15]
	v_mfma_f32_16x16x32_bf16 v[8:11], v[188:191], v[240:243], v[8:11]
	v_mfma_f32_16x16x32_bf16 v[60:63], v[132:135], v[216:219], v[60:63]
	v_mfma_f32_16x16x32_bf16 v[56:59], v[192:195], v[216:219], v[56:59]
	v_mfma_f32_16x16x32_bf16 v[44:47], v[132:135], v[228:231], v[44:47]
	v_mfma_f32_16x16x32_bf16 v[40:43], v[192:195], v[228:231], v[40:43]
	v_mfma_f32_16x16x32_bf16 v[28:31], v[132:135], v[236:239], v[28:31]
	v_mfma_f32_16x16x32_bf16 v[24:27], v[192:195], v[236:239], v[24:27]
	v_mfma_f32_16x16x32_bf16 v[12:15], v[132:135], v[244:247], v[12:15]
	v_mfma_f32_16x16x32_bf16 v[8:11], v[192:195], v[244:247], v[8:11]
	s_setprio 0
	s_setprio 1
	v_mfma_f32_16x16x32_bf16 v[52:55], v[196:199], v[212:215], v[52:55]
	v_mfma_f32_16x16x32_bf16 v[48:51], v[204:207], v[212:215], v[48:51]
	v_mfma_f32_16x16x32_bf16 v[36:39], v[196:199], v[224:227], v[36:39]
	v_mfma_f32_16x16x32_bf16 v[32:35], v[204:207], v[224:227], v[32:35]
	v_mfma_f32_16x16x32_bf16 v[20:23], v[196:199], v[232:235], v[20:23]
	v_mfma_f32_16x16x32_bf16 v[16:19], v[204:207], v[232:235], v[16:19]
	v_mfma_f32_16x16x32_bf16 v[4:7], v[196:199], v[240:243], v[4:7]
	v_mfma_f32_16x16x32_bf16 v[0:3], v[204:207], v[240:243], v[0:3]
	v_mfma_f32_16x16x32_bf16 v[52:55], v[200:203], v[216:219], v[52:55]
	v_mfma_f32_16x16x32_bf16 v[48:51], v[208:211], v[216:219], v[48:51]
	v_mfma_f32_16x16x32_bf16 v[36:39], v[200:203], v[228:231], v[36:39]
	v_mfma_f32_16x16x32_bf16 v[32:35], v[208:211], v[228:231], v[32:35]
	v_mfma_f32_16x16x32_bf16 v[20:23], v[200:203], v[236:239], v[20:23]
	v_mfma_f32_16x16x32_bf16 v[16:19], v[208:211], v[236:239], v[16:19]
	v_mfma_f32_16x16x32_bf16 v[4:7], v[200:203], v[244:247], v[4:7]
	v_mfma_f32_16x16x32_bf16 v[0:3], v[208:211], v[244:247], v[0:3]
	s_setprio 0
	s_barrier
; #define PG8_STAGE(bufoff, gbase, voff) do { _Pragma("unroll") for (int _i = 0; _i < 2; ++_i) \
;         __builtin_amdgcn_global_load_lds((const unsigned*)((const char*)(gbase) + (voff)[_i]), (PG8_LAS unsigned*)(lds + (bufoff) + ldsw + _i * 8192), 16, 0, 0); } while (0)
; #define PG8_LDA(dst, b, h) do { _Pragma("unroll") for (int m = 0; m < 4; ++m) _Pragma("unroll") for (int k = 0; k < 2; ++k) dst[m][k] = *(const PG8_LAS bf16x8*)(lds + PG8_SA(b, h) + aoff + m * 2048 + k * 1024); } while (0)
; #define PG8_LDB(dst, b, h) do { _Pragma("unroll") for (int n = 0; n < 2; ++n) _Pragma("unroll") for (int k = 0; k < 2; ++k) dst[n][k] = *(const PG8_LAS bf16x8*)(lds + PG8_SB(b, h) + boff + n * 2048 + k * 1024); } while (0)
; #define PG8_MMA(ai, bj, At, Bt) do { __builtin_amdgcn_s_setprio(1); _Pragma("unroll") for (int m = 0; m < 4; ++m) _Pragma("unroll") for (int n = 0; n < 2; ++n) _Pragma("unroll") for (int k = 0; k < 2; ++k) \
;         acc[ai][bj][m][n] = __builtin_amdgcn_mfma_f32_16x16x32_bf16(Bt[n][k], At[m][k], acc[ai][bj][m][n], 0, 0, 0); __builtin_amdgcn_s_setprio(0); } while (0)
; #define PG8_WAIT_V(n) asm volatile("s_waitcnt vmcnt(" #n ")" ::: "memory")
; #define PG8_WAIT_L(n) asm volatile("s_waitcnt lgkmcnt(" #n ")" ::: "memory")
; #define PG8_BAR __builtin_amdgcn_s_barrier()
; #define PG8_SCHED __builtin_amdgcn_sched_barrier(0)
; template <class Epi, class Sched, bool ALIGN_EPI = false, bool SP2 = false>
; __device__ __forceinline__ void gemm_phase(PG8_LAS unsigned char* lds, const Gemm g, const Sched& S, const Epi& E) {
;     ...
;             PG8_LDB(B0, 1, 0); PG8_LDB(B1, 1, 1); PG8_SCHED; PG8_LDA(At, 1, 0); PG8_STAGE(PG8_SA(0, 1), a2 + hstep, voffA);
;             PG8_WAIT_V(8); PG8_WAIT_L(0); PG8_BAR; PG8_MMA(0, 0, At, B0); PG8_MMA(0, 1, At, B1); PG8_BAR; PG8_SCHED;
;             PG8_LDA(At, 1, 1); PG8_STAGE(PG8_SB(1, 0), b3, voffB); PG8_STAGE(PG8_SB(1, 1), b3 + hstep, voffB); PG8_STAGE(PG8_SA(1, 0), a3, voffA);
;             PG8_WAIT_V(8); PG8_WAIT_L(0); PG8_BAR; PG8_MMA(1, 0, At, B0); PG8_MMA(1, 1, At, B1); PG8_BAR; PG8_SCHED;
	ds_read_b128 v[128:131], v179
	ds_read_b128 v[132:135], v180
	ds_read_b128 v[188:191], v181
	ds_read_b128 v[192:195], v182
	ds_read_b128 v[196:199], v183
	ds_read_b128 v[200:203], v184
	ds_read_b128 v[204:207], v185
	ds_read_b128 v[208:211], v186
	s_add_u32 s68, s68, 0x40000
	s_addc_u32 s69, s69, 0
	s_mov_b32 m0, s39
	ds_read_b128 v[212:215], v159 offset:32768
	ds_read_b128 v[216:219], v159 offset:33792
	ds_read_b128 v[224:227], v159 offset:34816
	ds_read_b128 v[228:231], v159 offset:35840
	ds_read_b128 v[232:235], v159 offset:36864
	ds_read_b128 v[236:239], v159 offset:37888
	ds_read_b128 v[240:243], v159 offset:38912
	ds_read_b128 v[244:247], v159 offset:39936
	global_load_lds_dwordx4 v138, s[68:69]
	v_lshl_add_u64 v[250:251], s[68:69], 0, v[142:143]
	s_mov_b32 m0, s43
	s_nop 0
	global_load_lds_dwordx4 v[250:251], off
	s_waitcnt vmcnt(8)
	s_waitcnt lgkmcnt(0)
	s_barrier
	s_setprio 1
	s_waitcnt lgkmcnt(0)
	v_mfma_f32_16x16x32_bf16 v[124:127], v[128:131], v[212:215], v[124:127]
	v_mfma_f32_16x16x32_bf16 v[120:123], v[188:191], v[212:215], v[120:123]
	v_mfma_f32_16x16x32_bf16 v[108:111], v[128:131], v[224:227], v[108:111]
	v_mfma_f32_16x16x32_bf16 v[104:107], v[188:191], v[224:227], v[104:107]
	v_mfma_f32_16x16x32_bf16 v[92:95], v[128:131], v[232:235], v[92:95]
	v_mfma_f32_16x16x32_bf16 v[88:91], v[188:191], v[232:235], v[88:91]
	v_mfma_f32_16x16x32_bf16 v[76:79], v[128:131], v[240:243], v[76:79]
	v_mfma_f32_16x16x32_bf16 v[72:75], v[188:191], v[240:243], v[72:75]
	v_mfma_f32_16x16x32_bf16 v[124:127], v[132:135], v[216:219], v[124:127]
	v_mfma_f32_16x16x32_bf16 v[120:123], v[192:195], v[216:219], v[120:123]
	v_mfma_f32_16x16x32_bf16 v[108:111], v[132:135], v[228:231], v[108:111]
	v_mfma_f32_16x16x32_bf16 v[104:107], v[192:195], v[228:231], v[104:107]
	v_mfma_f32_16x16x32_bf16 v[92:95], v[132:135], v[236:239], v[92:95]
	v_mfma_f32_16x16x32_bf16 v[88:91], v[192:195], v[236:239], v[88:91]
	v_mfma_f32_16x16x32_bf16 v[76:79], v[132:135], v[244:247], v[76:79]
	v_mfma_f32_16x16x32_bf16 v[72:75], v[192:195], v[244:247], v[72:75]
	s_setprio 0
	s_setprio 1
	v_mfma_f32_16x16x32_bf16 v[116:119], v[196:199], v[212:215], v[116:119]
	v_mfma_f32_16x16x32_bf16 v[112:115], v[204:207], v[212:215], v[112:115]
	v_mfma_f32_16x16x32_bf16 v[100:103], v[196:199], v[224:227], v[100:103]
	v_mfma_f32_16x16x32_bf16 v[96:99], v[204:207], v[224:227], v[96:99]
	v_mfma_f32_16x16x32_bf16 v[84:87], v[196:199], v[232:235], v[84:87]
	v_mfma_f32_16x16x32_bf16 v[80:83], v[204:207], v[232:235], v[80:83]
	v_mfma_f32_16x16x32_bf16 v[68:71], v[196:199], v[240:243], v[68:71]
	v_mfma_f32_16x16x32_bf16 v[64:67], v[204:207], v[240:243], v[64:67]
	v_mfma_f32_16x16x32_bf16 v[116:119], v[200:203], v[216:219], v[116:119]
	v_mfma_f32_16x16x32_bf16 v[112:115], v[208:211], v[216:219], v[112:115]
	v_mfma_f32_16x16x32_bf16 v[100:103], v[200:203], v[228:231], v[100:103]
	v_mfma_f32_16x16x32_bf16 v[96:99], v[208:211], v[228:231], v[96:99]
	v_mfma_f32_16x16x32_bf16 v[84:87], v[200:203], v[236:239], v[84:87]
	v_mfma_f32_16x16x32_bf16 v[80:83], v[208:211], v[236:239], v[80:83]
	v_mfma_f32_16x16x32_bf16 v[68:71], v[200:203], v[244:247], v[68:71]
	v_mfma_f32_16x16x32_bf16 v[64:67], v[208:211], v[244:247], v[64:67]
	s_setprio 0
	s_barrier
	s_mov_b32 m0, s63
	v_lshl_add_u64 v[136:137], v[136:137], 0, s[40:41]
	s_add_u32 s66, s66, 0x40080
	ds_read_b128 v[212:215], v159 offset:49152
	ds_read_b128 v[216:219], v159 offset:50176
	ds_read_b128 v[224:227], v159 offset:51200
	ds_read_b128 v[228:231], v159 offset:52224
	ds_read_b128 v[232:235], v159 offset:53248
	ds_read_b128 v[236:239], v159 offset:54272
	ds_read_b128 v[240:243], v159 offset:55296
	ds_read_b128 v[244:247], v159 offset:56320
	global_load_lds_dwordx4 v[136:137], off
	v_lshl_add_u64 v[136:137], v[154:155], 0, s[40:41]
	s_mov_b32 m0, s65
	s_addc_u32 s67, s67, 0
	global_load_lds_dwordx4 v[136:137], off
	s_mov_b32 m0, s72
	s_nop 0
	global_load_lds_dwordx4 v140, s[66:67]
	s_mov_b32 m0, s73
	s_nop 0
	global_load_lds_dwordx4 v144, s[66:67]
	v_lshl_add_u64 v[136:137], v[220:221], 0, s[40:41]
	s_mov_b32 m0, s70
	s_nop 0
	global_load_lds_dwordx4 v[136:137], off
	v_lshl_add_u64 v[136:137], v[248:249], 0, s[40:41]
	s_mov_b32 m0, s71
	s_nop 0
	global_load_lds_dwordx4 v[136:137], off
	s_waitcnt vmcnt(8)
	s_waitcnt lgkmcnt(0)
	s_barrier
	s_setprio 1
	s_waitcnt lgkmcnt(0)
	v_mfma_f32_16x16x32_bf16 v[60:63], v[128:131], v[212:215], v[60:63]
	v_mfma_f32_16x16x32_bf16 v[56:59], v[188:191], v[212:215], v[56:59]
	v_mfma_f32_16x16x32_bf16 v[44:47], v[128:131], v[224:227], v[44:47]
	v_mfma_f32_16x16x32_bf16 v[40:43], v[188:191], v[224:227], v[40:43]
	v_mfma_f32_16x16x32_bf16 v[28:31], v[128:131], v[232:235], v[28:31]
	v_mfma_f32_16x16x32_bf16 v[24:27], v[188:191], v[232:235], v[24:27]
	v_mfma_f32_16x16x32_bf16 v[12:15], v[128:131], v[240:243], v[12:15]
	v_mfma_f32_16x16x32_bf16 v[8:11], v[188:191], v[240:243], v[8:11]
	v_mfma_f32_16x16x32_bf16 v[60:63], v[132:135], v[216:219], v[60:63]
	v_mfma_f32_16x16x32_bf16 v[56:59], v[192:195], v[216:219], v[56:59]
	v_mfma_f32_16x16x32_bf16 v[44:47], v[132:135], v[228:231], v[44:47]
	v_mfma_f32_16x16x32_bf16 v[40:43], v[192:195], v[228:231], v[40:43]
	v_mfma_f32_16x16x32_bf16 v[28:31], v[132:135], v[236:239], v[28:31]
	v_mfma_f32_16x16x32_bf16 v[24:27], v[192:195], v[236:239], v[24:27]
	v_mfma_f32_16x16x32_bf16 v[12:15], v[132:135], v[244:247], v[12:15]
	v_mfma_f32_16x16x32_bf16 v[8:11], v[192:195], v[244:247], v[8:11]
	s_setprio 0
	s_setprio 1
	v_mfma_f32_16x16x32_bf16 v[52:55], v[196:199], v[212:215], v[52:55]
	v_mfma_f32_16x16x32_bf16 v[48:51], v[204:207], v[212:215], v[48:51]
	v_mfma_f32_16x16x32_bf16 v[36:39], v[196:199], v[224:227], v[36:39]
	v_mfma_f32_16x16x32_bf16 v[32:35], v[204:207], v[224:227], v[32:35]
	v_mfma_f32_16x16x32_bf16 v[20:23], v[196:199], v[232:235], v[20:23]
	v_mfma_f32_16x16x32_bf16 v[16:19], v[204:207], v[232:235], v[16:19]
	v_mfma_f32_16x16x32_bf16 v[4:7], v[196:199], v[240:243], v[4:7]
	v_mfma_f32_16x16x32_bf16 v[0:3], v[204:207], v[240:243], v[0:3]
	v_mfma_f32_16x16x32_bf16 v[52:55], v[200:203], v[216:219], v[52:55]
	v_mfma_f32_16x16x32_bf16 v[48:51], v[208:211], v[216:219], v[48:51]
	v_mfma_f32_16x16x32_bf16 v[36:39], v[200:203], v[228:231], v[36:39]
	v_mfma_f32_16x16x32_bf16 v[32:35], v[208:211], v[228:231], v[32:35]
	v_mfma_f32_16x16x32_bf16 v[20:23], v[200:203], v[236:239], v[20:23]
	v_mfma_f32_16x16x32_bf16 v[16:19], v[208:211], v[236:239], v[16:19]
	v_mfma_f32_16x16x32_bf16 v[4:7], v[200:203], v[244:247], v[4:7]
	v_mfma_f32_16x16x32_bf16 v[0:3], v[208:211], v[244:247], v[0:3]
	s_setprio 0
	s_barrier
	s_add_i32 s83, s83, 2
	s_add_u32 s10, s10, 0x100
	s_addc_u32 s11, s11, 0
	s_add_u32 s81, s81, 0x100
	s_addc_u32 s82, s82, 0
	s_cmp_gt_u32 s83, 13
	s_cbranch_scc0 .LBB0_1030
	s_and_b64 vcc, exec, s[52:53]
	s_cbranch_vccz .LBB0_1033
	s_barrier

; #define PG8_STAGE(bufoff, gbase, voff) do { _Pragma("unroll") for (int _i = 0; _i < 2; ++_i) \
;         __builtin_amdgcn_global_load_lds((const unsigned*)((const char*)(gbase) + (voff)[_i]), (PG8_LAS unsigned*)(lds + (bufoff) + ldsw + _i * 8192), 16, 0, 0); } while (0)
; #define PG8_LDA(dst, b, h) do { _Pragma("unroll") for (int m = 0; m < 4; ++m) _Pragma("unroll") for (int k = 0; k < 2; ++k) dst[m][k] = *(const PG8_LAS bf16x8*)(lds + PG8_SA(b, h) + aoff + m * 2048 + k * 1024); } while (0)
; #define PG8_LDB(dst, b, h) do { _Pragma("unroll") for (int n = 0; n < 2; ++n) _Pragma("unroll") for (int k = 0; k < 2; ++k) dst[n][k] = *(const PG8_LAS bf16x8*)(lds + PG8_SB(b, h) + boff + n * 2048 + k * 1024); } while (0)
; #define PG8_MMA(ai, bj, At, Bt) do { __builtin_amdgcn_s_setprio(1); _Pragma("unroll") for (int m = 0; m < 4; ++m) _Pragma("unroll") for (int n = 0; n < 2; ++n) _Pragma("unroll") for (int k = 0; k < 2; ++k) \
;         acc[ai][bj][m][n] = __builtin_amdgcn_mfma_f32_16x16x32_bf16(Bt[n][k], At[m][k], acc[ai][bj][m][n], 0, 0, 0); __builtin_amdgcn_s_setprio(0); } while (0)
; #define PG8_WAIT_V(n) asm volatile("s_waitcnt vmcnt(" #n ")" ::: "memory")
; #define PG8_WAIT_L(n) asm volatile("s_waitcnt lgkmcnt(" #n ")" ::: "memory")
; template <class Epi, class Sched, bool ALIGN_EPI = false, bool SP2 = false>
; __device__ __forceinline__ void gemm_phase(PG8_LAS unsigned char* lds, const Gemm g, const Sched& S, const Epi& E) {
;     ...
;             const bool last = (t == nt - 2);
;             const char* a1 = cA + (size_t)(t + 1) * kstep;
;             const char* a2 = last ? nA : cA + (size_t)(t + 2) * kstep; const char* b2 = last ? nB : cB + (size_t)(t + 2) * kstep;
;             const char* a3 = a2 + kstep; const char* b3 = b2 + kstep;
;             if (last && has_next) S.a_ready(nxt);
;             if constexpr (SP2) {
;             PG8_LDB(B0, 0, 0); PG8_LDB(B1, 0, 1); PG8_SCHED; PG8_LDA(At, 0, 0); PG8_STAGE(PG8_SA(1, 1), a1 + hstep, voffA);
;             PG8_WAIT_V(8); PG8_WAIT_L(0); PG8_BAR; PG8_MMA(0, 0, At, B0); PG8_MMA(0, 1, At, B1); PG8_BAR; PG8_SCHED;
;             PG8_LDA(At, 0, 1); PG8_STAGE(PG8_SB(0, 0), b2, voffB); PG8_STAGE(PG8_SB(0, 1), b2 + hstep, voffB); PG8_STAGE(PG8_SA(0, 0), a2, voffA);
;             PG8_WAIT_V(8); PG8_WAIT_L(0); PG8_BAR; PG8_MMA(1, 0, At, B0); PG8_MMA(1, 1, At, B1); PG8_BAR; PG8_SCHED;
.LBB0_1307:
	ds_read_b128 v[142:145], v174
	ds_read_b128 v[146:149], v175
	ds_read_b128 v[150:153], v176
	ds_read_b128 v[154:157], v177
	ds_read_b128 v[158:161], v178
	ds_read_b128 v[162:165], v179
	ds_read_b128 v[166:169], v180
	ds_read_b128 v[190:193], v181
	s_add_u32 s50, s40, 0x100
	s_addc_u32 s51, s41, 0
	s_cmp_eq_u32 s79, 12
	s_cselect_b32 s55, s21, s51
	s_cselect_b32 s54, s37, s50
	s_cselect_b32 s53, s19, s78
	s_cselect_b32 s52, s76, s77
	s_mov_b32 m0, s68
	v_lshl_add_u64 v[170:171], s[40:41], 0, v[134:135]
	ds_read_b128 v[194:197], v172
	ds_read_b128 v[198:201], v172 offset:1024
	ds_read_b128 v[202:205], v172 offset:2048
	ds_read_b128 v[206:209], v172 offset:3072
	ds_read_b128 v[210:213], v172 offset:4096
	ds_read_b128 v[214:217], v172 offset:5120
	ds_read_b128 v[218:221], v172 offset:6144
	ds_read_b128 v[224:227], v172 offset:7168
	global_load_lds_dwordx4 v[170:171], off
	v_lshl_add_u64 v[170:171], s[40:41], 0, v[136:137]
	s_mov_b32 m0, s69
	s_nop 0
	global_load_lds_dwordx4 v[170:171], off
	s_waitcnt vmcnt(8)
	s_waitcnt lgkmcnt(0)
	s_barrier
	s_setprio 1
	s_waitcnt lgkmcnt(0)
	v_mfma_f32_16x16x32_bf16 v[124:127], v[142:145], v[194:197], v[124:127]
	v_mfma_f32_16x16x32_bf16 v[108:111], v[150:153], v[194:197], v[108:111]
	v_mfma_f32_16x16x32_bf16 v[120:123], v[142:145], v[202:205], v[120:123]
	v_mfma_f32_16x16x32_bf16 v[96:99], v[150:153], v[202:205], v[96:99]
	v_mfma_f32_16x16x32_bf16 v[116:119], v[142:145], v[210:213], v[116:119]
	v_mfma_f32_16x16x32_bf16 v[88:91], v[150:153], v[210:213], v[88:91]
	v_mfma_f32_16x16x32_bf16 v[112:115], v[142:145], v[218:221], v[112:115]
	v_mfma_f32_16x16x32_bf16 v[84:87], v[150:153], v[218:221], v[84:87]
	v_mfma_f32_16x16x32_bf16 v[124:127], v[146:149], v[198:201], v[124:127]
	v_mfma_f32_16x16x32_bf16 v[108:111], v[154:157], v[198:201], v[108:111]
	v_mfma_f32_16x16x32_bf16 v[120:123], v[146:149], v[206:209], v[120:123]
	v_mfma_f32_16x16x32_bf16 v[96:99], v[154:157], v[206:209], v[96:99]
	v_mfma_f32_16x16x32_bf16 v[116:119], v[146:149], v[214:217], v[116:119]
	v_mfma_f32_16x16x32_bf16 v[88:91], v[154:157], v[214:217], v[88:91]
	v_mfma_f32_16x16x32_bf16 v[112:115], v[146:149], v[224:227], v[112:115]
	v_mfma_f32_16x16x32_bf16 v[84:87], v[154:157], v[224:227], v[84:87]
	s_setprio 0
	s_setprio 1
	v_mfma_f32_16x16x32_bf16 v[68:71], v[158:161], v[194:197], v[68:71]
	v_mfma_f32_16x16x32_bf16 v[40:43], v[166:169], v[194:197], v[40:43]
	v_mfma_f32_16x16x32_bf16 v[60:63], v[158:161], v[202:205], v[60:63]
	v_mfma_f32_16x16x32_bf16 v[32:35], v[166:169], v[202:205], v[32:35]
	v_mfma_f32_16x16x32_bf16 v[52:55], v[158:161], v[210:213], v[52:55]
	v_mfma_f32_16x16x32_bf16 v[24:27], v[166:169], v[210:213], v[24:27]
	v_mfma_f32_16x16x32_bf16 v[48:51], v[158:161], v[218:221], v[48:51]
	v_mfma_f32_16x16x32_bf16 v[16:19], v[166:169], v[218:221], v[16:19]
	v_mfma_f32_16x16x32_bf16 v[68:71], v[162:165], v[198:201], v[68:71]
	v_mfma_f32_16x16x32_bf16 v[40:43], v[190:193], v[198:201], v[40:43]
	v_mfma_f32_16x16x32_bf16 v[60:63], v[162:165], v[206:209], v[60:63]
	v_mfma_f32_16x16x32_bf16 v[32:35], v[190:193], v[206:209], v[32:35]
	v_mfma_f32_16x16x32_bf16 v[52:55], v[162:165], v[214:217], v[52:55]
	v_mfma_f32_16x16x32_bf16 v[24:27], v[190:193], v[214:217], v[24:27]
	v_mfma_f32_16x16x32_bf16 v[48:51], v[162:165], v[224:227], v[48:51]
	v_mfma_f32_16x16x32_bf16 v[16:19], v[190:193], v[224:227], v[16:19]
	s_setprio 0
	s_barrier
	s_mov_b32 m0, s12
	v_lshl_add_u64 v[170:171], s[52:53], 0, v[128:129]
	s_add_u32 s40, s52, 0x40000
	ds_read_b128 v[194:197], v172 offset:16384
	ds_read_b128 v[198:201], v172 offset:17408
	ds_read_b128 v[202:205], v172 offset:18432
	ds_read_b128 v[206:209], v172 offset:19456
	ds_read_b128 v[210:213], v172 offset:20480
	ds_read_b128 v[214:217], v172 offset:21504
	ds_read_b128 v[218:221], v172 offset:22528
	ds_read_b128 v[224:227], v172 offset:23552
	global_load_lds_dwordx4 v[170:171], off
	v_lshl_add_u64 v[228:229], s[52:53], 0, v[130:131]
	s_mov_b32 m0, s13
	s_addc_u32 s41, s53, 0
	global_load_lds_dwordx4 v[228:229], off
	s_mov_b32 m0, s14
	v_lshl_add_u64 v[238:239], s[54:55], 0, v[130:131]
	global_load_lds_dwordx4 v128, s[40:41]
	s_mov_b32 m0, s15
	s_nop 0
	global_load_lds_dwordx4 v130, s[40:41]
	v_lshl_add_u64 v[236:237], s[54:55], 0, v[128:129]
	s_mov_b32 m0, s5
	s_nop 0
	global_load_lds_dwordx4 v[236:237], off
	s_mov_b32 m0, s39
	s_nop 0
	global_load_lds_dwordx4 v[238:239], off
	s_waitcnt vmcnt(8)
	s_waitcnt lgkmcnt(0)
	s_barrier
	s_setprio 1
	s_waitcnt lgkmcnt(0)
	v_mfma_f32_16x16x32_bf16 v[104:107], v[142:145], v[194:197], v[104:107]
	v_mfma_f32_16x16x32_bf16 v[76:79], v[150:153], v[194:197], v[76:79]
	v_mfma_f32_16x16x32_bf16 v[100:103], v[142:145], v[202:205], v[100:103]
	v_mfma_f32_16x16x32_bf16 v[72:75], v[150:153], v[202:205], v[72:75]
	v_mfma_f32_16x16x32_bf16 v[92:95], v[142:145], v[210:213], v[92:95]
	v_mfma_f32_16x16x32_bf16 v[64:67], v[150:153], v[210:213], v[64:67]
	v_mfma_f32_16x16x32_bf16 v[80:83], v[142:145], v[218:221], v[80:83]
	v_mfma_f32_16x16x32_bf16 v[56:59], v[150:153], v[218:221], v[56:59]
	v_mfma_f32_16x16x32_bf16 v[104:107], v[146:149], v[198:201], v[104:107]
	v_mfma_f32_16x16x32_bf16 v[76:79], v[154:157], v[198:201], v[76:79]
	v_mfma_f32_16x16x32_bf16 v[100:103], v[146:149], v[206:209], v[100:103]
	v_mfma_f32_16x16x32_bf16 v[72:75], v[154:157], v[206:209], v[72:75]
	v_mfma_f32_16x16x32_bf16 v[92:95], v[146:149], v[214:217], v[92:95]
	v_mfma_f32_16x16x32_bf16 v[64:67], v[154:157], v[214:217], v[64:67]
	v_mfma_f32_16x16x32_bf16 v[80:83], v[146:149], v[224:227], v[80:83]
	v_mfma_f32_16x16x32_bf16 v[56:59], v[154:157], v[224:227], v[56:59]
	s_setprio 0
	s_setprio 1
	v_mfma_f32_16x16x32_bf16 v[44:47], v[158:161], v[194:197], v[44:47]
	v_mfma_f32_16x16x32_bf16 v[12:15], v[166:169], v[194:197], v[12:15]
	v_mfma_f32_16x16x32_bf16 v[36:39], v[158:161], v[202:205], v[36:39]
	v_mfma_f32_16x16x32_bf16 v[8:11], v[166:169], v[202:205], v[8:11]
	v_mfma_f32_16x16x32_bf16 v[28:31], v[158:161], v[210:213], v[28:31]
	v_mfma_f32_16x16x32_bf16 v[4:7], v[166:169], v[210:213], v[4:7]
	v_mfma_f32_16x16x32_bf16 v[20:23], v[158:161], v[218:221], v[20:23]
	v_mfma_f32_16x16x32_bf16 v[0:3], v[166:169], v[218:221], v[0:3]
	v_mfma_f32_16x16x32_bf16 v[44:47], v[162:165], v[198:201], v[44:47]
	v_mfma_f32_16x16x32_bf16 v[12:15], v[190:193], v[198:201], v[12:15]
	v_mfma_f32_16x16x32_bf16 v[36:39], v[162:165], v[206:209], v[36:39]
	v_mfma_f32_16x16x32_bf16 v[8:11], v[190:193], v[206:209], v[8:11]
	v_mfma_f32_16x16x32_bf16 v[28:31], v[162:165], v[214:217], v[28:31]
	v_mfma_f32_16x16x32_bf16 v[4:7], v[190:193], v[214:217], v[4:7]
	v_mfma_f32_16x16x32_bf16 v[20:23], v[162:165], v[224:227], v[20:23]
	v_mfma_f32_16x16x32_bf16 v[0:3], v[190:193], v[224:227], v[0:3]
	s_setprio 0
	s_barrier
; #define PG8_STAGE(bufoff, gbase, voff) do { _Pragma("unroll") for (int _i = 0; _i < 2; ++_i) \
;         __builtin_amdgcn_global_load_lds((const unsigned*)((const char*)(gbase) + (voff)[_i]), (PG8_LAS unsigned*)(lds + (bufoff) + ldsw + _i * 8192), 16, 0, 0); } while (0)
; #define PG8_LDA(dst, b, h) do { _Pragma("unroll") for (int m = 0; m < 4; ++m) _Pragma("unroll") for (int k = 0; k < 2; ++k) dst[m][k] = *(const PG8_LAS bf16x8*)(lds + PG8_SA(b, h) + aoff + m * 2048 + k * 1024); } while (0)
; #define PG8_LDB(dst, b, h) do { _Pragma("unroll") for (int n = 0; n < 2; ++n) _Pragma("unroll") for (int k = 0; k < 2; ++k) dst[n][k] = *(const PG8_LAS bf16x8*)(lds + PG8_SB(b, h) + boff + n * 2048 + k * 1024); } while (0)
; #define PG8_MMA(ai, bj, At, Bt) do { __builtin_amdgcn_s_setprio(1); _Pragma("unroll") for (int m = 0; m < 4; ++m) _Pragma("unroll") for (int n = 0; n < 2; ++n) _Pragma("unroll") for (int k = 0; k < 2; ++k) \
;         acc[ai][bj][m][n] = __builtin_amdgcn_mfma_f32_16x16x32_bf16(Bt[n][k], At[m][k], acc[ai][bj][m][n], 0, 0, 0); __builtin_amdgcn_s_setprio(0); } while (0)
; #define PG8_WAIT_V(n) asm volatile("s_waitcnt vmcnt(" #n ")" ::: "memory")
; #define PG8_WAIT_L(n) asm volatile("s_waitcnt lgkmcnt(" #n ")" ::: "memory")
; #define PG8_BAR __builtin_amdgcn_s_barrier()
; #define PG8_SCHED __builtin_amdgcn_sched_barrier(0)
; template <class Epi, class Sched, bool ALIGN_EPI = false, bool SP2 = false>
; __device__ __forceinline__ void gemm_phase(PG8_LAS unsigned char* lds, const Gemm g, const Sched& S, const Epi& E) {
;     ...
;             PG8_LDB(B0, 1, 0); PG8_LDB(B1, 1, 1); PG8_SCHED; PG8_LDA(At, 1, 0); PG8_STAGE(PG8_SA(0, 1), a2 + hstep, voffA);
;             PG8_WAIT_V(8); PG8_WAIT_L(0); PG8_BAR; PG8_MMA(0, 0, At, B0); PG8_MMA(0, 1, At, B1); PG8_BAR; PG8_SCHED;
;             PG8_LDA(At, 1, 1); PG8_STAGE(PG8_SB(1, 0), b3, voffB); PG8_STAGE(PG8_SB(1, 1), b3 + hstep, voffB); PG8_STAGE(PG8_SA(1, 0), a3, voffA);
;             PG8_WAIT_V(8); PG8_WAIT_L(0); PG8_BAR; PG8_MMA(1, 0, At, B0); PG8_MMA(1, 1, At, B1); PG8_BAR; PG8_SCHED;
	ds_read_b128 v[142:145], v182
	ds_read_b128 v[146:149], v183
	ds_read_b128 v[150:153], v184
	ds_read_b128 v[154:157], v185
	ds_read_b128 v[158:161], v186
	ds_read_b128 v[162:165], v187
	ds_read_b128 v[166:169], v188
	ds_read_b128 v[190:193], v189
	s_add_u32 s40, s54, 0x40000
	s_addc_u32 s41, s55, 0
	s_mov_b32 m0, s43
	ds_read_b128 v[194:197], v172 offset:32768
	ds_read_b128 v[198:201], v172 offset:33792
	ds_read_b128 v[202:205], v172 offset:34816
	ds_read_b128 v[206:209], v172 offset:35840
	ds_read_b128 v[210:213], v172 offset:36864
	ds_read_b128 v[214:217], v172 offset:37888
	ds_read_b128 v[218:221], v172 offset:38912
	ds_read_b128 v[224:227], v172 offset:39936
	global_load_lds_dwordx4 v128, s[40:41]
	v_lshl_add_u64 v[240:241], s[40:41], 0, v[130:131]
	s_mov_b32 m0, s56
	s_nop 0
	global_load_lds_dwordx4 v[240:241], off
	s_waitcnt vmcnt(8)
	s_waitcnt lgkmcnt(0)
	s_barrier
	s_setprio 1
	s_waitcnt lgkmcnt(0)
	v_mfma_f32_16x16x32_bf16 v[124:127], v[142:145], v[194:197], v[124:127]
	v_mfma_f32_16x16x32_bf16 v[108:111], v[150:153], v[194:197], v[108:111]
	v_mfma_f32_16x16x32_bf16 v[120:123], v[142:145], v[202:205], v[120:123]
	v_mfma_f32_16x16x32_bf16 v[96:99], v[150:153], v[202:205], v[96:99]
	v_mfma_f32_16x16x32_bf16 v[116:119], v[142:145], v[210:213], v[116:119]
	v_mfma_f32_16x16x32_bf16 v[88:91], v[150:153], v[210:213], v[88:91]
	v_mfma_f32_16x16x32_bf16 v[112:115], v[142:145], v[218:221], v[112:115]
	v_mfma_f32_16x16x32_bf16 v[84:87], v[150:153], v[218:221], v[84:87]
	v_mfma_f32_16x16x32_bf16 v[124:127], v[146:149], v[198:201], v[124:127]
	v_mfma_f32_16x16x32_bf16 v[108:111], v[154:157], v[198:201], v[108:111]
	v_mfma_f32_16x16x32_bf16 v[120:123], v[146:149], v[206:209], v[120:123]
	v_mfma_f32_16x16x32_bf16 v[96:99], v[154:157], v[206:209], v[96:99]
	v_mfma_f32_16x16x32_bf16 v[116:119], v[146:149], v[214:217], v[116:119]
	v_mfma_f32_16x16x32_bf16 v[88:91], v[154:157], v[214:217], v[88:91]
	v_mfma_f32_16x16x32_bf16 v[112:115], v[146:149], v[224:227], v[112:115]
	v_mfma_f32_16x16x32_bf16 v[84:87], v[154:157], v[224:227], v[84:87]
	s_setprio 0
	s_setprio 1
	v_mfma_f32_16x16x32_bf16 v[68:71], v[158:161], v[194:197], v[68:71]
	v_mfma_f32_16x16x32_bf16 v[40:43], v[166:169], v[194:197], v[40:43]
	v_mfma_f32_16x16x32_bf16 v[60:63], v[158:161], v[202:205], v[60:63]
	v_mfma_f32_16x16x32_bf16 v[32:35], v[166:169], v[202:205], v[32:35]
	v_mfma_f32_16x16x32_bf16 v[52:55], v[158:161], v[210:213], v[52:55]
	v_mfma_f32_16x16x32_bf16 v[24:27], v[166:169], v[210:213], v[24:27]
	v_mfma_f32_16x16x32_bf16 v[48:51], v[158:161], v[218:221], v[48:51]
	v_mfma_f32_16x16x32_bf16 v[16:19], v[166:169], v[218:221], v[16:19]
	v_mfma_f32_16x16x32_bf16 v[68:71], v[162:165], v[198:201], v[68:71]
	v_mfma_f32_16x16x32_bf16 v[40:43], v[190:193], v[198:201], v[40:43]
	v_mfma_f32_16x16x32_bf16 v[60:63], v[162:165], v[206:209], v[60:63]
	v_mfma_f32_16x16x32_bf16 v[32:35], v[190:193], v[206:209], v[32:35]
	v_mfma_f32_16x16x32_bf16 v[52:55], v[162:165], v[214:217], v[52:55]
	v_mfma_f32_16x16x32_bf16 v[24:27], v[190:193], v[214:217], v[24:27]
	v_mfma_f32_16x16x32_bf16 v[48:51], v[162:165], v[224:227], v[48:51]
	v_mfma_f32_16x16x32_bf16 v[16:19], v[190:193], v[224:227], v[16:19]
	s_setprio 0
	s_barrier
	s_mov_b32 m0, s60
	v_lshl_add_u64 v[170:171], v[170:171], 0, s[10:11]
	s_add_u32 s40, s52, 0x40080
	ds_read_b128 v[194:197], v172 offset:49152
	ds_read_b128 v[198:201], v172 offset:50176
	ds_read_b128 v[202:205], v172 offset:51200
	ds_read_b128 v[206:209], v172 offset:52224
	ds_read_b128 v[210:213], v172 offset:53248
	ds_read_b128 v[214:217], v172 offset:54272
	ds_read_b128 v[218:221], v172 offset:55296
	ds_read_b128 v[224:227], v172 offset:56320
	global_load_lds_dwordx4 v[170:171], off
	v_lshl_add_u64 v[170:171], v[228:229], 0, s[10:11]
	s_mov_b32 m0, s61
	s_addc_u32 s41, s53, 0
	global_load_lds_dwordx4 v[170:171], off
	s_mov_b32 m0, s64
	s_nop 0
	global_load_lds_dwordx4 v128, s[40:41]
	s_mov_b32 m0, s65
	s_nop 0
	global_load_lds_dwordx4 v130, s[40:41]
	v_lshl_add_u64 v[170:171], v[236:237], 0, s[10:11]
	s_mov_b32 m0, s62
	s_nop 0
	global_load_lds_dwordx4 v[170:171], off
	v_lshl_add_u64 v[170:171], v[238:239], 0, s[10:11]
	s_mov_b32 m0, s63
	s_nop 0
	global_load_lds_dwordx4 v[170:171], off
	s_waitcnt vmcnt(8)
	s_waitcnt lgkmcnt(0)
	s_barrier
	s_setprio 1
	s_waitcnt lgkmcnt(0)
	v_mfma_f32_16x16x32_bf16 v[104:107], v[142:145], v[194:197], v[104:107]
	v_mfma_f32_16x16x32_bf16 v[76:79], v[150:153], v[194:197], v[76:79]
	v_mfma_f32_16x16x32_bf16 v[100:103], v[142:145], v[202:205], v[100:103]
	v_mfma_f32_16x16x32_bf16 v[72:75], v[150:153], v[202:205], v[72:75]
	v_mfma_f32_16x16x32_bf16 v[92:95], v[142:145], v[210:213], v[92:95]
	v_mfma_f32_16x16x32_bf16 v[64:67], v[150:153], v[210:213], v[64:67]
	v_mfma_f32_16x16x32_bf16 v[80:83], v[142:145], v[218:221], v[80:83]
	v_mfma_f32_16x16x32_bf16 v[56:59], v[150:153], v[218:221], v[56:59]
	v_mfma_f32_16x16x32_bf16 v[104:107], v[146:149], v[198:201], v[104:107]
	v_mfma_f32_16x16x32_bf16 v[76:79], v[154:157], v[198:201], v[76:79]
	v_mfma_f32_16x16x32_bf16 v[100:103], v[146:149], v[206:209], v[100:103]
	v_mfma_f32_16x16x32_bf16 v[72:75], v[154:157], v[206:209], v[72:75]
	v_mfma_f32_16x16x32_bf16 v[92:95], v[146:149], v[214:217], v[92:95]
	v_mfma_f32_16x16x32_bf16 v[64:67], v[154:157], v[214:217], v[64:67]
	v_mfma_f32_16x16x32_bf16 v[80:83], v[146:149], v[224:227], v[80:83]
	v_mfma_f32_16x16x32_bf16 v[56:59], v[154:157], v[224:227], v[56:59]
	s_setprio 0
	s_setprio 1
	v_mfma_f32_16x16x32_bf16 v[44:47], v[158:161], v[194:197], v[44:47]
	v_mfma_f32_16x16x32_bf16 v[12:15], v[166:169], v[194:197], v[12:15]
	v_mfma_f32_16x16x32_bf16 v[36:39], v[158:161], v[202:205], v[36:39]
	v_mfma_f32_16x16x32_bf16 v[8:11], v[166:169], v[202:205], v[8:11]
	v_mfma_f32_16x16x32_bf16 v[28:31], v[158:161], v[210:213], v[28:31]
	v_mfma_f32_16x16x32_bf16 v[4:7], v[166:169], v[210:213], v[4:7]
	v_mfma_f32_16x16x32_bf16 v[20:23], v[158:161], v[218:221], v[20:23]
	v_mfma_f32_16x16x32_bf16 v[0:3], v[166:169], v[218:221], v[0:3]
	v_mfma_f32_16x16x32_bf16 v[44:47], v[162:165], v[198:201], v[44:47]
	v_mfma_f32_16x16x32_bf16 v[12:15], v[190:193], v[198:201], v[12:15]
	v_mfma_f32_16x16x32_bf16 v[36:39], v[162:165], v[206:209], v[36:39]
	v_mfma_f32_16x16x32_bf16 v[8:11], v[190:193], v[206:209], v[8:11]
	v_mfma_f32_16x16x32_bf16 v[28:31], v[162:165], v[214:217], v[28:31]
	v_mfma_f32_16x16x32_bf16 v[4:7], v[190:193], v[214:217], v[4:7]
	v_mfma_f32_16x16x32_bf16 v[20:23], v[162:165], v[224:227], v[20:23]
	v_mfma_f32_16x16x32_bf16 v[0:3], v[190:193], v[224:227], v[0:3]
	s_setprio 0
	s_barrier
	s_add_i32 s79, s79, 2
	s_add_u32 s77, s77, 0x100
	s_addc_u32 s78, s78, 0
	s_cmp_gt_u32 s79, 13
	s_mov_b64 s[40:41], s[50:51]
	s_cbranch_scc0 .LBB0_1307
	s_and_b64 vcc, exec, s[16:17]
	s_cbranch_vccz .LBB0_1310
	s_barrier

; #define PG8_STAGE(bufoff, gbase, voff) do { _Pragma("unroll") for (int _i = 0; _i < 2; ++_i) \
;         __builtin_amdgcn_global_load_lds((const unsigned*)((const char*)(gbase) + (voff)[_i]), (PG8_LAS unsigned*)(lds + (bufoff) + ldsw + _i * 8192), 16, 0, 0); } while (0)
; #define PG8_LDA(dst, b, h) do { _Pragma("unroll") for (int m = 0; m < 4; ++m) _Pragma("unroll") for (int k = 0; k < 2; ++k) dst[m][k] = *(const PG8_LAS bf16x8*)(lds + PG8_SA(b, h) + aoff + m * 2048 + k * 1024); } while (0)
; #define PG8_LDB(dst, b, h) do { _Pragma("unroll") for (int n = 0; n < 2; ++n) _Pragma("unroll") for (int k = 0; k < 2; ++k) dst[n][k] = *(const PG8_LAS bf16x8*)(lds + PG8_SB(b, h) + boff + n * 2048 + k * 1024); } while (0)
; #define PG8_MMA(ai, bj, At, Bt) do { __builtin_amdgcn_s_setprio(1); _Pragma("unroll") for (int m = 0; m < 4; ++m) _Pragma("unroll") for (int n = 0; n < 2; ++n) _Pragma("unroll") for (int k = 0; k < 2; ++k) \
;         acc[ai][bj][m][n] = __builtin_amdgcn_mfma_f32_16x16x32_bf16(Bt[n][k], At[m][k], acc[ai][bj][m][n], 0, 0, 0); __builtin_amdgcn_s_setprio(0); } while (0)
; #define PG8_WAIT_V(n) asm volatile("s_waitcnt vmcnt(" #n ")" ::: "memory")
; #define PG8_WAIT_L(n) asm volatile("s_waitcnt lgkmcnt(" #n ")" ::: "memory")
; template <class Epi, class Sched, bool ALIGN_EPI = false, bool SP2 = false>
; __device__ __forceinline__ void gemm_phase(PG8_LAS unsigned char* lds, const Gemm g, const Sched& S, const Epi& E) {
;     ...
;             const bool last = (t == nt - 2);
;             const char* a1 = cA + (size_t)(t + 1) * kstep;
;             const char* a2 = last ? nA : cA + (size_t)(t + 2) * kstep; const char* b2 = last ? nB : cB + (size_t)(t + 2) * kstep;
;             const char* a3 = a2 + kstep; const char* b3 = b2 + kstep;
;             if (last && has_next) S.a_ready(nxt);
;             if constexpr (SP2) {
;             PG8_LDB(B0, 0, 0); PG8_LDB(B1, 0, 1); PG8_SCHED; PG8_LDA(At, 0, 0); PG8_STAGE(PG8_SA(1, 1), a1 + hstep, voffA);
;             PG8_WAIT_V(8); PG8_WAIT_L(0); PG8_BAR; PG8_MMA(0, 0, At, B0); PG8_MMA(0, 1, At, B1); PG8_BAR; PG8_SCHED;
;             PG8_LDA(At, 0, 1); PG8_STAGE(PG8_SB(0, 0), b2, voffB); PG8_STAGE(PG8_SB(0, 1), b2 + hstep, voffB); PG8_STAGE(PG8_SA(0, 0), a2, voffA);
;             PG8_WAIT_V(8); PG8_WAIT_L(0); PG8_BAR; PG8_MMA(1, 0, At, B0); PG8_MMA(1, 1, At, B1); PG8_BAR; PG8_SCHED;
.LBB0_1438:
	ds_read_b128 v[166:169], v149
	ds_read_b128 v[170:173], v150
	ds_read_b128 v[174:177], v151
	ds_read_b128 v[178:181], v152
	ds_read_b128 v[182:185], v153
	ds_read_b128 v[186:189], v154
	ds_read_b128 v[190:193], v155
	ds_read_b128 v[194:197], v156
	s_add_u32 s40, s36, 0xfffc0080
	s_addc_u32 s41, s37, -1
	s_cmp_eq_u32 s70, 12
	s_cselect_b32 s51, s19, s41
	s_cselect_b32 s50, s66, s40
	s_cselect_b32 s41, s17, s69
	s_cselect_b32 s40, s67, s68
	s_mov_b32 m0, s63
	ds_read_b128 v[198:201], v147
	ds_read_b128 v[202:205], v147 offset:1024
	ds_read_b128 v[206:209], v147 offset:2048
	ds_read_b128 v[210:213], v147 offset:3072
	ds_read_b128 v[214:217], v147 offset:4096
	ds_read_b128 v[218:221], v147 offset:5120
	ds_read_b128 v[224:227], v147 offset:6144
	ds_read_b128 v[236:239], v147 offset:7168
	global_load_lds_dwordx4 v136, s[36:37]
	s_mov_b32 m0, s64
	s_nop 0
	global_load_lds_dwordx4 v138, s[36:37]
	s_waitcnt vmcnt(8)
	s_waitcnt lgkmcnt(0)
	s_barrier
	s_setprio 1
	s_waitcnt lgkmcnt(0)
	v_mfma_f32_16x16x32_bf16 v[124:127], v[166:169], v[198:201], v[124:127]
	v_mfma_f32_16x16x32_bf16 v[120:123], v[174:177], v[198:201], v[120:123]
	v_mfma_f32_16x16x32_bf16 v[108:111], v[166:169], v[206:209], v[108:111]
	v_mfma_f32_16x16x32_bf16 v[104:107], v[174:177], v[206:209], v[104:107]
	v_mfma_f32_16x16x32_bf16 v[92:95], v[166:169], v[214:217], v[92:95]
	v_mfma_f32_16x16x32_bf16 v[88:91], v[174:177], v[214:217], v[88:91]
	v_mfma_f32_16x16x32_bf16 v[76:79], v[166:169], v[224:227], v[76:79]
	v_mfma_f32_16x16x32_bf16 v[72:75], v[174:177], v[224:227], v[72:75]
	v_mfma_f32_16x16x32_bf16 v[124:127], v[170:173], v[202:205], v[124:127]
	v_mfma_f32_16x16x32_bf16 v[120:123], v[178:181], v[202:205], v[120:123]
	v_mfma_f32_16x16x32_bf16 v[108:111], v[170:173], v[210:213], v[108:111]
	v_mfma_f32_16x16x32_bf16 v[104:107], v[178:181], v[210:213], v[104:107]
	v_mfma_f32_16x16x32_bf16 v[92:95], v[170:173], v[218:221], v[92:95]
	v_mfma_f32_16x16x32_bf16 v[88:91], v[178:181], v[218:221], v[88:91]
	v_mfma_f32_16x16x32_bf16 v[76:79], v[170:173], v[236:239], v[76:79]
	v_mfma_f32_16x16x32_bf16 v[72:75], v[178:181], v[236:239], v[72:75]
	s_setprio 0
	s_setprio 1
	v_mfma_f32_16x16x32_bf16 v[116:119], v[182:185], v[198:201], v[116:119]
	v_mfma_f32_16x16x32_bf16 v[112:115], v[190:193], v[198:201], v[112:115]
	v_mfma_f32_16x16x32_bf16 v[100:103], v[182:185], v[206:209], v[100:103]
	v_mfma_f32_16x16x32_bf16 v[96:99], v[190:193], v[206:209], v[96:99]
	v_mfma_f32_16x16x32_bf16 v[84:87], v[182:185], v[214:217], v[84:87]
	v_mfma_f32_16x16x32_bf16 v[80:83], v[190:193], v[214:217], v[80:83]
	v_mfma_f32_16x16x32_bf16 v[68:71], v[182:185], v[224:227], v[68:71]
	v_mfma_f32_16x16x32_bf16 v[64:67], v[190:193], v[224:227], v[64:67]
	v_mfma_f32_16x16x32_bf16 v[116:119], v[186:189], v[202:205], v[116:119]
	v_mfma_f32_16x16x32_bf16 v[112:115], v[194:197], v[202:205], v[112:115]
	v_mfma_f32_16x16x32_bf16 v[100:103], v[186:189], v[210:213], v[100:103]
	v_mfma_f32_16x16x32_bf16 v[96:99], v[194:197], v[210:213], v[96:99]
	v_mfma_f32_16x16x32_bf16 v[84:87], v[186:189], v[218:221], v[84:87]
	v_mfma_f32_16x16x32_bf16 v[80:83], v[194:197], v[218:221], v[80:83]
	v_mfma_f32_16x16x32_bf16 v[68:71], v[186:189], v[236:239], v[68:71]
	v_mfma_f32_16x16x32_bf16 v[64:67], v[194:197], v[236:239], v[64:67]
	s_setprio 0
	s_barrier
	s_mov_b32 m0, s15
	v_lshl_add_u64 v[144:145], s[40:41], 0, v[132:133]
	s_add_u32 s72, s40, 0x40000
	ds_read_b128 v[198:201], v147 offset:16384
	ds_read_b128 v[202:205], v147 offset:17408
	ds_read_b128 v[206:209], v147 offset:18432
	ds_read_b128 v[210:213], v147 offset:19456
	ds_read_b128 v[214:217], v147 offset:20480
	ds_read_b128 v[218:221], v147 offset:21504
	ds_read_b128 v[224:227], v147 offset:22528
	ds_read_b128 v[236:239], v147 offset:23552
	global_load_lds_dwordx4 v[144:145], off
	v_lshl_add_u64 v[228:229], s[40:41], 0, v[128:129]
	s_mov_b32 m0, s25
	s_addc_u32 s73, s41, 0
	global_load_lds_dwordx4 v[228:229], off
	s_mov_b32 m0, s39
	v_lshl_add_u64 v[242:243], s[50:51], 0, v[130:131]
	global_load_lds_dwordx4 v132, s[72:73]
	s_mov_b32 m0, s43
	s_nop 0
	global_load_lds_dwordx4 v128, s[72:73]
	v_lshl_add_u64 v[240:241], s[50:51], 0, v[134:135]
	s_mov_b32 m0, s4
	s_nop 0
	global_load_lds_dwordx4 v[240:241], off
	s_mov_b32 m0, s52
	s_nop 0
	global_load_lds_dwordx4 v[242:243], off
	s_waitcnt vmcnt(8)
	s_waitcnt lgkmcnt(0)
	s_barrier
	s_setprio 1
	s_waitcnt lgkmcnt(0)
	v_mfma_f32_16x16x32_bf16 v[60:63], v[166:169], v[198:201], v[60:63]
	v_mfma_f32_16x16x32_bf16 v[56:59], v[174:177], v[198:201], v[56:59]
	v_mfma_f32_16x16x32_bf16 v[44:47], v[166:169], v[206:209], v[44:47]
	v_mfma_f32_16x16x32_bf16 v[40:43], v[174:177], v[206:209], v[40:43]
	v_mfma_f32_16x16x32_bf16 v[28:31], v[166:169], v[214:217], v[28:31]
	v_mfma_f32_16x16x32_bf16 v[24:27], v[174:177], v[214:217], v[24:27]
	v_mfma_f32_16x16x32_bf16 v[12:15], v[166:169], v[224:227], v[12:15]
	v_mfma_f32_16x16x32_bf16 v[8:11], v[174:177], v[224:227], v[8:11]
	v_mfma_f32_16x16x32_bf16 v[60:63], v[170:173], v[202:205], v[60:63]
	v_mfma_f32_16x16x32_bf16 v[56:59], v[178:181], v[202:205], v[56:59]
	v_mfma_f32_16x16x32_bf16 v[44:47], v[170:173], v[210:213], v[44:47]
	v_mfma_f32_16x16x32_bf16 v[40:43], v[178:181], v[210:213], v[40:43]
	v_mfma_f32_16x16x32_bf16 v[28:31], v[170:173], v[218:221], v[28:31]
	v_mfma_f32_16x16x32_bf16 v[24:27], v[178:181], v[218:221], v[24:27]
	v_mfma_f32_16x16x32_bf16 v[12:15], v[170:173], v[236:239], v[12:15]
	v_mfma_f32_16x16x32_bf16 v[8:11], v[178:181], v[236:239], v[8:11]
	s_setprio 0
	s_setprio 1
	v_mfma_f32_16x16x32_bf16 v[52:55], v[182:185], v[198:201], v[52:55]
	v_mfma_f32_16x16x32_bf16 v[48:51], v[190:193], v[198:201], v[48:51]
	v_mfma_f32_16x16x32_bf16 v[36:39], v[182:185], v[206:209], v[36:39]
	v_mfma_f32_16x16x32_bf16 v[32:35], v[190:193], v[206:209], v[32:35]
	v_mfma_f32_16x16x32_bf16 v[20:23], v[182:185], v[214:217], v[20:23]
	v_mfma_f32_16x16x32_bf16 v[16:19], v[190:193], v[214:217], v[16:19]
	v_mfma_f32_16x16x32_bf16 v[4:7], v[182:185], v[224:227], v[4:7]
	v_mfma_f32_16x16x32_bf16 v[0:3], v[190:193], v[224:227], v[0:3]
	v_mfma_f32_16x16x32_bf16 v[52:55], v[186:189], v[202:205], v[52:55]
	v_mfma_f32_16x16x32_bf16 v[48:51], v[194:197], v[202:205], v[48:51]
	v_mfma_f32_16x16x32_bf16 v[36:39], v[186:189], v[210:213], v[36:39]
	v_mfma_f32_16x16x32_bf16 v[32:35], v[194:197], v[210:213], v[32:35]
	v_mfma_f32_16x16x32_bf16 v[20:23], v[186:189], v[218:221], v[20:23]
	v_mfma_f32_16x16x32_bf16 v[16:19], v[194:197], v[218:221], v[16:19]
	v_mfma_f32_16x16x32_bf16 v[4:7], v[186:189], v[236:239], v[4:7]
	v_mfma_f32_16x16x32_bf16 v[0:3], v[194:197], v[236:239], v[0:3]
	s_setprio 0
	s_barrier
; #define PG8_STAGE(bufoff, gbase, voff) do { _Pragma("unroll") for (int _i = 0; _i < 2; ++_i) \
;         __builtin_amdgcn_global_load_lds((const unsigned*)((const char*)(gbase) + (voff)[_i]), (PG8_LAS unsigned*)(lds + (bufoff) + ldsw + _i * 8192), 16, 0, 0); } while (0)
; #define PG8_LDA(dst, b, h) do { _Pragma("unroll") for (int m = 0; m < 4; ++m) _Pragma("unroll") for (int k = 0; k < 2; ++k) dst[m][k] = *(const PG8_LAS bf16x8*)(lds + PG8_SA(b, h) + aoff + m * 2048 + k * 1024); } while (0)
; #define PG8_LDB(dst, b, h) do { _Pragma("unroll") for (int n = 0; n < 2; ++n) _Pragma("unroll") for (int k = 0; k < 2; ++k) dst[n][k] = *(const PG8_LAS bf16x8*)(lds + PG8_SB(b, h) + boff + n * 2048 + k * 1024); } while (0)
; #define PG8_MMA(ai, bj, At, Bt) do { __builtin_amdgcn_s_setprio(1); _Pragma("unroll") for (int m = 0; m < 4; ++m) _Pragma("unroll") for (int n = 0; n < 2; ++n) _Pragma("unroll") for (int k = 0; k < 2; ++k) \
;         acc[ai][bj][m][n] = __builtin_amdgcn_mfma_f32_16x16x32_bf16(Bt[n][k], At[m][k], acc[ai][bj][m][n], 0, 0, 0); __builtin_amdgcn_s_setprio(0); } while (0)
; #define PG8_WAIT_V(n) asm volatile("s_waitcnt vmcnt(" #n ")" ::: "memory")
; #define PG8_WAIT_L(n) asm volatile("s_waitcnt lgkmcnt(" #n ")" ::: "memory")
; #define PG8_BAR __builtin_amdgcn_s_barrier()
; #define PG8_SCHED __builtin_amdgcn_sched_barrier(0)
; template <class Epi, class Sched, bool ALIGN_EPI = false, bool SP2 = false>
; __device__ __forceinline__ void gemm_phase(PG8_LAS unsigned char* lds, const Gemm g, const Sched& S, const Epi& E) {
;     ...
;             PG8_LDB(B0, 1, 0); PG8_LDB(B1, 1, 1); PG8_SCHED; PG8_LDA(At, 1, 0); PG8_STAGE(PG8_SA(0, 1), a2 + hstep, voffA);
;             PG8_WAIT_V(8); PG8_WAIT_L(0); PG8_BAR; PG8_MMA(0, 0, At, B0); PG8_MMA(0, 1, At, B1); PG8_BAR; PG8_SCHED;
;             PG8_LDA(At, 1, 1); PG8_STAGE(PG8_SB(1, 0), b3, voffB); PG8_STAGE(PG8_SB(1, 1), b3 + hstep, voffB); PG8_STAGE(PG8_SA(1, 0), a3, voffA);
;             PG8_WAIT_V(8); PG8_WAIT_L(0); PG8_BAR; PG8_MMA(1, 0, At, B0); PG8_MMA(1, 1, At, B1); PG8_BAR; PG8_SCHED;
	ds_read_b128 v[166:169], v157
	ds_read_b128 v[170:173], v158
	ds_read_b128 v[174:177], v159
	ds_read_b128 v[178:181], v160
	ds_read_b128 v[182:185], v161
	ds_read_b128 v[186:189], v162
	ds_read_b128 v[190:193], v163
	ds_read_b128 v[194:197], v164
	s_add_u32 s50, s50, 0x40000
	s_addc_u32 s51, s51, 0
	s_mov_b32 m0, s53
	ds_read_b128 v[198:201], v147 offset:32768
	ds_read_b128 v[202:205], v147 offset:33792
	ds_read_b128 v[206:209], v147 offset:34816
	ds_read_b128 v[210:213], v147 offset:35840
	ds_read_b128 v[214:217], v147 offset:36864
	ds_read_b128 v[218:221], v147 offset:37888
	ds_read_b128 v[224:227], v147 offset:38912
	ds_read_b128 v[236:239], v147 offset:39936
	global_load_lds_dwordx4 v134, s[50:51]
	v_lshl_add_u64 v[244:245], s[50:51], 0, v[130:131]
	s_mov_b32 m0, s54
	s_nop 0
	global_load_lds_dwordx4 v[244:245], off
	s_waitcnt vmcnt(8)
	s_waitcnt lgkmcnt(0)
	s_barrier
	s_setprio 1
	s_waitcnt lgkmcnt(0)
	v_mfma_f32_16x16x32_bf16 v[124:127], v[166:169], v[198:201], v[124:127]
	v_mfma_f32_16x16x32_bf16 v[120:123], v[174:177], v[198:201], v[120:123]
	v_mfma_f32_16x16x32_bf16 v[108:111], v[166:169], v[206:209], v[108:111]
	v_mfma_f32_16x16x32_bf16 v[104:107], v[174:177], v[206:209], v[104:107]
	v_mfma_f32_16x16x32_bf16 v[92:95], v[166:169], v[214:217], v[92:95]
	v_mfma_f32_16x16x32_bf16 v[88:91], v[174:177], v[214:217], v[88:91]
	v_mfma_f32_16x16x32_bf16 v[76:79], v[166:169], v[224:227], v[76:79]
	v_mfma_f32_16x16x32_bf16 v[72:75], v[174:177], v[224:227], v[72:75]
	v_mfma_f32_16x16x32_bf16 v[124:127], v[170:173], v[202:205], v[124:127]
	v_mfma_f32_16x16x32_bf16 v[120:123], v[178:181], v[202:205], v[120:123]
	v_mfma_f32_16x16x32_bf16 v[108:111], v[170:173], v[210:213], v[108:111]
	v_mfma_f32_16x16x32_bf16 v[104:107], v[178:181], v[210:213], v[104:107]
	v_mfma_f32_16x16x32_bf16 v[92:95], v[170:173], v[218:221], v[92:95]
	v_mfma_f32_16x16x32_bf16 v[88:91], v[178:181], v[218:221], v[88:91]
	v_mfma_f32_16x16x32_bf16 v[76:79], v[170:173], v[236:239], v[76:79]
	v_mfma_f32_16x16x32_bf16 v[72:75], v[178:181], v[236:239], v[72:75]
	s_setprio 0
	s_setprio 1
	v_mfma_f32_16x16x32_bf16 v[116:119], v[182:185], v[198:201], v[116:119]
	v_mfma_f32_16x16x32_bf16 v[112:115], v[190:193], v[198:201], v[112:115]
	v_mfma_f32_16x16x32_bf16 v[100:103], v[182:185], v[206:209], v[100:103]
	v_mfma_f32_16x16x32_bf16 v[96:99], v[190:193], v[206:209], v[96:99]
	v_mfma_f32_16x16x32_bf16 v[84:87], v[182:185], v[214:217], v[84:87]
	v_mfma_f32_16x16x32_bf16 v[80:83], v[190:193], v[214:217], v[80:83]
	v_mfma_f32_16x16x32_bf16 v[68:71], v[182:185], v[224:227], v[68:71]
	v_mfma_f32_16x16x32_bf16 v[64:67], v[190:193], v[224:227], v[64:67]
	v_mfma_f32_16x16x32_bf16 v[116:119], v[186:189], v[202:205], v[116:119]
	v_mfma_f32_16x16x32_bf16 v[112:115], v[194:197], v[202:205], v[112:115]
	v_mfma_f32_16x16x32_bf16 v[100:103], v[186:189], v[210:213], v[100:103]
	v_mfma_f32_16x16x32_bf16 v[96:99], v[194:197], v[210:213], v[96:99]
	v_mfma_f32_16x16x32_bf16 v[84:87], v[186:189], v[218:221], v[84:87]
	v_mfma_f32_16x16x32_bf16 v[80:83], v[194:197], v[218:221], v[80:83]
	v_mfma_f32_16x16x32_bf16 v[68:71], v[186:189], v[236:239], v[68:71]
	v_mfma_f32_16x16x32_bf16 v[64:67], v[194:197], v[236:239], v[64:67]
	s_setprio 0
	s_barrier
	s_mov_b32 m0, s56
	v_lshl_add_u64 v[144:145], v[144:145], 0, s[10:11]
	s_add_u32 s40, s40, 0x40080
	ds_read_b128 v[198:201], v147 offset:49152
	ds_read_b128 v[202:205], v147 offset:50176
	ds_read_b128 v[206:209], v147 offset:51200
	ds_read_b128 v[210:213], v147 offset:52224
	ds_read_b128 v[214:217], v147 offset:53248
	ds_read_b128 v[218:221], v147 offset:54272
	ds_read_b128 v[224:227], v147 offset:55296
	ds_read_b128 v[236:239], v147 offset:56320
	global_load_lds_dwordx4 v[144:145], off
	v_lshl_add_u64 v[144:145], v[228:229], 0, s[10:11]
	s_mov_b32 m0, s57
	s_addc_u32 s41, s41, 0
	global_load_lds_dwordx4 v[144:145], off
	s_mov_b32 m0, s60
	s_nop 0
	global_load_lds_dwordx4 v132, s[40:41]
	s_mov_b32 m0, s61
	s_nop 0
	global_load_lds_dwordx4 v128, s[40:41]
	v_lshl_add_u64 v[144:145], v[240:241], 0, s[10:11]
	s_mov_b32 m0, s58
	s_nop 0
	global_load_lds_dwordx4 v[144:145], off
	v_lshl_add_u64 v[144:145], v[242:243], 0, s[10:11]
	s_mov_b32 m0, s59
	s_nop 0
	global_load_lds_dwordx4 v[144:145], off
	s_waitcnt vmcnt(8)
	s_waitcnt lgkmcnt(0)
	s_barrier
	s_setprio 1
	s_waitcnt lgkmcnt(0)
	v_mfma_f32_16x16x32_bf16 v[60:63], v[166:169], v[198:201], v[60:63]
	v_mfma_f32_16x16x32_bf16 v[56:59], v[174:177], v[198:201], v[56:59]
	v_mfma_f32_16x16x32_bf16 v[44:47], v[166:169], v[206:209], v[44:47]
	v_mfma_f32_16x16x32_bf16 v[40:43], v[174:177], v[206:209], v[40:43]
	v_mfma_f32_16x16x32_bf16 v[28:31], v[166:169], v[214:217], v[28:31]
	v_mfma_f32_16x16x32_bf16 v[24:27], v[174:177], v[214:217], v[24:27]
	v_mfma_f32_16x16x32_bf16 v[12:15], v[166:169], v[224:227], v[12:15]
	v_mfma_f32_16x16x32_bf16 v[8:11], v[174:177], v[224:227], v[8:11]
	v_mfma_f32_16x16x32_bf16 v[60:63], v[170:173], v[202:205], v[60:63]
	v_mfma_f32_16x16x32_bf16 v[56:59], v[178:181], v[202:205], v[56:59]
	v_mfma_f32_16x16x32_bf16 v[44:47], v[170:173], v[210:213], v[44:47]
	v_mfma_f32_16x16x32_bf16 v[40:43], v[178:181], v[210:213], v[40:43]
	v_mfma_f32_16x16x32_bf16 v[28:31], v[170:173], v[218:221], v[28:31]
	v_mfma_f32_16x16x32_bf16 v[24:27], v[178:181], v[218:221], v[24:27]
	v_mfma_f32_16x16x32_bf16 v[12:15], v[170:173], v[236:239], v[12:15]
	v_mfma_f32_16x16x32_bf16 v[8:11], v[178:181], v[236:239], v[8:11]
	s_setprio 0
	s_setprio 1
	v_mfma_f32_16x16x32_bf16 v[52:55], v[182:185], v[198:201], v[52:55]
	v_mfma_f32_16x16x32_bf16 v[48:51], v[190:193], v[198:201], v[48:51]
	v_mfma_f32_16x16x32_bf16 v[36:39], v[182:185], v[206:209], v[36:39]
	v_mfma_f32_16x16x32_bf16 v[32:35], v[190:193], v[206:209], v[32:35]
	v_mfma_f32_16x16x32_bf16 v[20:23], v[182:185], v[214:217], v[20:23]
	v_mfma_f32_16x16x32_bf16 v[16:19], v[190:193], v[214:217], v[16:19]
	v_mfma_f32_16x16x32_bf16 v[4:7], v[182:185], v[224:227], v[4:7]
	v_mfma_f32_16x16x32_bf16 v[0:3], v[190:193], v[224:227], v[0:3]
	v_mfma_f32_16x16x32_bf16 v[52:55], v[186:189], v[202:205], v[52:55]
	v_mfma_f32_16x16x32_bf16 v[48:51], v[194:197], v[202:205], v[48:51]
	v_mfma_f32_16x16x32_bf16 v[36:39], v[186:189], v[210:213], v[36:39]
	v_mfma_f32_16x16x32_bf16 v[32:35], v[194:197], v[210:213], v[32:35]
	v_mfma_f32_16x16x32_bf16 v[20:23], v[186:189], v[218:221], v[20:23]
	v_mfma_f32_16x16x32_bf16 v[16:19], v[194:197], v[218:221], v[16:19]
	v_mfma_f32_16x16x32_bf16 v[4:7], v[186:189], v[236:239], v[4:7]
	v_mfma_f32_16x16x32_bf16 v[0:3], v[194:197], v[236:239], v[0:3]
	s_setprio 0
	s_barrier
	s_add_i32 s70, s70, 2
	s_add_u32 s36, s36, 0x100
	s_addc_u32 s37, s37, 0
	s_add_u32 s68, s68, 0x100
	s_addc_u32 s69, s69, 0
	s_cmp_gt_u32 s70, 13
	s_cbranch_scc0 .LBB0_1438
	s_and_b64 vcc, exec, s[12:13]
	s_cbranch_vccz .LBB0_1441
	s_barrier

; #define PG8_STAGE(bufoff, gbase, voff) do { _Pragma("unroll") for (int _i = 0; _i < 2; ++_i) \
;         __builtin_amdgcn_global_load_lds((const unsigned*)((const char*)(gbase) + (voff)[_i]), (PG8_LAS unsigned*)(lds + (bufoff) + ldsw + _i * 8192), 16, 0, 0); } while (0)
; #define PG8_LDA(dst, b, h) do { _Pragma("unroll") for (int m = 0; m < 4; ++m) _Pragma("unroll") for (int k = 0; k < 2; ++k) dst[m][k] = *(const PG8_LAS bf16x8*)(lds + PG8_SA(b, h) + aoff + m * 2048 + k * 1024); } while (0)
; #define PG8_LDB(dst, b, h) do { _Pragma("unroll") for (int n = 0; n < 2; ++n) _Pragma("unroll") for (int k = 0; k < 2; ++k) dst[n][k] = *(const PG8_LAS bf16x8*)(lds + PG8_SB(b, h) + boff + n * 2048 + k * 1024); } while (0)
; #define PG8_MMA(ai, bj, At, Bt) do { __builtin_amdgcn_s_setprio(1); _Pragma("unroll") for (int m = 0; m < 4; ++m) _Pragma("unroll") for (int n = 0; n < 2; ++n) _Pragma("unroll") for (int k = 0; k < 2; ++k) \
;         acc[ai][bj][m][n] = __builtin_amdgcn_mfma_f32_16x16x32_bf16(Bt[n][k], At[m][k], acc[ai][bj][m][n], 0, 0, 0); __builtin_amdgcn_s_setprio(0); } while (0)
; #define PG8_WAIT_V(n) asm volatile("s_waitcnt vmcnt(" #n ")" ::: "memory")
; #define PG8_WAIT_L(n) asm volatile("s_waitcnt lgkmcnt(" #n ")" ::: "memory")
; template <class Epi, class Sched, bool ALIGN_EPI = false, bool SP2 = false>
; __device__ __forceinline__ void gemm_phase(PG8_LAS unsigned char* lds, const Gemm g, const Sched& S, const Epi& E) {
;     ...
;             const bool last = (t == nt - 2);
;             const char* a1 = cA + (size_t)(t + 1) * kstep;
;             const char* a2 = last ? nA : cA + (size_t)(t + 2) * kstep; const char* b2 = last ? nB : cB + (size_t)(t + 2) * kstep;
;             const char* a3 = a2 + kstep; const char* b3 = b2 + kstep;
;             if (last && has_next) S.a_ready(nxt);
;             if constexpr (SP2) {
;             PG8_LDB(B0, 0, 0); PG8_LDB(B1, 0, 1); PG8_SCHED; PG8_LDA(At, 0, 0); PG8_STAGE(PG8_SA(1, 1), a1 + hstep, voffA);
;             PG8_WAIT_V(8); PG8_WAIT_L(0); PG8_BAR; PG8_MMA(0, 0, At, B0); PG8_MMA(0, 1, At, B1); PG8_BAR; PG8_SCHED;
;             PG8_LDA(At, 0, 1); PG8_STAGE(PG8_SB(0, 0), b2, voffB); PG8_STAGE(PG8_SB(0, 1), b2 + hstep, voffB); PG8_STAGE(PG8_SA(0, 0), a2, voffA);
;             PG8_WAIT_V(8); PG8_WAIT_L(0); PG8_BAR; PG8_MMA(1, 0, At, B0); PG8_MMA(1, 1, At, B1); PG8_BAR; PG8_SCHED;
.LBB0_1518:
	ds_read_b128 v[142:145], v174
	ds_read_b128 v[146:149], v175
	ds_read_b128 v[150:153], v176
	ds_read_b128 v[154:157], v177
	ds_read_b128 v[158:161], v178
	ds_read_b128 v[162:165], v179
	ds_read_b128 v[166:169], v180
	ds_read_b128 v[190:193], v181
	s_add_u32 s22, s20, 0x100
	s_addc_u32 s23, s21, 0
	s_cmp_eq_u32 s73, 40
	s_cselect_b32 s37, s5, s23
	s_cselect_b32 s36, s4, s22
	s_cselect_b32 s25, s17, s72
	s_cselect_b32 s24, s16, s33
	s_mov_b32 m0, s62
	v_lshl_add_u64 v[170:171], s[20:21], 0, v[134:135]
	ds_read_b128 v[194:197], v172
	ds_read_b128 v[198:201], v172 offset:1024
	ds_read_b128 v[202:205], v172 offset:2048
	ds_read_b128 v[206:209], v172 offset:3072
	ds_read_b128 v[210:213], v172 offset:4096
	ds_read_b128 v[214:217], v172 offset:5120
	ds_read_b128 v[218:221], v172 offset:6144
	ds_read_b128 v[224:227], v172 offset:7168
	global_load_lds_dwordx4 v[170:171], off
	v_lshl_add_u64 v[170:171], s[20:21], 0, v[136:137]
	s_mov_b32 m0, s63
	s_nop 0
	global_load_lds_dwordx4 v[170:171], off
	s_waitcnt vmcnt(8)
	s_waitcnt lgkmcnt(0)
	s_barrier
	s_setprio 1
	s_waitcnt lgkmcnt(0)
	v_mfma_f32_16x16x32_bf16 v[124:127], v[142:145], v[194:197], v[124:127]
	v_mfma_f32_16x16x32_bf16 v[108:111], v[150:153], v[194:197], v[108:111]
	v_mfma_f32_16x16x32_bf16 v[120:123], v[142:145], v[202:205], v[120:123]
	v_mfma_f32_16x16x32_bf16 v[96:99], v[150:153], v[202:205], v[96:99]
	v_mfma_f32_16x16x32_bf16 v[116:119], v[142:145], v[210:213], v[116:119]
	v_mfma_f32_16x16x32_bf16 v[88:91], v[150:153], v[210:213], v[88:91]
	v_mfma_f32_16x16x32_bf16 v[112:115], v[142:145], v[218:221], v[112:115]
	v_mfma_f32_16x16x32_bf16 v[84:87], v[150:153], v[218:221], v[84:87]
	v_mfma_f32_16x16x32_bf16 v[124:127], v[146:149], v[198:201], v[124:127]
	v_mfma_f32_16x16x32_bf16 v[108:111], v[154:157], v[198:201], v[108:111]
	v_mfma_f32_16x16x32_bf16 v[120:123], v[146:149], v[206:209], v[120:123]
	v_mfma_f32_16x16x32_bf16 v[96:99], v[154:157], v[206:209], v[96:99]
	v_mfma_f32_16x16x32_bf16 v[116:119], v[146:149], v[214:217], v[116:119]
	v_mfma_f32_16x16x32_bf16 v[88:91], v[154:157], v[214:217], v[88:91]
	v_mfma_f32_16x16x32_bf16 v[112:115], v[146:149], v[224:227], v[112:115]
	v_mfma_f32_16x16x32_bf16 v[84:87], v[154:157], v[224:227], v[84:87]
	s_setprio 0
	s_setprio 1
	v_mfma_f32_16x16x32_bf16 v[68:71], v[158:161], v[194:197], v[68:71]
	v_mfma_f32_16x16x32_bf16 v[40:43], v[166:169], v[194:197], v[40:43]
	v_mfma_f32_16x16x32_bf16 v[60:63], v[158:161], v[202:205], v[60:63]
	v_mfma_f32_16x16x32_bf16 v[32:35], v[166:169], v[202:205], v[32:35]
	v_mfma_f32_16x16x32_bf16 v[52:55], v[158:161], v[210:213], v[52:55]
	v_mfma_f32_16x16x32_bf16 v[24:27], v[166:169], v[210:213], v[24:27]
	v_mfma_f32_16x16x32_bf16 v[48:51], v[158:161], v[218:221], v[48:51]
	v_mfma_f32_16x16x32_bf16 v[16:19], v[166:169], v[218:221], v[16:19]
	v_mfma_f32_16x16x32_bf16 v[68:71], v[162:165], v[198:201], v[68:71]
	v_mfma_f32_16x16x32_bf16 v[40:43], v[190:193], v[198:201], v[40:43]
	v_mfma_f32_16x16x32_bf16 v[60:63], v[162:165], v[206:209], v[60:63]
	v_mfma_f32_16x16x32_bf16 v[32:35], v[190:193], v[206:209], v[32:35]
	v_mfma_f32_16x16x32_bf16 v[52:55], v[162:165], v[214:217], v[52:55]
	v_mfma_f32_16x16x32_bf16 v[24:27], v[190:193], v[214:217], v[24:27]
	v_mfma_f32_16x16x32_bf16 v[48:51], v[162:165], v[224:227], v[48:51]
	v_mfma_f32_16x16x32_bf16 v[16:19], v[190:193], v[224:227], v[16:19]
	s_setprio 0
	s_barrier
	s_mov_b32 m0, s39
	v_lshl_add_u64 v[170:171], s[24:25], 0, v[128:129]
	s_add_u32 s20, s24, 0xb0000
	ds_read_b128 v[194:197], v172 offset:16384
	ds_read_b128 v[198:201], v172 offset:17408
	ds_read_b128 v[202:205], v172 offset:18432
	ds_read_b128 v[206:209], v172 offset:19456
	ds_read_b128 v[210:213], v172 offset:20480
	ds_read_b128 v[214:217], v172 offset:21504
	ds_read_b128 v[218:221], v172 offset:22528
	ds_read_b128 v[224:227], v172 offset:23552
	global_load_lds_dwordx4 v[170:171], off
	v_lshl_add_u64 v[228:229], s[24:25], 0, v[130:131]
	s_mov_b32 m0, s40
	s_addc_u32 s21, s25, 0
	global_load_lds_dwordx4 v[228:229], off
	s_mov_b32 m0, s41
	v_lshl_add_u64 v[238:239], s[36:37], 0, v[130:131]
	global_load_lds_dwordx4 v128, s[20:21]
	s_mov_b32 m0, s43
	s_nop 0
	global_load_lds_dwordx4 v130, s[20:21]
	v_lshl_add_u64 v[236:237], s[36:37], 0, v[128:129]
	s_mov_b32 m0, s15
	s_nop 0
	global_load_lds_dwordx4 v[236:237], off
	s_mov_b32 m0, s46
	s_nop 0
	global_load_lds_dwordx4 v[238:239], off
	s_waitcnt vmcnt(8)
	s_waitcnt lgkmcnt(0)
	s_barrier
	s_setprio 1
	s_waitcnt lgkmcnt(0)
	v_mfma_f32_16x16x32_bf16 v[104:107], v[142:145], v[194:197], v[104:107]
	v_mfma_f32_16x16x32_bf16 v[76:79], v[150:153], v[194:197], v[76:79]
	v_mfma_f32_16x16x32_bf16 v[100:103], v[142:145], v[202:205], v[100:103]
	v_mfma_f32_16x16x32_bf16 v[72:75], v[150:153], v[202:205], v[72:75]
	v_mfma_f32_16x16x32_bf16 v[92:95], v[142:145], v[210:213], v[92:95]
	v_mfma_f32_16x16x32_bf16 v[64:67], v[150:153], v[210:213], v[64:67]
	v_mfma_f32_16x16x32_bf16 v[80:83], v[142:145], v[218:221], v[80:83]
	v_mfma_f32_16x16x32_bf16 v[56:59], v[150:153], v[218:221], v[56:59]
	v_mfma_f32_16x16x32_bf16 v[104:107], v[146:149], v[198:201], v[104:107]
	v_mfma_f32_16x16x32_bf16 v[76:79], v[154:157], v[198:201], v[76:79]
	v_mfma_f32_16x16x32_bf16 v[100:103], v[146:149], v[206:209], v[100:103]
	v_mfma_f32_16x16x32_bf16 v[72:75], v[154:157], v[206:209], v[72:75]
	v_mfma_f32_16x16x32_bf16 v[92:95], v[146:149], v[214:217], v[92:95]
	v_mfma_f32_16x16x32_bf16 v[64:67], v[154:157], v[214:217], v[64:67]
	v_mfma_f32_16x16x32_bf16 v[80:83], v[146:149], v[224:227], v[80:83]
	v_mfma_f32_16x16x32_bf16 v[56:59], v[154:157], v[224:227], v[56:59]
	s_setprio 0
	s_setprio 1
	v_mfma_f32_16x16x32_bf16 v[44:47], v[158:161], v[194:197], v[44:47]
	v_mfma_f32_16x16x32_bf16 v[12:15], v[166:169], v[194:197], v[12:15]
	v_mfma_f32_16x16x32_bf16 v[36:39], v[158:161], v[202:205], v[36:39]
	v_mfma_f32_16x16x32_bf16 v[8:11], v[166:169], v[202:205], v[8:11]
	v_mfma_f32_16x16x32_bf16 v[28:31], v[158:161], v[210:213], v[28:31]
	v_mfma_f32_16x16x32_bf16 v[4:7], v[166:169], v[210:213], v[4:7]
	v_mfma_f32_16x16x32_bf16 v[20:23], v[158:161], v[218:221], v[20:23]
	v_mfma_f32_16x16x32_bf16 v[0:3], v[166:169], v[218:221], v[0:3]
	v_mfma_f32_16x16x32_bf16 v[44:47], v[162:165], v[198:201], v[44:47]
	v_mfma_f32_16x16x32_bf16 v[12:15], v[190:193], v[198:201], v[12:15]
	v_mfma_f32_16x16x32_bf16 v[36:39], v[162:165], v[206:209], v[36:39]
	v_mfma_f32_16x16x32_bf16 v[8:11], v[190:193], v[206:209], v[8:11]
	v_mfma_f32_16x16x32_bf16 v[28:31], v[162:165], v[214:217], v[28:31]
	v_mfma_f32_16x16x32_bf16 v[4:7], v[190:193], v[214:217], v[4:7]
	v_mfma_f32_16x16x32_bf16 v[20:23], v[162:165], v[224:227], v[20:23]
	v_mfma_f32_16x16x32_bf16 v[0:3], v[190:193], v[224:227], v[0:3]
	s_setprio 0
	s_barrier
; #define PG8_STAGE(bufoff, gbase, voff) do { _Pragma("unroll") for (int _i = 0; _i < 2; ++_i) \
;         __builtin_amdgcn_global_load_lds((const unsigned*)((const char*)(gbase) + (voff)[_i]), (PG8_LAS unsigned*)(lds + (bufoff) + ldsw + _i * 8192), 16, 0, 0); } while (0)
; #define PG8_LDA(dst, b, h) do { _Pragma("unroll") for (int m = 0; m < 4; ++m) _Pragma("unroll") for (int k = 0; k < 2; ++k) dst[m][k] = *(const PG8_LAS bf16x8*)(lds + PG8_SA(b, h) + aoff + m * 2048 + k * 1024); } while (0)
; #define PG8_LDB(dst, b, h) do { _Pragma("unroll") for (int n = 0; n < 2; ++n) _Pragma("unroll") for (int k = 0; k < 2; ++k) dst[n][k] = *(const PG8_LAS bf16x8*)(lds + PG8_SB(b, h) + boff + n * 2048 + k * 1024); } while (0)
; #define PG8_MMA(ai, bj, At, Bt) do { __builtin_amdgcn_s_setprio(1); _Pragma("unroll") for (int m = 0; m < 4; ++m) _Pragma("unroll") for (int n = 0; n < 2; ++n) _Pragma("unroll") for (int k = 0; k < 2; ++k) \
;         acc[ai][bj][m][n] = __builtin_amdgcn_mfma_f32_16x16x32_bf16(Bt[n][k], At[m][k], acc[ai][bj][m][n], 0, 0, 0); __builtin_amdgcn_s_setprio(0); } while (0)
; #define PG8_WAIT_V(n) asm volatile("s_waitcnt vmcnt(" #n ")" ::: "memory")
; #define PG8_WAIT_L(n) asm volatile("s_waitcnt lgkmcnt(" #n ")" ::: "memory")
; #define PG8_BAR __builtin_amdgcn_s_barrier()
; #define PG8_SCHED __builtin_amdgcn_sched_barrier(0)
; template <class Epi, class Sched, bool ALIGN_EPI = false, bool SP2 = false>
; __device__ __forceinline__ void gemm_phase(PG8_LAS unsigned char* lds, const Gemm g, const Sched& S, const Epi& E) {
;     ...
;             PG8_LDB(B0, 1, 0); PG8_LDB(B1, 1, 1); PG8_SCHED; PG8_LDA(At, 1, 0); PG8_STAGE(PG8_SA(0, 1), a2 + hstep, voffA);
;             PG8_WAIT_V(8); PG8_WAIT_L(0); PG8_BAR; PG8_MMA(0, 0, At, B0); PG8_MMA(0, 1, At, B1); PG8_BAR; PG8_SCHED;
;             PG8_LDA(At, 1, 1); PG8_STAGE(PG8_SB(1, 0), b3, voffB); PG8_STAGE(PG8_SB(1, 1), b3 + hstep, voffB); PG8_STAGE(PG8_SA(1, 0), a3, voffA);
;             PG8_WAIT_V(8); PG8_WAIT_L(0); PG8_BAR; PG8_MMA(1, 0, At, B0); PG8_MMA(1, 1, At, B1); PG8_BAR; PG8_SCHED;
	ds_read_b128 v[142:145], v182
	ds_read_b128 v[146:149], v183
	ds_read_b128 v[150:153], v184
	ds_read_b128 v[154:157], v185
	ds_read_b128 v[158:161], v186
	ds_read_b128 v[162:165], v187
	ds_read_b128 v[166:169], v188
	ds_read_b128 v[190:193], v189
	s_add_u32 s20, s36, 0xb0000
	s_addc_u32 s21, s37, 0
	s_mov_b32 m0, s47
	ds_read_b128 v[194:197], v172 offset:32768
	ds_read_b128 v[198:201], v172 offset:33792
	ds_read_b128 v[202:205], v172 offset:34816
	ds_read_b128 v[206:209], v172 offset:35840
	ds_read_b128 v[210:213], v172 offset:36864
	ds_read_b128 v[214:217], v172 offset:37888
	ds_read_b128 v[218:221], v172 offset:38912
	ds_read_b128 v[224:227], v172 offset:39936
	global_load_lds_dwordx4 v128, s[20:21]
	v_lshl_add_u64 v[240:241], s[20:21], 0, v[130:131]
	s_mov_b32 m0, s50
	s_nop 0
	global_load_lds_dwordx4 v[240:241], off
	s_waitcnt vmcnt(8)
	s_waitcnt lgkmcnt(0)
	s_barrier
	s_setprio 1
	s_waitcnt lgkmcnt(0)
	v_mfma_f32_16x16x32_bf16 v[124:127], v[142:145], v[194:197], v[124:127]
	v_mfma_f32_16x16x32_bf16 v[108:111], v[150:153], v[194:197], v[108:111]
	v_mfma_f32_16x16x32_bf16 v[120:123], v[142:145], v[202:205], v[120:123]
	v_mfma_f32_16x16x32_bf16 v[96:99], v[150:153], v[202:205], v[96:99]
	v_mfma_f32_16x16x32_bf16 v[116:119], v[142:145], v[210:213], v[116:119]
	v_mfma_f32_16x16x32_bf16 v[88:91], v[150:153], v[210:213], v[88:91]
	v_mfma_f32_16x16x32_bf16 v[112:115], v[142:145], v[218:221], v[112:115]
	v_mfma_f32_16x16x32_bf16 v[84:87], v[150:153], v[218:221], v[84:87]
	v_mfma_f32_16x16x32_bf16 v[124:127], v[146:149], v[198:201], v[124:127]
	v_mfma_f32_16x16x32_bf16 v[108:111], v[154:157], v[198:201], v[108:111]
	v_mfma_f32_16x16x32_bf16 v[120:123], v[146:149], v[206:209], v[120:123]
	v_mfma_f32_16x16x32_bf16 v[96:99], v[154:157], v[206:209], v[96:99]
	v_mfma_f32_16x16x32_bf16 v[116:119], v[146:149], v[214:217], v[116:119]
	v_mfma_f32_16x16x32_bf16 v[88:91], v[154:157], v[214:217], v[88:91]
	v_mfma_f32_16x16x32_bf16 v[112:115], v[146:149], v[224:227], v[112:115]
	v_mfma_f32_16x16x32_bf16 v[84:87], v[154:157], v[224:227], v[84:87]
	s_setprio 0
	s_setprio 1
	v_mfma_f32_16x16x32_bf16 v[68:71], v[158:161], v[194:197], v[68:71]
	v_mfma_f32_16x16x32_bf16 v[40:43], v[166:169], v[194:197], v[40:43]
	v_mfma_f32_16x16x32_bf16 v[60:63], v[158:161], v[202:205], v[60:63]
	v_mfma_f32_16x16x32_bf16 v[32:35], v[166:169], v[202:205], v[32:35]
	v_mfma_f32_16x16x32_bf16 v[52:55], v[158:161], v[210:213], v[52:55]
	v_mfma_f32_16x16x32_bf16 v[24:27], v[166:169], v[210:213], v[24:27]
	v_mfma_f32_16x16x32_bf16 v[48:51], v[158:161], v[218:221], v[48:51]
	v_mfma_f32_16x16x32_bf16 v[16:19], v[166:169], v[218:221], v[16:19]
	v_mfma_f32_16x16x32_bf16 v[68:71], v[162:165], v[198:201], v[68:71]
	v_mfma_f32_16x16x32_bf16 v[40:43], v[190:193], v[198:201], v[40:43]
	v_mfma_f32_16x16x32_bf16 v[60:63], v[162:165], v[206:209], v[60:63]
	v_mfma_f32_16x16x32_bf16 v[32:35], v[190:193], v[206:209], v[32:35]
	v_mfma_f32_16x16x32_bf16 v[52:55], v[162:165], v[214:217], v[52:55]
	v_mfma_f32_16x16x32_bf16 v[24:27], v[190:193], v[214:217], v[24:27]
	v_mfma_f32_16x16x32_bf16 v[48:51], v[162:165], v[224:227], v[48:51]
	v_mfma_f32_16x16x32_bf16 v[16:19], v[190:193], v[224:227], v[16:19]
	s_setprio 0
	s_barrier
	s_mov_b32 m0, s54
	v_lshl_add_u64 v[170:171], v[170:171], 0, s[10:11]
	s_add_u32 s20, s24, 0xb0080
	ds_read_b128 v[194:197], v172 offset:49152
	ds_read_b128 v[198:201], v172 offset:50176
	ds_read_b128 v[202:205], v172 offset:51200
	ds_read_b128 v[206:209], v172 offset:52224
	ds_read_b128 v[210:213], v172 offset:53248
	ds_read_b128 v[214:217], v172 offset:54272
	ds_read_b128 v[218:221], v172 offset:55296
	ds_read_b128 v[224:227], v172 offset:56320
	global_load_lds_dwordx4 v[170:171], off
	v_lshl_add_u64 v[170:171], v[228:229], 0, s[10:11]
	s_mov_b32 m0, s55
	s_addc_u32 s21, s25, 0
	global_load_lds_dwordx4 v[170:171], off
	s_mov_b32 m0, s58
	s_nop 0
	global_load_lds_dwordx4 v128, s[20:21]
	s_mov_b32 m0, s59
	s_nop 0
	global_load_lds_dwordx4 v130, s[20:21]
	v_lshl_add_u64 v[170:171], v[236:237], 0, s[10:11]
	s_mov_b32 m0, s56
	s_nop 0
	global_load_lds_dwordx4 v[170:171], off
	v_lshl_add_u64 v[170:171], v[238:239], 0, s[10:11]
	s_mov_b32 m0, s57
	s_nop 0
	global_load_lds_dwordx4 v[170:171], off
	s_waitcnt vmcnt(8)
	s_waitcnt lgkmcnt(0)
	s_barrier
	s_setprio 1
	s_waitcnt lgkmcnt(0)
	v_mfma_f32_16x16x32_bf16 v[104:107], v[142:145], v[194:197], v[104:107]
	v_mfma_f32_16x16x32_bf16 v[76:79], v[150:153], v[194:197], v[76:79]
	v_mfma_f32_16x16x32_bf16 v[100:103], v[142:145], v[202:205], v[100:103]
	v_mfma_f32_16x16x32_bf16 v[72:75], v[150:153], v[202:205], v[72:75]
	v_mfma_f32_16x16x32_bf16 v[92:95], v[142:145], v[210:213], v[92:95]
	v_mfma_f32_16x16x32_bf16 v[64:67], v[150:153], v[210:213], v[64:67]
	v_mfma_f32_16x16x32_bf16 v[80:83], v[142:145], v[218:221], v[80:83]
	v_mfma_f32_16x16x32_bf16 v[56:59], v[150:153], v[218:221], v[56:59]
	v_mfma_f32_16x16x32_bf16 v[104:107], v[146:149], v[198:201], v[104:107]
	v_mfma_f32_16x16x32_bf16 v[76:79], v[154:157], v[198:201], v[76:79]
	v_mfma_f32_16x16x32_bf16 v[100:103], v[146:149], v[206:209], v[100:103]
	v_mfma_f32_16x16x32_bf16 v[72:75], v[154:157], v[206:209], v[72:75]
	v_mfma_f32_16x16x32_bf16 v[92:95], v[146:149], v[214:217], v[92:95]
	v_mfma_f32_16x16x32_bf16 v[64:67], v[154:157], v[214:217], v[64:67]
	v_mfma_f32_16x16x32_bf16 v[80:83], v[146:149], v[224:227], v[80:83]
	v_mfma_f32_16x16x32_bf16 v[56:59], v[154:157], v[224:227], v[56:59]
	s_setprio 0
	s_setprio 1
	v_mfma_f32_16x16x32_bf16 v[44:47], v[158:161], v[194:197], v[44:47]
	v_mfma_f32_16x16x32_bf16 v[12:15], v[166:169], v[194:197], v[12:15]
	v_mfma_f32_16x16x32_bf16 v[36:39], v[158:161], v[202:205], v[36:39]
	v_mfma_f32_16x16x32_bf16 v[8:11], v[166:169], v[202:205], v[8:11]
	v_mfma_f32_16x16x32_bf16 v[28:31], v[158:161], v[210:213], v[28:31]
	v_mfma_f32_16x16x32_bf16 v[4:7], v[166:169], v[210:213], v[4:7]
	v_mfma_f32_16x16x32_bf16 v[20:23], v[158:161], v[218:221], v[20:23]
	v_mfma_f32_16x16x32_bf16 v[0:3], v[166:169], v[218:221], v[0:3]
	v_mfma_f32_16x16x32_bf16 v[44:47], v[162:165], v[198:201], v[44:47]
	v_mfma_f32_16x16x32_bf16 v[12:15], v[190:193], v[198:201], v[12:15]
	v_mfma_f32_16x16x32_bf16 v[36:39], v[162:165], v[206:209], v[36:39]
	v_mfma_f32_16x16x32_bf16 v[8:11], v[190:193], v[206:209], v[8:11]
	v_mfma_f32_16x16x32_bf16 v[28:31], v[162:165], v[214:217], v[28:31]
	v_mfma_f32_16x16x32_bf16 v[4:7], v[190:193], v[214:217], v[4:7]
	v_mfma_f32_16x16x32_bf16 v[20:23], v[162:165], v[224:227], v[20:23]
	v_mfma_f32_16x16x32_bf16 v[0:3], v[190:193], v[224:227], v[0:3]
	s_setprio 0
	s_barrier
	s_add_i32 s73, s73, 2
	s_add_u32 s33, s33, 0x100
	s_addc_u32 s72, s72, 0
	s_cmp_gt_u32 s73, 41
	s_mov_b64 s[20:21], s[22:23]
	s_cbranch_scc0 .LBB0_1518
	s_and_b64 vcc, exec, s[12:13]
	s_cbranch_vccz .LBB0_1521
	s_barrier
